# v39
# baseline (speedup 1.0000x reference)
; #define PG8_STAGE(bufoff, gbase, voff) do { _Pragma("unroll") for (int _i = 0; _i < 2; ++_i) \
;         __builtin_amdgcn_global_load_lds((const unsigned*)((const char*)(gbase) + (voff)[_i]), (PG8_LAS unsigned*)(lds + (bufoff) + ldsw + _i * 8192), 16, 0, 0); } while (0)
; #define PG8_LDA(dst, b, h) do { _Pragma("unroll") for (int m = 0; m < 4; ++m) _Pragma("unroll") for (int k = 0; k < 2; ++k) dst[m][k] = *(const PG8_LAS bf16x8*)(lds + PG8_SA(b, h) + aoff + m * 2048 + k * 1024); } while (0)
; #define PG8_LDB(dst, b, h) do { _Pragma("unroll") for (int n = 0; n < 2; ++n) _Pragma("unroll") for (int k = 0; k < 2; ++k) dst[n][k] = *(const PG8_LAS bf16x8*)(lds + PG8_SB(b, h) + boff + n * 2048 + k * 1024); } while (0)
; #define PG8_MMA(ai, bj, At, Bt) do { __builtin_amdgcn_s_setprio(1); _Pragma("unroll") for (int m = 0; m < 4; ++m) _Pragma("unroll") for (int n = 0; n < 2; ++n) _Pragma("unroll") for (int k = 0; k < 2; ++k) \
;         acc[ai][bj][m][n] = __builtin_amdgcn_mfma_f32_16x16x32_bf16(Bt[n][k], At[m][k], acc[ai][bj][m][n], 0, 0, 0); __builtin_amdgcn_s_setprio(0); } while (0)
; #define PG8_BAR __builtin_amdgcn_s_barrier()
; template <class Epi, class Sched, bool ALIGN_EPI = false, bool SP2 = false>
; __device__ __forceinline__ void gemm_phase(PG8_LAS unsigned char* lds, const Gemm g, const Sched& S, const Epi& E) {
;     ...
;         const bool has_next = S.next(ui + 1, nxt);
;         const char* nA = has_next ? (const char*)g.A + (size_t)nxt.pm * tstep : cA; const char* nB = has_next ? (const char*)g.Bt + (size_t)nxt.pn * tstep : cB;
;         for (int t = 0; t < nt; t += 2) {
;             const bool last = (t == nt - 2);
;             const char* a1 = cA + (size_t)(t + 1) * kstep;
;             const char* a2 = last ? nA : cA + (size_t)(t + 2) * kstep; const char* b2 = last ? nB : cB + (size_t)(t + 2) * kstep;
;             const char* a3 = a2 + kstep; const char* b3 = b2 + kstep;
;             if (last && has_next) S.a_ready(nxt);
;             if constexpr (SP2) {
;             PG8_LDB(B0, 0, 0); PG8_LDB(B1, 0, 1); PG8_SCHED; PG8_LDA(At, 0, 0); PG8_STAGE(PG8_SA(1, 1), a1 + hstep, voffA);
;             PG8_WAIT_V(8); PG8_WAIT_L(0); PG8_BAR; PG8_MMA(0, 0, At, B0); PG8_MMA(0, 1, At, B1); PG8_BAR; PG8_SCHED;
;             PG8_LDA(At, 0, 1); PG8_STAGE(PG8_SB(0, 0), b2, voffB); PG8_STAGE(PG8_SB(0, 1), b2 + hstep, voffB); PG8_STAGE(PG8_SA(0, 0), a2, voffA);
.LBB0_168:
	s_ashr_i32 s29, s28, 31
	v_cmp_lt_i64_e32 vcc, s[30:31], v[140:141]
	s_lshl_b64 s[30:31], s[28:29], 20
	s_add_u32 s30, s6, s30
	s_addc_u32 s31, s7, s31
	s_and_b64 s[34:35], vcc, exec
	s_cselect_b32 s29, s31, s39
	s_cselect_b32 s57, s30, s38
	s_ashr_i32 s27, s26, 31
	s_lshl_b64 s[34:35], s[26:27], 20
	s_add_u32 s34, s22, s34
	s_addc_u32 s35, s23, s35
	s_and_b64 s[42:43], vcc, exec
	s_cselect_b32 s27, s35, s41
	s_cselect_b32 s58, s34, s40
	s_add_u32 s38, s38, 0x80080
	s_addc_u32 s39, s39, 0
	s_add_u32 s59, s40, 0x100
	s_addc_u32 s60, s41, 0
	s_mov_b32 s61, -2
	ds_read_b128 v[152:155], v149
	ds_read_b128 v[156:159], v149 offset:1024
	ds_read_b128 v[160:163], v149 offset:2048
	ds_read_b128 v[164:167], v149 offset:3072
	ds_read_b128 v[168:171], v150
	ds_read_b128 v[172:175], v150 offset:1024
	ds_read_b128 v[176:179], v150 offset:2048
	ds_read_b128 v[180:183], v150 offset:3072
	s_add_u32 s40, s38, 0xfff80080
	s_addc_u32 s41, s39, -1
	s_cmp_eq_u32 s61, 28
	s_cselect_b32 s43, s29, s41
	s_cselect_b32 s42, s57, s40
	s_cselect_b32 s41, s27, s60
	s_cselect_b32 s40, s58, s59
	s_add_i32 m0, s37, 0xc000
	ds_read_b128 v[184:187], v151
	ds_read_b128 v[188:191], v151 offset:1024
	ds_read_b128 v[192:195], v151 offset:2048
	ds_read_b128 v[196:199], v151 offset:3072
	ds_read_b128 v[200:203], v151 offset:4096
	ds_read_b128 v[204:207], v151 offset:5120
	ds_read_b128 v[208:211], v151 offset:6144
	ds_read_b128 v[214:217], v151 offset:7168
	global_load_lds_dwordx4 v136, s[38:39]
	s_add_i32 m0, s37, 0xe000
	s_nop 0
	global_load_lds_dwordx4 v138, s[38:39]
	s_waitcnt vmcnt(8)
	s_waitcnt lgkmcnt(0)
	s_barrier
	s_waitcnt lgkmcnt(0)
	v_mfma_f32_16x16x32_bf16 v[124:127], v[152:155], v[184:187], 0
	v_mfma_f32_16x16x32_bf16 v[120:123], v[160:163], v[184:187], 0
	v_mfma_f32_16x16x32_bf16 v[108:111], v[152:155], v[192:195], 0
	v_mfma_f32_16x16x32_bf16 v[104:107], v[160:163], v[192:195], 0
	v_mfma_f32_16x16x32_bf16 v[92:95], v[152:155], v[200:203], 0
	v_mfma_f32_16x16x32_bf16 v[88:91], v[160:163], v[200:203], 0
	v_mfma_f32_16x16x32_bf16 v[76:79], v[152:155], v[208:211], 0
	v_mfma_f32_16x16x32_bf16 v[72:75], v[160:163], v[208:211], 0
	v_mfma_f32_16x16x32_bf16 v[124:127], v[156:159], v[188:191], v[124:127]
	v_mfma_f32_16x16x32_bf16 v[120:123], v[164:167], v[188:191], v[120:123]
	v_mfma_f32_16x16x32_bf16 v[108:111], v[156:159], v[196:199], v[108:111]
	v_mfma_f32_16x16x32_bf16 v[104:107], v[164:167], v[196:199], v[104:107]
	v_mfma_f32_16x16x32_bf16 v[92:95], v[156:159], v[204:207], v[92:95]
	v_mfma_f32_16x16x32_bf16 v[88:91], v[164:167], v[204:207], v[88:91]
	v_mfma_f32_16x16x32_bf16 v[76:79], v[156:159], v[214:217], v[76:79]
	v_mfma_f32_16x16x32_bf16 v[72:75], v[164:167], v[214:217], v[72:75]
	v_mfma_f32_16x16x32_bf16 v[116:119], v[168:171], v[184:187], 0
	v_mfma_f32_16x16x32_bf16 v[112:115], v[176:179], v[184:187], 0
	v_mfma_f32_16x16x32_bf16 v[100:103], v[168:171], v[192:195], 0
	v_mfma_f32_16x16x32_bf16 v[96:99], v[176:179], v[192:195], 0
	v_mfma_f32_16x16x32_bf16 v[84:87], v[168:171], v[200:203], 0
	v_mfma_f32_16x16x32_bf16 v[80:83], v[176:179], v[200:203], 0
	v_mfma_f32_16x16x32_bf16 v[68:71], v[168:171], v[208:211], 0
	v_mfma_f32_16x16x32_bf16 v[64:67], v[176:179], v[208:211], 0
	v_mfma_f32_16x16x32_bf16 v[116:119], v[172:175], v[188:191], v[116:119]
	v_mfma_f32_16x16x32_bf16 v[112:115], v[180:183], v[188:191], v[112:115]
	v_mfma_f32_16x16x32_bf16 v[100:103], v[172:175], v[196:199], v[100:103]
	v_mfma_f32_16x16x32_bf16 v[96:99], v[180:183], v[196:199], v[96:99]
	v_mfma_f32_16x16x32_bf16 v[84:87], v[172:175], v[204:207], v[84:87]
	v_mfma_f32_16x16x32_bf16 v[80:83], v[180:183], v[204:207], v[80:83]
	v_mfma_f32_16x16x32_bf16 v[68:71], v[172:175], v[214:217], v[68:71]
	v_mfma_f32_16x16x32_bf16 v[64:67], v[180:183], v[214:217], v[64:67]
	s_barrier
	s_add_i32 s62, s53, s24
	s_mov_b32 m0, s62
	ds_read_b128 v[184:187], v151 offset:16384
	ds_read_b128 v[188:191], v151 offset:17408
	ds_read_b128 v[192:195], v151 offset:18432
	ds_read_b128 v[196:199], v151 offset:19456
	ds_read_b128 v[200:203], v151 offset:20480
	ds_read_b128 v[204:207], v151 offset:21504
	ds_read_b128 v[208:211], v151 offset:22528
	ds_read_b128 v[214:217], v151 offset:23552
	global_load_lds_dwordx4 v132, s[40:41]
	s_add_i32 m0, s62, 0x2000
	s_add_u32 s62, s40, 0x80000
	s_addc_u32 s63, s41, 0
	s_add_i32 s64, s54, s24
	global_load_lds_dwordx4 v128, s[40:41]
	s_mov_b32 m0, s64
	s_nop 0
	global_load_lds_dwordx4 v132, s[62:63]
	s_add_i32 m0, s64, 0x2000
	s_nop 0
	global_load_lds_dwordx4 v128, s[62:63]
	s_mov_b32 m0, s37
	s_nop 0
	global_load_lds_dwordx4 v134, s[42:43]
	s_mov_b32 m0, s45
	s_nop 0
	global_load_lds_dwordx4 v130, s[42:43]
	s_waitcnt vmcnt(8)
	s_waitcnt lgkmcnt(0)
	s_barrier
; #define PG8_STAGE(bufoff, gbase, voff) do { _Pragma("unroll") for (int _i = 0; _i < 2; ++_i) \
;         __builtin_amdgcn_global_load_lds((const unsigned*)((const char*)(gbase) + (voff)[_i]), (PG8_LAS unsigned*)(lds + (bufoff) + ldsw + _i * 8192), 16, 0, 0); } while (0)
; #define PG8_LDA(dst, b, h) do { _Pragma("unroll") for (int m = 0; m < 4; ++m) _Pragma("unroll") for (int k = 0; k < 2; ++k) dst[m][k] = *(const PG8_LAS bf16x8*)(lds + PG8_SA(b, h) + aoff + m * 2048 + k * 1024); } while (0)
; #define PG8_LDB(dst, b, h) do { _Pragma("unroll") for (int n = 0; n < 2; ++n) _Pragma("unroll") for (int k = 0; k < 2; ++k) dst[n][k] = *(const PG8_LAS bf16x8*)(lds + PG8_SB(b, h) + boff + n * 2048 + k * 1024); } while (0)
; #define PG8_MMA(ai, bj, At, Bt) do { __builtin_amdgcn_s_setprio(1); _Pragma("unroll") for (int m = 0; m < 4; ++m) _Pragma("unroll") for (int n = 0; n < 2; ++n) _Pragma("unroll") for (int k = 0; k < 2; ++k) \
;         acc[ai][bj][m][n] = __builtin_amdgcn_mfma_f32_16x16x32_bf16(Bt[n][k], At[m][k], acc[ai][bj][m][n], 0, 0, 0); __builtin_amdgcn_s_setprio(0); } while (0)
; #define PG8_WAIT_V(n) asm volatile("s_waitcnt vmcnt(" #n ")" ::: "memory")
; #define PG8_WAIT_L(n) asm volatile("s_waitcnt lgkmcnt(" #n ")" ::: "memory")
; #define PG8_BAR __builtin_amdgcn_s_barrier()
; #define PG8_SCHED __builtin_amdgcn_sched_barrier(0)
; template <class Epi, class Sched, bool ALIGN_EPI = false, bool SP2 = false>
; __device__ __forceinline__ void gemm_phase(PG8_LAS unsigned char* lds, const Gemm g, const Sched& S, const Epi& E) {
;     ...
;             PG8_LDA(At, 0, 1); PG8_STAGE(PG8_SB(0, 0), b2, voffB); PG8_STAGE(PG8_SB(0, 1), b2 + hstep, voffB); PG8_STAGE(PG8_SA(0, 0), a2, voffA);
;             PG8_WAIT_V(8); PG8_WAIT_L(0); PG8_BAR; PG8_MMA(1, 0, At, B0); PG8_MMA(1, 1, At, B1); PG8_BAR; PG8_SCHED;
;             PG8_LDB(B0, 1, 0); PG8_LDB(B1, 1, 1); PG8_SCHED; PG8_LDA(At, 1, 0); PG8_STAGE(PG8_SA(0, 1), a2 + hstep, voffA);
;             PG8_WAIT_V(8); PG8_WAIT_L(0); PG8_BAR; PG8_MMA(0, 0, At, B0); PG8_MMA(0, 1, At, B1); PG8_BAR; PG8_SCHED;
	s_waitcnt lgkmcnt(0)
	v_mfma_f32_16x16x32_bf16 v[60:63], v[152:155], v[184:187], 0
	v_mfma_f32_16x16x32_bf16 v[56:59], v[160:163], v[184:187], 0
	v_mfma_f32_16x16x32_bf16 v[44:47], v[152:155], v[192:195], 0
	v_mfma_f32_16x16x32_bf16 v[40:43], v[160:163], v[192:195], 0
	v_mfma_f32_16x16x32_bf16 v[28:31], v[152:155], v[200:203], 0
	v_mfma_f32_16x16x32_bf16 v[24:27], v[160:163], v[200:203], 0
	v_mfma_f32_16x16x32_bf16 v[12:15], v[152:155], v[208:211], 0
	v_mfma_f32_16x16x32_bf16 v[8:11], v[160:163], v[208:211], 0
	v_mfma_f32_16x16x32_bf16 v[60:63], v[156:159], v[188:191], v[60:63]
	v_mfma_f32_16x16x32_bf16 v[56:59], v[164:167], v[188:191], v[56:59]
	v_mfma_f32_16x16x32_bf16 v[44:47], v[156:159], v[196:199], v[44:47]
	v_mfma_f32_16x16x32_bf16 v[40:43], v[164:167], v[196:199], v[40:43]
	v_mfma_f32_16x16x32_bf16 v[28:31], v[156:159], v[204:207], v[28:31]
	v_mfma_f32_16x16x32_bf16 v[24:27], v[164:167], v[204:207], v[24:27]
	v_mfma_f32_16x16x32_bf16 v[12:15], v[156:159], v[214:217], v[12:15]
	v_mfma_f32_16x16x32_bf16 v[8:11], v[164:167], v[214:217], v[8:11]
	v_mfma_f32_16x16x32_bf16 v[52:55], v[168:171], v[184:187], 0
	v_mfma_f32_16x16x32_bf16 v[48:51], v[176:179], v[184:187], 0
	v_mfma_f32_16x16x32_bf16 v[36:39], v[168:171], v[192:195], 0
	v_mfma_f32_16x16x32_bf16 v[32:35], v[176:179], v[192:195], 0
	v_mfma_f32_16x16x32_bf16 v[20:23], v[168:171], v[200:203], 0
	v_mfma_f32_16x16x32_bf16 v[16:19], v[176:179], v[200:203], 0
	v_mfma_f32_16x16x32_bf16 v[4:7], v[168:171], v[208:211], 0
	v_mfma_f32_16x16x32_bf16 v[0:3], v[176:179], v[208:211], 0
	v_mfma_f32_16x16x32_bf16 v[52:55], v[172:175], v[188:191], v[52:55]
	v_mfma_f32_16x16x32_bf16 v[48:51], v[180:183], v[188:191], v[48:51]
	v_mfma_f32_16x16x32_bf16 v[36:39], v[172:175], v[196:199], v[36:39]
	v_mfma_f32_16x16x32_bf16 v[32:35], v[180:183], v[196:199], v[32:35]
	v_mfma_f32_16x16x32_bf16 v[20:23], v[172:175], v[204:207], v[20:23]
	v_mfma_f32_16x16x32_bf16 v[16:19], v[180:183], v[204:207], v[16:19]
	v_mfma_f32_16x16x32_bf16 v[4:7], v[172:175], v[214:217], v[4:7]
	v_mfma_f32_16x16x32_bf16 v[0:3], v[180:183], v[214:217], v[0:3]
	s_barrier
	s_add_i32 s62, 0, 0x18000
	s_add_i32 s63, 0, 0x1c000
	v_add_u32_e32 v164, s62, v147
	v_add_u32_e32 v180, s63, v147
	ds_read_b128 v[152:155], v164
	ds_read_b128 v[156:159], v164 offset:1024
	ds_read_b128 v[160:163], v164 offset:2048
	ds_read_b128 v[164:167], v164 offset:3072
	ds_read_b128 v[168:171], v180
	ds_read_b128 v[172:175], v180 offset:1024
	ds_read_b128 v[176:179], v180 offset:2048
	ds_read_b128 v[180:183], v180 offset:3072
	s_add_u32 s84, s42, 0x80
	s_addc_u32 s85, s43, 0
	s_add_u32 s42, s42, 0x80000
	s_addc_u32 s43, s43, 0
	s_mov_b32 m0, s46
	ds_read_b128 v[184:187], v151 offset:32768
	ds_read_b128 v[188:191], v151 offset:33792
	ds_read_b128 v[192:195], v151 offset:34816
	ds_read_b128 v[196:199], v151 offset:35840
	ds_read_b128 v[200:203], v151 offset:36864
	ds_read_b128 v[204:207], v151 offset:37888
	ds_read_b128 v[208:211], v151 offset:38912
	ds_read_b128 v[214:217], v151 offset:39936
	global_load_lds_dwordx4 v134, s[42:43]
	s_mov_b32 m0, s47
	s_nop 0
	global_load_lds_dwordx4 v130, s[42:43]
	s_waitcnt vmcnt(8)
	s_waitcnt lgkmcnt(0)
	s_barrier
	s_waitcnt lgkmcnt(0)
	v_mfma_f32_16x16x32_bf16 v[124:127], v[152:155], v[184:187], v[124:127]
	v_mfma_f32_16x16x32_bf16 v[120:123], v[160:163], v[184:187], v[120:123]
	v_mfma_f32_16x16x32_bf16 v[108:111], v[152:155], v[192:195], v[108:111]
	v_mfma_f32_16x16x32_bf16 v[104:107], v[160:163], v[192:195], v[104:107]
	v_mfma_f32_16x16x32_bf16 v[92:95], v[152:155], v[200:203], v[92:95]
	v_mfma_f32_16x16x32_bf16 v[88:91], v[160:163], v[200:203], v[88:91]
	v_mfma_f32_16x16x32_bf16 v[76:79], v[152:155], v[208:211], v[76:79]
	v_mfma_f32_16x16x32_bf16 v[72:75], v[160:163], v[208:211], v[72:75]
	v_mfma_f32_16x16x32_bf16 v[124:127], v[156:159], v[188:191], v[124:127]
	v_mfma_f32_16x16x32_bf16 v[120:123], v[164:167], v[188:191], v[120:123]
	v_mfma_f32_16x16x32_bf16 v[108:111], v[156:159], v[196:199], v[108:111]
	v_mfma_f32_16x16x32_bf16 v[104:107], v[164:167], v[196:199], v[104:107]
	v_mfma_f32_16x16x32_bf16 v[92:95], v[156:159], v[204:207], v[92:95]
	v_mfma_f32_16x16x32_bf16 v[88:91], v[164:167], v[204:207], v[88:91]
	v_mfma_f32_16x16x32_bf16 v[76:79], v[156:159], v[214:217], v[76:79]
	v_mfma_f32_16x16x32_bf16 v[72:75], v[164:167], v[214:217], v[72:75]
	v_mfma_f32_16x16x32_bf16 v[116:119], v[168:171], v[184:187], v[116:119]
	v_mfma_f32_16x16x32_bf16 v[112:115], v[176:179], v[184:187], v[112:115]
	v_mfma_f32_16x16x32_bf16 v[100:103], v[168:171], v[192:195], v[100:103]
	v_mfma_f32_16x16x32_bf16 v[96:99], v[176:179], v[192:195], v[96:99]
	v_mfma_f32_16x16x32_bf16 v[84:87], v[168:171], v[200:203], v[84:87]
	v_mfma_f32_16x16x32_bf16 v[80:83], v[176:179], v[200:203], v[80:83]
	v_mfma_f32_16x16x32_bf16 v[68:71], v[168:171], v[208:211], v[68:71]
	v_mfma_f32_16x16x32_bf16 v[64:67], v[176:179], v[208:211], v[64:67]
	v_mfma_f32_16x16x32_bf16 v[116:119], v[172:175], v[188:191], v[116:119]
	v_mfma_f32_16x16x32_bf16 v[112:115], v[180:183], v[188:191], v[112:115]
	v_mfma_f32_16x16x32_bf16 v[100:103], v[172:175], v[196:199], v[100:103]
	v_mfma_f32_16x16x32_bf16 v[96:99], v[180:183], v[196:199], v[96:99]
	v_mfma_f32_16x16x32_bf16 v[84:87], v[172:175], v[204:207], v[84:87]
	v_mfma_f32_16x16x32_bf16 v[80:83], v[180:183], v[204:207], v[80:83]
	v_mfma_f32_16x16x32_bf16 v[68:71], v[172:175], v[214:217], v[68:71]
	v_mfma_f32_16x16x32_bf16 v[64:67], v[180:183], v[214:217], v[64:67]
	s_barrier
; #define PG8_STAGE(bufoff, gbase, voff) do { _Pragma("unroll") for (int _i = 0; _i < 2; ++_i) \
;         __builtin_amdgcn_global_load_lds((const unsigned*)((const char*)(gbase) + (voff)[_i]), (PG8_LAS unsigned*)(lds + (bufoff) + ldsw + _i * 8192), 16, 0, 0); } while (0)
; #define PG8_LDA(dst, b, h) do { _Pragma("unroll") for (int m = 0; m < 4; ++m) _Pragma("unroll") for (int k = 0; k < 2; ++k) dst[m][k] = *(const PG8_LAS bf16x8*)(lds + PG8_SA(b, h) + aoff + m * 2048 + k * 1024); } while (0)
; #define PG8_MMA(ai, bj, At, Bt) do { __builtin_amdgcn_s_setprio(1); _Pragma("unroll") for (int m = 0; m < 4; ++m) _Pragma("unroll") for (int n = 0; n < 2; ++n) _Pragma("unroll") for (int k = 0; k < 2; ++k) \
;         acc[ai][bj][m][n] = __builtin_amdgcn_mfma_f32_16x16x32_bf16(Bt[n][k], At[m][k], acc[ai][bj][m][n], 0, 0, 0); __builtin_amdgcn_s_setprio(0); } while (0)
; #define PG8_WAIT_V(n) asm volatile("s_waitcnt vmcnt(" #n ")" ::: "memory")
; #define PG8_WAIT_L(n) asm volatile("s_waitcnt lgkmcnt(" #n ")" ::: "memory")
; #define PG8_BAR __builtin_amdgcn_s_barrier()
; #define PG8_SCHED __builtin_amdgcn_sched_barrier(0)
; template <class Epi, class Sched, bool ALIGN_EPI = false, bool SP2 = false>
; __device__ __forceinline__ void gemm_phase(PG8_LAS unsigned char* lds, const Gemm g, const Sched& S, const Epi& E) {
;     ...
;             PG8_LDA(At, 1, 1); PG8_STAGE(PG8_SB(1, 0), b3, voffB); PG8_STAGE(PG8_SB(1, 1), b3 + hstep, voffB); PG8_STAGE(PG8_SA(1, 0), a3, voffA);
;             PG8_WAIT_V(8); PG8_WAIT_L(0); PG8_BAR; PG8_MMA(1, 0, At, B0); PG8_MMA(1, 1, At, B1); PG8_BAR; PG8_SCHED;
	s_add_i32 s42, s62, s24
	s_add_u32 s86, s40, 0x80
	s_addc_u32 s87, s41, 0
	s_mov_b32 m0, s42
	ds_read_b128 v[184:187], v151 offset:49152
	ds_read_b128 v[188:191], v151 offset:50176
	ds_read_b128 v[192:195], v151 offset:51200
	ds_read_b128 v[196:199], v151 offset:52224
	ds_read_b128 v[200:203], v151 offset:53248
	ds_read_b128 v[204:207], v151 offset:54272
	ds_read_b128 v[208:211], v151 offset:55296
	ds_read_b128 v[214:217], v151 offset:56320
	global_load_lds_dwordx4 v132, s[86:87]
	s_add_i32 m0, s42, 0x2000
	s_add_u32 s40, s40, 0x80080
	s_addc_u32 s41, s41, 0
	s_add_i32 s42, s63, s24
	global_load_lds_dwordx4 v128, s[86:87]
	s_mov_b32 m0, s42
	s_nop 0
	global_load_lds_dwordx4 v132, s[40:41]
	s_add_i32 m0, s42, 0x2000
	s_nop 0
	global_load_lds_dwordx4 v128, s[40:41]
	s_mov_b32 m0, s49
	s_nop 0
	global_load_lds_dwordx4 v134, s[84:85]
	s_mov_b32 m0, s50
	s_nop 0
	global_load_lds_dwordx4 v130, s[84:85]
	s_waitcnt vmcnt(8)
	s_waitcnt lgkmcnt(0)
	s_barrier
	s_waitcnt lgkmcnt(0)
	v_mfma_f32_16x16x32_bf16 v[60:63], v[152:155], v[184:187], v[60:63]
	v_mfma_f32_16x16x32_bf16 v[56:59], v[160:163], v[184:187], v[56:59]
	v_mfma_f32_16x16x32_bf16 v[44:47], v[152:155], v[192:195], v[44:47]
	v_mfma_f32_16x16x32_bf16 v[40:43], v[160:163], v[192:195], v[40:43]
	v_mfma_f32_16x16x32_bf16 v[28:31], v[152:155], v[200:203], v[28:31]
	v_mfma_f32_16x16x32_bf16 v[24:27], v[160:163], v[200:203], v[24:27]
	v_mfma_f32_16x16x32_bf16 v[12:15], v[152:155], v[208:211], v[12:15]
	v_mfma_f32_16x16x32_bf16 v[8:11], v[160:163], v[208:211], v[8:11]
	v_mfma_f32_16x16x32_bf16 v[60:63], v[156:159], v[188:191], v[60:63]
	v_mfma_f32_16x16x32_bf16 v[56:59], v[164:167], v[188:191], v[56:59]
	v_mfma_f32_16x16x32_bf16 v[44:47], v[156:159], v[196:199], v[44:47]
	v_mfma_f32_16x16x32_bf16 v[40:43], v[164:167], v[196:199], v[40:43]
	v_mfma_f32_16x16x32_bf16 v[28:31], v[156:159], v[204:207], v[28:31]
	v_mfma_f32_16x16x32_bf16 v[24:27], v[164:167], v[204:207], v[24:27]
	v_mfma_f32_16x16x32_bf16 v[12:15], v[156:159], v[214:217], v[12:15]
	v_mfma_f32_16x16x32_bf16 v[8:11], v[164:167], v[214:217], v[8:11]
	v_mfma_f32_16x16x32_bf16 v[52:55], v[168:171], v[184:187], v[52:55]
	v_mfma_f32_16x16x32_bf16 v[48:51], v[176:179], v[184:187], v[48:51]
	v_mfma_f32_16x16x32_bf16 v[36:39], v[168:171], v[192:195], v[36:39]
	v_mfma_f32_16x16x32_bf16 v[32:35], v[176:179], v[192:195], v[32:35]
	v_mfma_f32_16x16x32_bf16 v[20:23], v[168:171], v[200:203], v[20:23]
	v_mfma_f32_16x16x32_bf16 v[16:19], v[176:179], v[200:203], v[16:19]
	v_mfma_f32_16x16x32_bf16 v[4:7], v[168:171], v[208:211], v[4:7]
	v_mfma_f32_16x16x32_bf16 v[0:3], v[176:179], v[208:211], v[0:3]
	v_mfma_f32_16x16x32_bf16 v[52:55], v[172:175], v[188:191], v[52:55]
	v_mfma_f32_16x16x32_bf16 v[48:51], v[180:183], v[188:191], v[48:51]
	v_mfma_f32_16x16x32_bf16 v[36:39], v[172:175], v[196:199], v[36:39]
	v_mfma_f32_16x16x32_bf16 v[32:35], v[180:183], v[196:199], v[32:35]
	v_mfma_f32_16x16x32_bf16 v[20:23], v[172:175], v[204:207], v[20:23]
	v_mfma_f32_16x16x32_bf16 v[16:19], v[180:183], v[204:207], v[16:19]
	v_mfma_f32_16x16x32_bf16 v[4:7], v[172:175], v[214:217], v[4:7]
	v_mfma_f32_16x16x32_bf16 v[0:3], v[180:183], v[214:217], v[0:3]
	s_barrier
	s_add_i32 s61, s61, 2
	s_add_u32 s38, s38, 0x100
	s_addc_u32 s39, s39, 0
	s_add_u32 s59, s59, 0x100
	s_addc_u32 s60, s60, 0
	s_cmp_gt_u32 s61, 29

; #define PG8_STAGE(bufoff, gbase, voff) do { _Pragma("unroll") for (int _i = 0; _i < 2; ++_i) \
;         __builtin_amdgcn_global_load_lds((const unsigned*)((const char*)(gbase) + (voff)[_i]), (PG8_LAS unsigned*)(lds + (bufoff) + ldsw + _i * 8192), 16, 0, 0); } while (0)
; #define PG8_LDA(dst, b, h) do { _Pragma("unroll") for (int m = 0; m < 4; ++m) _Pragma("unroll") for (int k = 0; k < 2; ++k) dst[m][k] = *(const PG8_LAS bf16x8*)(lds + PG8_SA(b, h) + aoff + m * 2048 + k * 1024); } while (0)
; #define PG8_LDB(dst, b, h) do { _Pragma("unroll") for (int n = 0; n < 2; ++n) _Pragma("unroll") for (int k = 0; k < 2; ++k) dst[n][k] = *(const PG8_LAS bf16x8*)(lds + PG8_SB(b, h) + boff + n * 2048 + k * 1024); } while (0)
; #define PG8_MMA(ai, bj, At, Bt) do { __builtin_amdgcn_s_setprio(1); _Pragma("unroll") for (int m = 0; m < 4; ++m) _Pragma("unroll") for (int n = 0; n < 2; ++n) _Pragma("unroll") for (int k = 0; k < 2; ++k) \
;         acc[ai][bj][m][n] = __builtin_amdgcn_mfma_f32_16x16x32_bf16(Bt[n][k], At[m][k], acc[ai][bj][m][n], 0, 0, 0); __builtin_amdgcn_s_setprio(0); } while (0)
; #define PG8_WAIT_V(n) asm volatile("s_waitcnt vmcnt(" #n ")" ::: "memory")
; #define PG8_BAR __builtin_amdgcn_s_barrier()
; template <class Epi, class Sched, bool ALIGN_EPI = false, bool SP2 = false>
; __device__ __forceinline__ void gemm_phase(PG8_LAS unsigned char* lds, const Gemm g, const Sched& S, const Epi& E) {
;     ...
;         for (int t = 0; t < nt; t += 2) {
;             const bool last = (t == nt - 2);
;             const char* a1 = cA + (size_t)(t + 1) * kstep;
;             const char* a2 = last ? nA : cA + (size_t)(t + 2) * kstep; const char* b2 = last ? nB : cB + (size_t)(t + 2) * kstep;
;             const char* a3 = a2 + kstep; const char* b3 = b2 + kstep;
;             if (last && has_next) S.a_ready(nxt);
;             if constexpr (SP2) {
;             PG8_LDB(B0, 0, 0); PG8_LDB(B1, 0, 1); PG8_SCHED; PG8_LDA(At, 0, 0); PG8_STAGE(PG8_SA(1, 1), a1 + hstep, voffA);
;             PG8_WAIT_V(8); PG8_WAIT_L(0); PG8_BAR; PG8_MMA(0, 0, At, B0); PG8_MMA(0, 1, At, B1); PG8_BAR; PG8_SCHED;
;             PG8_LDA(At, 0, 1); PG8_STAGE(PG8_SB(0, 0), b2, voffB); PG8_STAGE(PG8_SB(0, 1), b2 + hstep, voffB); PG8_STAGE(PG8_SA(0, 0), a2, voffA);
;             PG8_WAIT_V(8); PG8_WAIT_L(0); PG8_BAR; PG8_MMA(1, 0, At, B0); PG8_MMA(1, 1, At, B1); PG8_BAR; PG8_SCHED;
.LBB0_244:
	s_add_u32 s67, s46, 0x100
	v_mov_b32_e32 v220, v251
	s_addc_u32 s68, s47, 0
	s_mov_b32 s69, -2
	ds_read_b128 v[140:143], v169
	ds_read_b128 v[144:147], v169 offset:1024
	ds_read_b128 v[148:151], v169 offset:2048
	ds_read_b128 v[152:155], v169 offset:3072
	ds_read_b128 v[156:159], v170
	ds_read_b128 v[160:163], v170 offset:1024
	ds_read_b128 v[172:175], v170 offset:2048
	ds_read_b128 v[176:179], v170 offset:3072
	s_add_u32 s46, s44, 0x100
	s_addc_u32 s47, s45, 0
	s_cmpk_eq_i32 s69, 0x54
	s_cselect_b32 s51, s11, s47
	s_cselect_b32 s50, s10, s46
	s_cselect_b32 s49, s13, s68
	s_cselect_b32 s48, s12, s67
	s_add_i32 m0, s26, 0xc000
	ds_read_b128 v[180:183], v171
	ds_read_b128 v[184:187], v171 offset:1024
	ds_read_b128 v[188:191], v171 offset:2048
	ds_read_b128 v[192:195], v171 offset:3072
	ds_read_b128 v[196:199], v171 offset:4096
	ds_read_b128 v[200:203], v171 offset:5120
	ds_read_b128 v[204:207], v171 offset:6144
	ds_read_b128 v[208:211], v171 offset:7168
	global_load_lds_dwordx4 v136, s[44:45]
	s_add_i32 m0, s26, 0xe000
	s_nop 0
	global_load_lds_dwordx4 v138, s[44:45]
	s_waitcnt vmcnt(8)
	s_waitcnt lgkmcnt(0)
	s_barrier
	s_waitcnt lgkmcnt(0)
	v_mfma_f32_16x16x32_bf16 v[124:127], v[140:143], v[180:183], 0
	v_mfma_f32_16x16x32_bf16 v[120:123], v[148:151], v[180:183], 0
	v_mfma_f32_16x16x32_bf16 v[116:119], v[140:143], v[188:191], 0
	v_mfma_f32_16x16x32_bf16 v[112:115], v[148:151], v[188:191], 0
	v_mfma_f32_16x16x32_bf16 v[108:111], v[140:143], v[196:199], 0
	v_mfma_f32_16x16x32_bf16 v[96:99], v[148:151], v[196:199], 0
	v_mfma_f32_16x16x32_bf16 v[84:87], v[140:143], v[204:207], 0
	v_mfma_f32_16x16x32_bf16 v[76:79], v[148:151], v[204:207], 0
	v_mfma_f32_16x16x32_bf16 v[124:127], v[144:147], v[184:187], v[124:127]
	v_mfma_f32_16x16x32_bf16 v[120:123], v[152:155], v[184:187], v[120:123]
	v_mfma_f32_16x16x32_bf16 v[116:119], v[144:147], v[192:195], v[116:119]
	v_mfma_f32_16x16x32_bf16 v[112:115], v[152:155], v[192:195], v[112:115]
	v_mfma_f32_16x16x32_bf16 v[108:111], v[144:147], v[200:203], v[108:111]
	v_mfma_f32_16x16x32_bf16 v[96:99], v[152:155], v[200:203], v[96:99]
	v_mfma_f32_16x16x32_bf16 v[84:87], v[144:147], v[208:211], v[84:87]
	v_mfma_f32_16x16x32_bf16 v[76:79], v[152:155], v[208:211], v[76:79]
	v_mfma_f32_16x16x32_bf16 v[104:107], v[156:159], v[180:183], 0
	v_mfma_f32_16x16x32_bf16 v[100:103], v[172:175], v[180:183], 0
	v_mfma_f32_16x16x32_bf16 v[92:95], v[156:159], v[188:191], 0
	v_mfma_f32_16x16x32_bf16 v[88:91], v[172:175], v[188:191], 0
	v_mfma_f32_16x16x32_bf16 v[80:83], v[156:159], v[196:199], 0
	v_mfma_f32_16x16x32_bf16 v[72:75], v[172:175], v[196:199], 0
	v_mfma_f32_16x16x32_bf16 v[68:71], v[156:159], v[204:207], 0
	v_mfma_f32_16x16x32_bf16 v[64:67], v[172:175], v[204:207], 0
	v_mfma_f32_16x16x32_bf16 v[104:107], v[160:163], v[184:187], v[104:107]
	v_mfma_f32_16x16x32_bf16 v[100:103], v[176:179], v[184:187], v[100:103]
	v_mfma_f32_16x16x32_bf16 v[92:95], v[160:163], v[192:195], v[92:95]
	v_mfma_f32_16x16x32_bf16 v[88:91], v[176:179], v[192:195], v[88:91]
	v_mfma_f32_16x16x32_bf16 v[80:83], v[160:163], v[200:203], v[80:83]
	v_mfma_f32_16x16x32_bf16 v[72:75], v[176:179], v[200:203], v[72:75]
	v_mfma_f32_16x16x32_bf16 v[68:71], v[160:163], v[208:211], v[68:71]
	v_mfma_f32_16x16x32_bf16 v[64:67], v[176:179], v[208:211], v[64:67]
	s_barrier
	s_add_i32 s44, s61, s25
	s_mov_b32 m0, s44
	ds_read_b128 v[180:183], v171 offset:16384
	ds_read_b128 v[184:187], v171 offset:17408
	ds_read_b128 v[188:191], v171 offset:18432
	ds_read_b128 v[192:195], v171 offset:19456
	ds_read_b128 v[196:199], v171 offset:20480
	ds_read_b128 v[200:203], v171 offset:21504
	ds_read_b128 v[204:207], v171 offset:22528
	ds_read_b128 v[208:211], v171 offset:23552
	global_load_lds_dwordx4 v130, s[48:49]
	s_add_i32 m0, s44, 0x2000
	s_add_u32 s44, s48, 0x160000
	s_addc_u32 s45, s49, 0
	s_add_i32 s70, s62, s25
	global_load_lds_dwordx4 v134, s[48:49]
	s_mov_b32 m0, s70
	s_nop 0
	global_load_lds_dwordx4 v130, s[44:45]
	s_add_i32 m0, s70, 0x2000
	s_nop 0
	global_load_lds_dwordx4 v134, s[44:45]
	s_mov_b32 m0, s26
	s_nop 0
	global_load_lds_dwordx4 v128, s[50:51]
	s_mov_b32 m0, s27
	s_nop 0
	global_load_lds_dwordx4 v132, s[50:51]
	s_waitcnt vmcnt(8)
	s_waitcnt lgkmcnt(0)
	s_barrier
	s_waitcnt lgkmcnt(0)
	v_mfma_f32_16x16x32_bf16 v[60:63], v[140:143], v[180:183], 0
	v_mfma_f32_16x16x32_bf16 v[56:59], v[148:151], v[180:183], 0
	v_mfma_f32_16x16x32_bf16 v[52:55], v[140:143], v[188:191], 0
	v_mfma_f32_16x16x32_bf16 v[48:51], v[148:151], v[188:191], 0
	v_mfma_f32_16x16x32_bf16 v[44:47], v[140:143], v[196:199], 0
	v_mfma_f32_16x16x32_bf16 v[32:35], v[148:151], v[196:199], 0
	v_mfma_f32_16x16x32_bf16 v[20:23], v[140:143], v[204:207], 0
	v_mfma_f32_16x16x32_bf16 v[12:15], v[148:151], v[204:207], 0
	v_mfma_f32_16x16x32_bf16 v[60:63], v[144:147], v[184:187], v[60:63]
	v_mfma_f32_16x16x32_bf16 v[56:59], v[152:155], v[184:187], v[56:59]
	v_mfma_f32_16x16x32_bf16 v[52:55], v[144:147], v[192:195], v[52:55]
	v_mfma_f32_16x16x32_bf16 v[48:51], v[152:155], v[192:195], v[48:51]
	v_mfma_f32_16x16x32_bf16 v[44:47], v[144:147], v[200:203], v[44:47]
	v_mfma_f32_16x16x32_bf16 v[32:35], v[152:155], v[200:203], v[32:35]
	v_mfma_f32_16x16x32_bf16 v[20:23], v[144:147], v[208:211], v[20:23]
	v_mfma_f32_16x16x32_bf16 v[12:15], v[152:155], v[208:211], v[12:15]
	v_mfma_f32_16x16x32_bf16 v[40:43], v[156:159], v[180:183], 0
	v_mfma_f32_16x16x32_bf16 v[36:39], v[172:175], v[180:183], 0
	v_mfma_f32_16x16x32_bf16 v[28:31], v[156:159], v[188:191], 0
	v_mfma_f32_16x16x32_bf16 v[24:27], v[172:175], v[188:191], 0
	v_mfma_f32_16x16x32_bf16 v[16:19], v[156:159], v[196:199], 0
	v_mfma_f32_16x16x32_bf16 v[8:11], v[172:175], v[196:199], 0
	v_mfma_f32_16x16x32_bf16 v[4:7], v[156:159], v[204:207], 0
	v_mfma_f32_16x16x32_bf16 v[0:3], v[172:175], v[204:207], 0
	v_mfma_f32_16x16x32_bf16 v[40:43], v[160:163], v[184:187], v[40:43]
	v_mfma_f32_16x16x32_bf16 v[36:39], v[176:179], v[184:187], v[36:39]
	v_mfma_f32_16x16x32_bf16 v[28:31], v[160:163], v[192:195], v[28:31]
	v_mfma_f32_16x16x32_bf16 v[24:27], v[176:179], v[192:195], v[24:27]
	v_mfma_f32_16x16x32_bf16 v[16:19], v[160:163], v[200:203], v[16:19]
	v_mfma_f32_16x16x32_bf16 v[8:11], v[176:179], v[200:203], v[8:11]
	v_mfma_f32_16x16x32_bf16 v[4:7], v[160:163], v[208:211], v[4:7]
	v_mfma_f32_16x16x32_bf16 v[0:3], v[176:179], v[208:211], v[0:3]
	s_barrier
; #define PG8_STAGE(bufoff, gbase, voff) do { _Pragma("unroll") for (int _i = 0; _i < 2; ++_i) \
;         __builtin_amdgcn_global_load_lds((const unsigned*)((const char*)(gbase) + (voff)[_i]), (PG8_LAS unsigned*)(lds + (bufoff) + ldsw + _i * 8192), 16, 0, 0); } while (0)
; #define PG8_LDA(dst, b, h) do { _Pragma("unroll") for (int m = 0; m < 4; ++m) _Pragma("unroll") for (int k = 0; k < 2; ++k) dst[m][k] = *(const PG8_LAS bf16x8*)(lds + PG8_SA(b, h) + aoff + m * 2048 + k * 1024); } while (0)
; #define PG8_LDB(dst, b, h) do { _Pragma("unroll") for (int n = 0; n < 2; ++n) _Pragma("unroll") for (int k = 0; k < 2; ++k) dst[n][k] = *(const PG8_LAS bf16x8*)(lds + PG8_SB(b, h) + boff + n * 2048 + k * 1024); } while (0)
; #define PG8_MMA(ai, bj, At, Bt) do { __builtin_amdgcn_s_setprio(1); _Pragma("unroll") for (int m = 0; m < 4; ++m) _Pragma("unroll") for (int n = 0; n < 2; ++n) _Pragma("unroll") for (int k = 0; k < 2; ++k) \
;         acc[ai][bj][m][n] = __builtin_amdgcn_mfma_f32_16x16x32_bf16(Bt[n][k], At[m][k], acc[ai][bj][m][n], 0, 0, 0); __builtin_amdgcn_s_setprio(0); } while (0)
; #define PG8_WAIT_V(n) asm volatile("s_waitcnt vmcnt(" #n ")" ::: "memory")
; #define PG8_WAIT_L(n) asm volatile("s_waitcnt lgkmcnt(" #n ")" ::: "memory")
; #define PG8_BAR __builtin_amdgcn_s_barrier()
; #define PG8_SCHED __builtin_amdgcn_sched_barrier(0)
; template <class Epi, class Sched, bool ALIGN_EPI = false, bool SP2 = false>
; __device__ __forceinline__ void gemm_phase(PG8_LAS unsigned char* lds, const Gemm g, const Sched& S, const Epi& E) {
;     ...
;             PG8_LDB(B0, 1, 0); PG8_LDB(B1, 1, 1); PG8_SCHED; PG8_LDA(At, 1, 0); PG8_STAGE(PG8_SA(0, 1), a2 + hstep, voffA);
;             PG8_WAIT_V(8); PG8_WAIT_L(0); PG8_BAR; PG8_MMA(0, 0, At, B0); PG8_MMA(0, 1, At, B1); PG8_BAR; PG8_SCHED;
;             PG8_LDA(At, 1, 1); PG8_STAGE(PG8_SB(1, 0), b3, voffB); PG8_STAGE(PG8_SB(1, 1), b3 + hstep, voffB); PG8_STAGE(PG8_SA(1, 0), a3, voffA);
;             PG8_WAIT_V(8); PG8_WAIT_L(0); PG8_BAR; PG8_MMA(1, 0, At, B0); PG8_MMA(1, 1, At, B1); PG8_BAR; PG8_SCHED;
	s_add_i32 s70, 0, 0x18000
	s_add_i32 s71, 0, 0x1c000
	v_add_u32_e32 v152, s70, v167
	v_add_u32_e32 v176, s71, v167
	ds_read_b128 v[140:143], v152
	ds_read_b128 v[144:147], v152 offset:1024
	ds_read_b128 v[148:151], v152 offset:2048
	ds_read_b128 v[152:155], v152 offset:3072
	ds_read_b128 v[156:159], v176
	ds_read_b128 v[160:163], v176 offset:1024
	ds_read_b128 v[172:175], v176 offset:2048
	ds_read_b128 v[176:179], v176 offset:3072
	s_add_u32 s44, s50, 0x160000
	s_addc_u32 s45, s51, 0
	s_mov_b32 m0, s52
	ds_read_b128 v[180:183], v171 offset:32768
	ds_read_b128 v[184:187], v171 offset:33792
	ds_read_b128 v[188:191], v171 offset:34816
	ds_read_b128 v[192:195], v171 offset:35840
	ds_read_b128 v[196:199], v171 offset:36864
	ds_read_b128 v[200:203], v171 offset:37888
	ds_read_b128 v[204:207], v171 offset:38912
	ds_read_b128 v[208:211], v171 offset:39936
	global_load_lds_dwordx4 v128, s[44:45]
	s_mov_b32 m0, s53
	s_nop 0
	global_load_lds_dwordx4 v132, s[44:45]
	s_waitcnt vmcnt(8)
	s_waitcnt lgkmcnt(0)
	s_barrier
	s_waitcnt lgkmcnt(0)
	v_mfma_f32_16x16x32_bf16 v[124:127], v[140:143], v[180:183], v[124:127]
	v_mfma_f32_16x16x32_bf16 v[120:123], v[148:151], v[180:183], v[120:123]
	v_mfma_f32_16x16x32_bf16 v[116:119], v[140:143], v[188:191], v[116:119]
	v_mfma_f32_16x16x32_bf16 v[112:115], v[148:151], v[188:191], v[112:115]
	v_mfma_f32_16x16x32_bf16 v[108:111], v[140:143], v[196:199], v[108:111]
	v_mfma_f32_16x16x32_bf16 v[96:99], v[148:151], v[196:199], v[96:99]
	v_mfma_f32_16x16x32_bf16 v[84:87], v[140:143], v[204:207], v[84:87]
	v_mfma_f32_16x16x32_bf16 v[76:79], v[148:151], v[204:207], v[76:79]
	v_mfma_f32_16x16x32_bf16 v[124:127], v[144:147], v[184:187], v[124:127]
	v_mfma_f32_16x16x32_bf16 v[120:123], v[152:155], v[184:187], v[120:123]
	v_mfma_f32_16x16x32_bf16 v[116:119], v[144:147], v[192:195], v[116:119]
	v_mfma_f32_16x16x32_bf16 v[112:115], v[152:155], v[192:195], v[112:115]
	v_mfma_f32_16x16x32_bf16 v[108:111], v[144:147], v[200:203], v[108:111]
	v_mfma_f32_16x16x32_bf16 v[96:99], v[152:155], v[200:203], v[96:99]
	v_mfma_f32_16x16x32_bf16 v[84:87], v[144:147], v[208:211], v[84:87]
	v_mfma_f32_16x16x32_bf16 v[76:79], v[152:155], v[208:211], v[76:79]
	v_mfma_f32_16x16x32_bf16 v[104:107], v[156:159], v[180:183], v[104:107]
	v_mfma_f32_16x16x32_bf16 v[100:103], v[172:175], v[180:183], v[100:103]
	v_mfma_f32_16x16x32_bf16 v[92:95], v[156:159], v[188:191], v[92:95]
	v_mfma_f32_16x16x32_bf16 v[88:91], v[172:175], v[188:191], v[88:91]
	v_mfma_f32_16x16x32_bf16 v[80:83], v[156:159], v[196:199], v[80:83]
	v_mfma_f32_16x16x32_bf16 v[72:75], v[172:175], v[196:199], v[72:75]
	v_mfma_f32_16x16x32_bf16 v[68:71], v[156:159], v[204:207], v[68:71]
	v_mfma_f32_16x16x32_bf16 v[64:67], v[172:175], v[204:207], v[64:67]
	v_mfma_f32_16x16x32_bf16 v[104:107], v[160:163], v[184:187], v[104:107]
	v_mfma_f32_16x16x32_bf16 v[100:103], v[176:179], v[184:187], v[100:103]
	v_mfma_f32_16x16x32_bf16 v[92:95], v[160:163], v[192:195], v[92:95]
	v_mfma_f32_16x16x32_bf16 v[88:91], v[176:179], v[192:195], v[88:91]
	v_mfma_f32_16x16x32_bf16 v[80:83], v[160:163], v[200:203], v[80:83]
	v_mfma_f32_16x16x32_bf16 v[72:75], v[176:179], v[200:203], v[72:75]
	v_mfma_f32_16x16x32_bf16 v[68:71], v[160:163], v[208:211], v[68:71]
	v_mfma_f32_16x16x32_bf16 v[64:67], v[176:179], v[208:211], v[64:67]
	s_barrier
	s_add_i32 s44, s70, s25
	s_add_u32 s86, s48, 0x80
	s_addc_u32 s87, s49, 0
	s_mov_b32 m0, s44
	ds_read_b128 v[180:183], v171 offset:49152
	ds_read_b128 v[184:187], v171 offset:50176
	ds_read_b128 v[188:191], v171 offset:51200
	ds_read_b128 v[192:195], v171 offset:52224
	ds_read_b128 v[196:199], v171 offset:53248
	ds_read_b128 v[200:203], v171 offset:54272
	ds_read_b128 v[204:207], v171 offset:55296
	ds_read_b128 v[208:211], v171 offset:56320
	global_load_lds_dwordx4 v130, s[86:87]
	s_add_i32 m0, s44, 0x2000
	s_add_u32 s44, s48, 0x160080
	s_addc_u32 s45, s49, 0
	s_add_i32 s48, s71, s25
	global_load_lds_dwordx4 v134, s[86:87]
	s_mov_b32 m0, s48
	s_nop 0
	global_load_lds_dwordx4 v130, s[44:45]
	s_add_i32 m0, s48, 0x2000
	s_nop 0
	global_load_lds_dwordx4 v134, s[44:45]
	s_add_u32 s84, s50, 0x80
	s_addc_u32 s85, s51, 0
	s_mov_b32 m0, s57
	s_nop 0
	global_load_lds_dwordx4 v128, s[84:85]
	s_mov_b32 m0, s58
	s_nop 0
	global_load_lds_dwordx4 v132, s[84:85]
	s_waitcnt vmcnt(8)
	s_waitcnt lgkmcnt(0)
	s_barrier
	s_waitcnt lgkmcnt(0)
	v_mfma_f32_16x16x32_bf16 v[60:63], v[140:143], v[180:183], v[60:63]
	v_mfma_f32_16x16x32_bf16 v[56:59], v[148:151], v[180:183], v[56:59]
	v_mfma_f32_16x16x32_bf16 v[52:55], v[140:143], v[188:191], v[52:55]
	v_mfma_f32_16x16x32_bf16 v[48:51], v[148:151], v[188:191], v[48:51]
	v_mfma_f32_16x16x32_bf16 v[44:47], v[140:143], v[196:199], v[44:47]
	v_mfma_f32_16x16x32_bf16 v[32:35], v[148:151], v[196:199], v[32:35]
	v_mfma_f32_16x16x32_bf16 v[20:23], v[140:143], v[204:207], v[20:23]
	v_mfma_f32_16x16x32_bf16 v[12:15], v[148:151], v[204:207], v[12:15]
	v_mfma_f32_16x16x32_bf16 v[60:63], v[144:147], v[184:187], v[60:63]
	v_mfma_f32_16x16x32_bf16 v[56:59], v[152:155], v[184:187], v[56:59]
	v_mfma_f32_16x16x32_bf16 v[52:55], v[144:147], v[192:195], v[52:55]
	v_mfma_f32_16x16x32_bf16 v[48:51], v[152:155], v[192:195], v[48:51]
	v_mfma_f32_16x16x32_bf16 v[44:47], v[144:147], v[200:203], v[44:47]
	v_mfma_f32_16x16x32_bf16 v[32:35], v[152:155], v[200:203], v[32:35]
	v_mfma_f32_16x16x32_bf16 v[20:23], v[144:147], v[208:211], v[20:23]
	v_mfma_f32_16x16x32_bf16 v[12:15], v[152:155], v[208:211], v[12:15]
	v_mfma_f32_16x16x32_bf16 v[40:43], v[156:159], v[180:183], v[40:43]
	v_mfma_f32_16x16x32_bf16 v[36:39], v[172:175], v[180:183], v[36:39]
	v_mfma_f32_16x16x32_bf16 v[28:31], v[156:159], v[188:191], v[28:31]
	v_mfma_f32_16x16x32_bf16 v[24:27], v[172:175], v[188:191], v[24:27]
	v_mfma_f32_16x16x32_bf16 v[16:19], v[156:159], v[196:199], v[16:19]
	v_mfma_f32_16x16x32_bf16 v[8:11], v[172:175], v[196:199], v[8:11]
	v_mfma_f32_16x16x32_bf16 v[4:7], v[156:159], v[204:207], v[4:7]
	v_mfma_f32_16x16x32_bf16 v[0:3], v[172:175], v[204:207], v[0:3]
	v_mfma_f32_16x16x32_bf16 v[40:43], v[160:163], v[184:187], v[40:43]
	v_mfma_f32_16x16x32_bf16 v[36:39], v[176:179], v[184:187], v[36:39]
	v_mfma_f32_16x16x32_bf16 v[28:31], v[160:163], v[192:195], v[28:31]
	v_mfma_f32_16x16x32_bf16 v[24:27], v[176:179], v[192:195], v[24:27]
	v_mfma_f32_16x16x32_bf16 v[16:19], v[160:163], v[200:203], v[16:19]
	v_mfma_f32_16x16x32_bf16 v[8:11], v[176:179], v[200:203], v[8:11]
	v_mfma_f32_16x16x32_bf16 v[4:7], v[160:163], v[208:211], v[4:7]
	v_mfma_f32_16x16x32_bf16 v[0:3], v[176:179], v[208:211], v[0:3]
	s_barrier
	s_add_i32 s69, s69, 2
	s_add_u32 s67, s67, 0x100
	s_addc_u32 s68, s68, 0
	s_cmpk_gt_u32 s69, 0x55
	s_mov_b64 s[44:45], s[46:47]

; #define PG8_STAGE(bufoff, gbase, voff) do { _Pragma("unroll") for (int _i = 0; _i < 2; ++_i) \
;         __builtin_amdgcn_global_load_lds((const unsigned*)((const char*)(gbase) + (voff)[_i]), (PG8_LAS unsigned*)(lds + (bufoff) + ldsw + _i * 8192), 16, 0, 0); } while (0)
; #define PG8_LDA(dst, b, h) do { _Pragma("unroll") for (int m = 0; m < 4; ++m) _Pragma("unroll") for (int k = 0; k < 2; ++k) dst[m][k] = *(const PG8_LAS bf16x8*)(lds + PG8_SA(b, h) + aoff + m * 2048 + k * 1024); } while (0)
; #define PG8_LDB(dst, b, h) do { _Pragma("unroll") for (int n = 0; n < 2; ++n) _Pragma("unroll") for (int k = 0; k < 2; ++k) dst[n][k] = *(const PG8_LAS bf16x8*)(lds + PG8_SB(b, h) + boff + n * 2048 + k * 1024); } while (0)
; #define PG8_MMA(ai, bj, At, Bt) do { __builtin_amdgcn_s_setprio(1); _Pragma("unroll") for (int m = 0; m < 4; ++m) _Pragma("unroll") for (int n = 0; n < 2; ++n) _Pragma("unroll") for (int k = 0; k < 2; ++k) \
;         acc[ai][bj][m][n] = __builtin_amdgcn_mfma_f32_16x16x32_bf16(Bt[n][k], At[m][k], acc[ai][bj][m][n], 0, 0, 0); __builtin_amdgcn_s_setprio(0); } while (0)
; #define PG8_BAR __builtin_amdgcn_s_barrier()
; template <class Epi, class Sched, bool ALIGN_EPI = false, bool SP2 = false>
; __device__ __forceinline__ void gemm_phase(PG8_LAS unsigned char* lds, const Gemm g, const Sched& S, const Epi& E) {
;     ...
;         const bool has_next = S.next(ui + 1, nxt);
;         const char* nA = has_next ? (const char*)g.A + (size_t)nxt.pm * tstep : cA; const char* nB = has_next ? (const char*)g.Bt + (size_t)nxt.pn * tstep : cB;
;         for (int t = 0; t < nt; t += 2) {
;             const bool last = (t == nt - 2);
;             const char* a1 = cA + (size_t)(t + 1) * kstep;
;             const char* a2 = last ? nA : cA + (size_t)(t + 2) * kstep; const char* b2 = last ? nB : cB + (size_t)(t + 2) * kstep;
;             const char* a3 = a2 + kstep; const char* b3 = b2 + kstep;
;             if (last && has_next) S.a_ready(nxt);
;             if constexpr (SP2) {
;             PG8_LDB(B0, 0, 0); PG8_LDB(B1, 0, 1); PG8_SCHED; PG8_LDA(At, 0, 0); PG8_STAGE(PG8_SA(1, 1), a1 + hstep, voffA);
;             PG8_WAIT_V(8); PG8_WAIT_L(0); PG8_BAR; PG8_MMA(0, 0, At, B0); PG8_MMA(0, 1, At, B1); PG8_BAR; PG8_SCHED;
;             PG8_LDA(At, 0, 1); PG8_STAGE(PG8_SB(0, 0), b2, voffB); PG8_STAGE(PG8_SB(0, 1), b2 + hstep, voffB); PG8_STAGE(PG8_SA(0, 0), a2, voffA);
.LBB0_363:
	s_ashr_i32 s77, s76, 31
	s_lshl_b64 s[38:39], s[76:77], 20
	v_cmp_lt_i64_e32 vcc, s[78:79], v[178:179]
	s_add_u32 s78, s73, s38
	s_addc_u32 s79, s96, s39
	s_and_b64 s[38:39], vcc, exec
	s_cselect_b32 s77, s79, s85
	s_cselect_b32 s83, s78, s84
	s_ashr_i32 s75, s74, 31
	s_lshl_b64 s[38:39], s[74:75], 20
	s_add_u32 s80, s97, s38
	s_addc_u32 s81, s90, s39
	s_and_b64 s[38:39], vcc, exec
	s_cselect_b32 s75, s81, s87
	s_cselect_b32 vcc_lo, s80, s86
	s_add_u32 s84, s84, 0x80080
	s_addc_u32 s85, s85, 0
	s_add_u32 vcc_hi, s86, 0x100
	s_addc_u32 s38, s87, 0
	s_mov_b32 s39, -2
	ds_read_b128 v[128:131], v214
	ds_read_b128 v[132:135], v214 offset:1024
	ds_read_b128 v[136:139], v214 offset:2048
	ds_read_b128 v[140:143], v214 offset:3072
	ds_read_b128 v[144:147], v215
	ds_read_b128 v[148:151], v215 offset:1024
	ds_read_b128 v[152:155], v215 offset:2048
	ds_read_b128 v[156:159], v215 offset:3072
	s_add_u32 s58, s84, 0xfff80080
	s_addc_u32 s59, s85, -1
	s_cmp_eq_u32 s39, 28
	s_cselect_b32 s89, s77, s59
	s_cselect_b32 s88, s83, s58
	s_cselect_b32 s87, s75, s38
	s_cselect_b32 s86, vcc_lo, vcc_hi
	s_add_i32 m0, s7, 0xc000
	ds_read_b128 v[160:163], v216
	ds_read_b128 v[182:185], v216 offset:1024
	ds_read_b128 v[186:189], v216 offset:2048
	ds_read_b128 v[190:193], v216 offset:3072
	ds_read_b128 v[222:225], v216 offset:4096
	ds_read_b128 v[232:235], v216 offset:5120
	ds_read_b128 v[236:239], v216 offset:6144
	ds_read_b128 v[240:243], v216 offset:7168
	global_load_lds_dwordx4 v174, s[84:85]
	s_add_i32 m0, s7, 0xe000
	s_nop 0
	global_load_lds_dwordx4 v176, s[84:85]
	s_waitcnt vmcnt(8)
	s_waitcnt lgkmcnt(0)
	s_barrier
	s_waitcnt lgkmcnt(0)
	v_mfma_f32_16x16x32_bf16 v[124:127], v[128:131], v[160:163], 0
	v_mfma_f32_16x16x32_bf16 v[120:123], v[136:139], v[160:163], 0
	v_mfma_f32_16x16x32_bf16 v[116:119], v[128:131], v[186:189], 0
	v_mfma_f32_16x16x32_bf16 v[112:115], v[136:139], v[186:189], 0
	v_mfma_f32_16x16x32_bf16 v[100:103], v[128:131], v[222:225], 0
	v_mfma_f32_16x16x32_bf16 v[96:99], v[136:139], v[222:225], 0
	v_mfma_f32_16x16x32_bf16 v[84:87], v[128:131], v[236:239], 0
	v_mfma_f32_16x16x32_bf16 v[80:83], v[136:139], v[236:239], 0
	v_mfma_f32_16x16x32_bf16 v[124:127], v[132:135], v[182:185], v[124:127]
	v_mfma_f32_16x16x32_bf16 v[120:123], v[140:143], v[182:185], v[120:123]
	v_mfma_f32_16x16x32_bf16 v[116:119], v[132:135], v[190:193], v[116:119]
	v_mfma_f32_16x16x32_bf16 v[112:115], v[140:143], v[190:193], v[112:115]
	v_mfma_f32_16x16x32_bf16 v[100:103], v[132:135], v[232:235], v[100:103]
	v_mfma_f32_16x16x32_bf16 v[96:99], v[140:143], v[232:235], v[96:99]
	v_mfma_f32_16x16x32_bf16 v[84:87], v[132:135], v[240:243], v[84:87]
	v_mfma_f32_16x16x32_bf16 v[80:83], v[140:143], v[240:243], v[80:83]
	v_mfma_f32_16x16x32_bf16 v[108:111], v[144:147], v[160:163], 0
	v_mfma_f32_16x16x32_bf16 v[104:107], v[152:155], v[160:163], 0
	v_mfma_f32_16x16x32_bf16 v[92:95], v[144:147], v[186:189], 0
	v_mfma_f32_16x16x32_bf16 v[88:91], v[152:155], v[186:189], 0
	v_mfma_f32_16x16x32_bf16 v[76:79], v[144:147], v[222:225], 0
	v_mfma_f32_16x16x32_bf16 v[72:75], v[152:155], v[222:225], 0
	v_mfma_f32_16x16x32_bf16 v[68:71], v[144:147], v[236:239], 0
	v_mfma_f32_16x16x32_bf16 v[64:67], v[152:155], v[236:239], 0
	v_mfma_f32_16x16x32_bf16 v[108:111], v[148:151], v[182:185], v[108:111]
	v_mfma_f32_16x16x32_bf16 v[104:107], v[156:159], v[182:185], v[104:107]
	v_mfma_f32_16x16x32_bf16 v[92:95], v[148:151], v[190:193], v[92:95]
	v_mfma_f32_16x16x32_bf16 v[88:91], v[156:159], v[190:193], v[88:91]
	v_mfma_f32_16x16x32_bf16 v[76:79], v[148:151], v[232:235], v[76:79]
	v_mfma_f32_16x16x32_bf16 v[72:75], v[156:159], v[232:235], v[72:75]
	v_mfma_f32_16x16x32_bf16 v[68:71], v[148:151], v[240:243], v[68:71]
	v_mfma_f32_16x16x32_bf16 v[64:67], v[156:159], v[240:243], v[64:67]
	s_barrier
	s_add_i32 s58, s34, s24
	v_lshl_add_u64 v[194:195], s[86:87], 0, v[168:169]
	s_mov_b32 m0, s58
	ds_read_b128 v[160:163], v216 offset:16384
	ds_read_b128 v[182:185], v216 offset:17408
	ds_read_b128 v[186:189], v216 offset:18432
	ds_read_b128 v[190:193], v216 offset:19456
	ds_read_b128 v[222:225], v216 offset:20480
	ds_read_b128 v[232:235], v216 offset:21504
	ds_read_b128 v[236:239], v216 offset:22528
	ds_read_b128 v[240:243], v216 offset:23552
	global_load_lds_dwordx4 v168, s[86:87]
	s_add_i32 m0, s58, 0x2000
	s_add_u32 s58, s86, 0x80000
	v_lshl_add_u64 v[230:231], s[86:87], 0, v[164:165]
	s_addc_u32 s59, s87, 0
	s_add_i32 s48, s35, s24
	global_load_lds_dwordx4 v164, s[86:87]
	s_mov_b32 m0, s48
	v_lshl_add_u64 v[246:247], s[88:89], 0, v[166:167]
	global_load_lds_dwordx4 v168, s[58:59]
	s_add_i32 m0, s48, 0x2000
	s_nop 0
	global_load_lds_dwordx4 v164, s[58:59]
	v_lshl_add_u64 v[244:245], s[88:89], 0, v[170:171]
	s_mov_b32 m0, s7
	s_nop 0
	global_load_lds_dwordx4 v170, s[88:89]
	s_mov_b32 m0, s8
	s_nop 0
	global_load_lds_dwordx4 v166, s[88:89]
	s_waitcnt vmcnt(8)
	s_waitcnt lgkmcnt(0)
	s_barrier
; #define PG8_STAGE(bufoff, gbase, voff) do { _Pragma("unroll") for (int _i = 0; _i < 2; ++_i) \
;         __builtin_amdgcn_global_load_lds((const unsigned*)((const char*)(gbase) + (voff)[_i]), (PG8_LAS unsigned*)(lds + (bufoff) + ldsw + _i * 8192), 16, 0, 0); } while (0)
; #define PG8_LDA(dst, b, h) do { _Pragma("unroll") for (int m = 0; m < 4; ++m) _Pragma("unroll") for (int k = 0; k < 2; ++k) dst[m][k] = *(const PG8_LAS bf16x8*)(lds + PG8_SA(b, h) + aoff + m * 2048 + k * 1024); } while (0)
; #define PG8_LDB(dst, b, h) do { _Pragma("unroll") for (int n = 0; n < 2; ++n) _Pragma("unroll") for (int k = 0; k < 2; ++k) dst[n][k] = *(const PG8_LAS bf16x8*)(lds + PG8_SB(b, h) + boff + n * 2048 + k * 1024); } while (0)
; #define PG8_MMA(ai, bj, At, Bt) do { __builtin_amdgcn_s_setprio(1); _Pragma("unroll") for (int m = 0; m < 4; ++m) _Pragma("unroll") for (int n = 0; n < 2; ++n) _Pragma("unroll") for (int k = 0; k < 2; ++k) \
;         acc[ai][bj][m][n] = __builtin_amdgcn_mfma_f32_16x16x32_bf16(Bt[n][k], At[m][k], acc[ai][bj][m][n], 0, 0, 0); __builtin_amdgcn_s_setprio(0); } while (0)
; #define PG8_WAIT_V(n) asm volatile("s_waitcnt vmcnt(" #n ")" ::: "memory")
; #define PG8_WAIT_L(n) asm volatile("s_waitcnt lgkmcnt(" #n ")" ::: "memory")
; #define PG8_BAR __builtin_amdgcn_s_barrier()
; #define PG8_SCHED __builtin_amdgcn_sched_barrier(0)
; template <class Epi, class Sched, bool ALIGN_EPI = false, bool SP2 = false>
; __device__ __forceinline__ void gemm_phase(PG8_LAS unsigned char* lds, const Gemm g, const Sched& S, const Epi& E) {
;     ...
;             PG8_WAIT_V(8); PG8_WAIT_L(0); PG8_BAR; PG8_MMA(1, 0, At, B0); PG8_MMA(1, 1, At, B1); PG8_BAR; PG8_SCHED;
;             PG8_LDB(B0, 1, 0); PG8_LDB(B1, 1, 1); PG8_SCHED; PG8_LDA(At, 1, 0); PG8_STAGE(PG8_SA(0, 1), a2 + hstep, voffA);
;             PG8_WAIT_V(8); PG8_WAIT_L(0); PG8_BAR; PG8_MMA(0, 0, At, B0); PG8_MMA(0, 1, At, B1); PG8_BAR; PG8_SCHED;
	s_waitcnt lgkmcnt(0)
	v_mfma_f32_16x16x32_bf16 v[60:63], v[128:131], v[160:163], 0
	v_mfma_f32_16x16x32_bf16 v[56:59], v[136:139], v[160:163], 0
	v_mfma_f32_16x16x32_bf16 v[52:55], v[128:131], v[186:189], 0
	v_mfma_f32_16x16x32_bf16 v[48:51], v[136:139], v[186:189], 0
	v_mfma_f32_16x16x32_bf16 v[36:39], v[128:131], v[222:225], 0
	v_mfma_f32_16x16x32_bf16 v[32:35], v[136:139], v[222:225], 0
	v_mfma_f32_16x16x32_bf16 v[20:23], v[128:131], v[236:239], 0
	v_mfma_f32_16x16x32_bf16 v[16:19], v[136:139], v[236:239], 0
	v_mfma_f32_16x16x32_bf16 v[60:63], v[132:135], v[182:185], v[60:63]
	v_mfma_f32_16x16x32_bf16 v[56:59], v[140:143], v[182:185], v[56:59]
	v_mfma_f32_16x16x32_bf16 v[52:55], v[132:135], v[190:193], v[52:55]
	v_mfma_f32_16x16x32_bf16 v[48:51], v[140:143], v[190:193], v[48:51]
	v_mfma_f32_16x16x32_bf16 v[36:39], v[132:135], v[232:235], v[36:39]
	v_mfma_f32_16x16x32_bf16 v[32:35], v[140:143], v[232:235], v[32:35]
	v_mfma_f32_16x16x32_bf16 v[20:23], v[132:135], v[240:243], v[20:23]
	v_mfma_f32_16x16x32_bf16 v[16:19], v[140:143], v[240:243], v[16:19]
	v_mfma_f32_16x16x32_bf16 v[44:47], v[144:147], v[160:163], 0
	v_mfma_f32_16x16x32_bf16 v[40:43], v[152:155], v[160:163], 0
	v_mfma_f32_16x16x32_bf16 v[28:31], v[144:147], v[186:189], 0
	v_mfma_f32_16x16x32_bf16 v[24:27], v[152:155], v[186:189], 0
	v_mfma_f32_16x16x32_bf16 v[12:15], v[144:147], v[222:225], 0
	v_mfma_f32_16x16x32_bf16 v[8:11], v[152:155], v[222:225], 0
	v_mfma_f32_16x16x32_bf16 v[4:7], v[144:147], v[236:239], 0
	v_mfma_f32_16x16x32_bf16 v[0:3], v[152:155], v[236:239], 0
	v_mfma_f32_16x16x32_bf16 v[44:47], v[148:151], v[182:185], v[44:47]
	v_mfma_f32_16x16x32_bf16 v[40:43], v[156:159], v[182:185], v[40:43]
	v_mfma_f32_16x16x32_bf16 v[28:31], v[148:151], v[190:193], v[28:31]
	v_mfma_f32_16x16x32_bf16 v[24:27], v[156:159], v[190:193], v[24:27]
	v_mfma_f32_16x16x32_bf16 v[12:15], v[148:151], v[232:235], v[12:15]
	v_mfma_f32_16x16x32_bf16 v[8:11], v[156:159], v[232:235], v[8:11]
	v_mfma_f32_16x16x32_bf16 v[4:7], v[148:151], v[240:243], v[4:7]
	v_mfma_f32_16x16x32_bf16 v[0:3], v[156:159], v[240:243], v[0:3]
	s_barrier
	s_add_i32 s48, 0, 0x18000
	s_add_i32 s60, 0, 0x1c000
	v_add_u32_e32 v140, s48, v197
	v_add_u32_e32 v156, s60, v197
	ds_read_b128 v[128:131], v140
	ds_read_b128 v[132:135], v140 offset:1024
	ds_read_b128 v[136:139], v140 offset:2048
	ds_read_b128 v[140:143], v140 offset:3072
	ds_read_b128 v[144:147], v156
	ds_read_b128 v[148:151], v156 offset:1024
	ds_read_b128 v[152:155], v156 offset:2048
	ds_read_b128 v[156:159], v156 offset:3072
	s_add_u32 s58, s88, 0x80000
	s_addc_u32 s59, s89, 0
	s_mov_b32 m0, s9
	ds_read_b128 v[160:163], v216 offset:32768
	ds_read_b128 v[182:185], v216 offset:33792
	ds_read_b128 v[186:189], v216 offset:34816
	ds_read_b128 v[190:193], v216 offset:35840
	ds_read_b128 v[222:225], v216 offset:36864
	ds_read_b128 v[232:235], v216 offset:37888
	ds_read_b128 v[236:239], v216 offset:38912
	ds_read_b128 v[240:243], v216 offset:39936
	global_load_lds_dwordx4 v170, s[58:59]
	s_mov_b32 m0, s26
	s_nop 0
	global_load_lds_dwordx4 v166, s[58:59]
	s_waitcnt vmcnt(8)
	s_waitcnt lgkmcnt(0)
	s_barrier
	s_waitcnt lgkmcnt(0)
	v_mfma_f32_16x16x32_bf16 v[124:127], v[128:131], v[160:163], v[124:127]
	v_mfma_f32_16x16x32_bf16 v[120:123], v[136:139], v[160:163], v[120:123]
	v_mfma_f32_16x16x32_bf16 v[116:119], v[128:131], v[186:189], v[116:119]
	v_mfma_f32_16x16x32_bf16 v[112:115], v[136:139], v[186:189], v[112:115]
	v_mfma_f32_16x16x32_bf16 v[100:103], v[128:131], v[222:225], v[100:103]
	v_mfma_f32_16x16x32_bf16 v[96:99], v[136:139], v[222:225], v[96:99]
	v_mfma_f32_16x16x32_bf16 v[84:87], v[128:131], v[236:239], v[84:87]
	v_mfma_f32_16x16x32_bf16 v[80:83], v[136:139], v[236:239], v[80:83]
	v_mfma_f32_16x16x32_bf16 v[124:127], v[132:135], v[182:185], v[124:127]
	v_mfma_f32_16x16x32_bf16 v[120:123], v[140:143], v[182:185], v[120:123]
	v_mfma_f32_16x16x32_bf16 v[116:119], v[132:135], v[190:193], v[116:119]
	v_mfma_f32_16x16x32_bf16 v[112:115], v[140:143], v[190:193], v[112:115]
	v_mfma_f32_16x16x32_bf16 v[100:103], v[132:135], v[232:235], v[100:103]
	v_mfma_f32_16x16x32_bf16 v[96:99], v[140:143], v[232:235], v[96:99]
	v_mfma_f32_16x16x32_bf16 v[84:87], v[132:135], v[240:243], v[84:87]
	v_mfma_f32_16x16x32_bf16 v[80:83], v[140:143], v[240:243], v[80:83]
	v_mfma_f32_16x16x32_bf16 v[108:111], v[144:147], v[160:163], v[108:111]
	v_mfma_f32_16x16x32_bf16 v[104:107], v[152:155], v[160:163], v[104:107]
	v_mfma_f32_16x16x32_bf16 v[92:95], v[144:147], v[186:189], v[92:95]
	v_mfma_f32_16x16x32_bf16 v[88:91], v[152:155], v[186:189], v[88:91]
	v_mfma_f32_16x16x32_bf16 v[76:79], v[144:147], v[222:225], v[76:79]
	v_mfma_f32_16x16x32_bf16 v[72:75], v[152:155], v[222:225], v[72:75]
	v_mfma_f32_16x16x32_bf16 v[68:71], v[144:147], v[236:239], v[68:71]
	v_mfma_f32_16x16x32_bf16 v[64:67], v[152:155], v[236:239], v[64:67]
	v_mfma_f32_16x16x32_bf16 v[108:111], v[148:151], v[182:185], v[108:111]
	v_mfma_f32_16x16x32_bf16 v[104:107], v[156:159], v[182:185], v[104:107]
	v_mfma_f32_16x16x32_bf16 v[92:95], v[148:151], v[190:193], v[92:95]
	v_mfma_f32_16x16x32_bf16 v[88:91], v[156:159], v[190:193], v[88:91]
	v_mfma_f32_16x16x32_bf16 v[76:79], v[148:151], v[232:235], v[76:79]
	v_mfma_f32_16x16x32_bf16 v[72:75], v[156:159], v[232:235], v[72:75]
	v_mfma_f32_16x16x32_bf16 v[68:71], v[148:151], v[240:243], v[68:71]
	v_mfma_f32_16x16x32_bf16 v[64:67], v[156:159], v[240:243], v[64:67]
	s_barrier
; #define PG8_STAGE(bufoff, gbase, voff) do { _Pragma("unroll") for (int _i = 0; _i < 2; ++_i) \
;         __builtin_amdgcn_global_load_lds((const unsigned*)((const char*)(gbase) + (voff)[_i]), (PG8_LAS unsigned*)(lds + (bufoff) + ldsw + _i * 8192), 16, 0, 0); } while (0)
; #define PG8_LDA(dst, b, h) do { _Pragma("unroll") for (int m = 0; m < 4; ++m) _Pragma("unroll") for (int k = 0; k < 2; ++k) dst[m][k] = *(const PG8_LAS bf16x8*)(lds + PG8_SA(b, h) + aoff + m * 2048 + k * 1024); } while (0)
; #define PG8_MMA(ai, bj, At, Bt) do { __builtin_amdgcn_s_setprio(1); _Pragma("unroll") for (int m = 0; m < 4; ++m) _Pragma("unroll") for (int n = 0; n < 2; ++n) _Pragma("unroll") for (int k = 0; k < 2; ++k) \
;         acc[ai][bj][m][n] = __builtin_amdgcn_mfma_f32_16x16x32_bf16(Bt[n][k], At[m][k], acc[ai][bj][m][n], 0, 0, 0); __builtin_amdgcn_s_setprio(0); } while (0)
; #define PG8_WAIT_V(n) asm volatile("s_waitcnt vmcnt(" #n ")" ::: "memory")
; #define PG8_WAIT_L(n) asm volatile("s_waitcnt lgkmcnt(" #n ")" ::: "memory")
; #define PG8_BAR __builtin_amdgcn_s_barrier()
; #define PG8_SCHED __builtin_amdgcn_sched_barrier(0)
; template <class Epi, class Sched, bool ALIGN_EPI = false, bool SP2 = false>
; __device__ __forceinline__ void gemm_phase(PG8_LAS unsigned char* lds, const Gemm g, const Sched& S, const Epi& E) {
;     ...
;             PG8_LDA(At, 1, 1); PG8_STAGE(PG8_SB(1, 0), b3, voffB); PG8_STAGE(PG8_SB(1, 1), b3 + hstep, voffB); PG8_STAGE(PG8_SA(1, 0), a3, voffA);
;             PG8_WAIT_V(8); PG8_WAIT_L(0); PG8_BAR; PG8_MMA(1, 0, At, B0); PG8_MMA(1, 1, At, B1); PG8_BAR; PG8_SCHED;
	s_add_i32 s48, s48, s24
	v_lshl_add_u64 v[194:195], v[194:195], 0, s[54:55]
	s_mov_b32 m0, s48
	ds_read_b128 v[160:163], v216 offset:49152
	ds_read_b128 v[182:185], v216 offset:50176
	ds_read_b128 v[186:189], v216 offset:51200
	ds_read_b128 v[190:193], v216 offset:52224
	ds_read_b128 v[222:225], v216 offset:53248
	ds_read_b128 v[232:235], v216 offset:54272
	ds_read_b128 v[236:239], v216 offset:55296
	ds_read_b128 v[240:243], v216 offset:56320
	global_load_lds_dwordx4 v[194:195], off
	s_add_i32 m0, s48, 0x2000
	s_add_u32 s58, s86, 0x80080
	v_lshl_add_u64 v[194:195], v[230:231], 0, s[54:55]
	s_addc_u32 s59, s87, 0
	s_add_i32 s48, s60, s24
	global_load_lds_dwordx4 v[194:195], off
	s_mov_b32 m0, s48
	s_nop 0
	global_load_lds_dwordx4 v168, s[58:59]
	s_add_i32 m0, s48, 0x2000
	s_nop 0
	global_load_lds_dwordx4 v164, s[58:59]
	v_lshl_add_u64 v[194:195], v[244:245], 0, s[54:55]
	s_mov_b32 m0, s36
	s_nop 0
	global_load_lds_dwordx4 v[194:195], off
	v_lshl_add_u64 v[194:195], v[246:247], 0, s[54:55]
	s_mov_b32 m0, s37
	s_nop 0
	global_load_lds_dwordx4 v[194:195], off
	s_waitcnt vmcnt(8)
	s_waitcnt lgkmcnt(0)
	s_barrier
	s_waitcnt lgkmcnt(0)
	v_mfma_f32_16x16x32_bf16 v[60:63], v[128:131], v[160:163], v[60:63]
	v_mfma_f32_16x16x32_bf16 v[56:59], v[136:139], v[160:163], v[56:59]
	v_mfma_f32_16x16x32_bf16 v[52:55], v[128:131], v[186:189], v[52:55]
	v_mfma_f32_16x16x32_bf16 v[48:51], v[136:139], v[186:189], v[48:51]
	v_mfma_f32_16x16x32_bf16 v[36:39], v[128:131], v[222:225], v[36:39]
	v_mfma_f32_16x16x32_bf16 v[32:35], v[136:139], v[222:225], v[32:35]
	v_mfma_f32_16x16x32_bf16 v[20:23], v[128:131], v[236:239], v[20:23]
	v_mfma_f32_16x16x32_bf16 v[16:19], v[136:139], v[236:239], v[16:19]
	v_mfma_f32_16x16x32_bf16 v[60:63], v[132:135], v[182:185], v[60:63]
	v_mfma_f32_16x16x32_bf16 v[56:59], v[140:143], v[182:185], v[56:59]
	v_mfma_f32_16x16x32_bf16 v[52:55], v[132:135], v[190:193], v[52:55]
	v_mfma_f32_16x16x32_bf16 v[48:51], v[140:143], v[190:193], v[48:51]
	v_mfma_f32_16x16x32_bf16 v[36:39], v[132:135], v[232:235], v[36:39]
	v_mfma_f32_16x16x32_bf16 v[32:35], v[140:143], v[232:235], v[32:35]
	v_mfma_f32_16x16x32_bf16 v[20:23], v[132:135], v[240:243], v[20:23]
	v_mfma_f32_16x16x32_bf16 v[16:19], v[140:143], v[240:243], v[16:19]
	v_mfma_f32_16x16x32_bf16 v[44:47], v[144:147], v[160:163], v[44:47]
	v_mfma_f32_16x16x32_bf16 v[40:43], v[152:155], v[160:163], v[40:43]
	v_mfma_f32_16x16x32_bf16 v[28:31], v[144:147], v[186:189], v[28:31]
	v_mfma_f32_16x16x32_bf16 v[24:27], v[152:155], v[186:189], v[24:27]
	v_mfma_f32_16x16x32_bf16 v[12:15], v[144:147], v[222:225], v[12:15]
	v_mfma_f32_16x16x32_bf16 v[8:11], v[152:155], v[222:225], v[8:11]
	v_mfma_f32_16x16x32_bf16 v[4:7], v[144:147], v[236:239], v[4:7]
	v_mfma_f32_16x16x32_bf16 v[0:3], v[152:155], v[236:239], v[0:3]
	v_mfma_f32_16x16x32_bf16 v[44:47], v[148:151], v[182:185], v[44:47]
	v_mfma_f32_16x16x32_bf16 v[40:43], v[156:159], v[182:185], v[40:43]
	v_mfma_f32_16x16x32_bf16 v[28:31], v[148:151], v[190:193], v[28:31]
	v_mfma_f32_16x16x32_bf16 v[24:27], v[156:159], v[190:193], v[24:27]
	v_mfma_f32_16x16x32_bf16 v[12:15], v[148:151], v[232:235], v[12:15]
	v_mfma_f32_16x16x32_bf16 v[8:11], v[156:159], v[232:235], v[8:11]
	v_mfma_f32_16x16x32_bf16 v[4:7], v[148:151], v[240:243], v[4:7]
	v_mfma_f32_16x16x32_bf16 v[0:3], v[156:159], v[240:243], v[0:3]
	s_barrier
	s_add_i32 s39, s39, 2
	s_add_u32 s84, s84, 0x100
	s_addc_u32 s85, s85, 0
	s_add_u32 vcc_hi, vcc_hi, 0x100
	s_addc_u32 s38, s38, 0
	s_cmp_gt_u32 s39, 29

; #define PG8_STAGE(bufoff, gbase, voff) do { _Pragma("unroll") for (int _i = 0; _i < 2; ++_i) \
;         __builtin_amdgcn_global_load_lds((const unsigned*)((const char*)(gbase) + (voff)[_i]), (PG8_LAS unsigned*)(lds + (bufoff) + ldsw + _i * 8192), 16, 0, 0); } while (0)
; #define PG8_LDA(dst, b, h) do { _Pragma("unroll") for (int m = 0; m < 4; ++m) _Pragma("unroll") for (int k = 0; k < 2; ++k) dst[m][k] = *(const PG8_LAS bf16x8*)(lds + PG8_SA(b, h) + aoff + m * 2048 + k * 1024); } while (0)
; #define PG8_LDB(dst, b, h) do { _Pragma("unroll") for (int n = 0; n < 2; ++n) _Pragma("unroll") for (int k = 0; k < 2; ++k) dst[n][k] = *(const PG8_LAS bf16x8*)(lds + PG8_SB(b, h) + boff + n * 2048 + k * 1024); } while (0)
; #define PG8_MMA(ai, bj, At, Bt) do { __builtin_amdgcn_s_setprio(1); _Pragma("unroll") for (int m = 0; m < 4; ++m) _Pragma("unroll") for (int n = 0; n < 2; ++n) _Pragma("unroll") for (int k = 0; k < 2; ++k) \
;         acc[ai][bj][m][n] = __builtin_amdgcn_mfma_f32_16x16x32_bf16(Bt[n][k], At[m][k], acc[ai][bj][m][n], 0, 0, 0); __builtin_amdgcn_s_setprio(0); } while (0)
; #define PG8_BAR __builtin_amdgcn_s_barrier()
; template <class Epi, class Sched, bool ALIGN_EPI = false, bool SP2 = false>
; __device__ __forceinline__ void gemm_phase(PG8_LAS unsigned char* lds, const Gemm g, const Sched& S, const Epi& E) {
;     ...
;         const bool has_next = S.next(ui + 1, nxt);
;         const char* nA = has_next ? (const char*)g.A + (size_t)nxt.pm * tstep : cA; const char* nB = has_next ? (const char*)g.Bt + (size_t)nxt.pn * tstep : cB;
;         for (int t = 0; t < nt; t += 2) {
;             const bool last = (t == nt - 2);
;             const char* a1 = cA + (size_t)(t + 1) * kstep;
;             const char* a2 = last ? nA : cA + (size_t)(t + 2) * kstep; const char* b2 = last ? nB : cB + (size_t)(t + 2) * kstep;
;             const char* a3 = a2 + kstep; const char* b3 = b2 + kstep;
;             if (last && has_next) S.a_ready(nxt);
;             if constexpr (SP2) {
;             PG8_LDB(B0, 0, 0); PG8_LDB(B1, 0, 1); PG8_SCHED; PG8_LDA(At, 0, 0); PG8_STAGE(PG8_SA(1, 1), a1 + hstep, voffA);
;             PG8_WAIT_V(8); PG8_WAIT_L(0); PG8_BAR; PG8_MMA(0, 0, At, B0); PG8_MMA(0, 1, At, B1); PG8_BAR; PG8_SCHED;
;             PG8_LDA(At, 0, 1); PG8_STAGE(PG8_SB(0, 0), b2, voffB); PG8_STAGE(PG8_SB(0, 1), b2 + hstep, voffB); PG8_STAGE(PG8_SA(0, 0), a2, voffA);
.LBB0_734:
	s_ashr_i32 s39, s38, 31
	v_cmp_lt_i64_e32 vcc, s[40:41], v[140:141]
	s_lshl_b64 s[40:41], s[38:39], 19
	s_add_u32 s40, s9, s40
	s_addc_u32 s41, s22, s41
	s_and_b64 s[42:43], vcc, exec
	s_cselect_b32 s39, s41, s47
	s_cselect_b32 s65, s40, s46
	s_ashr_i32 s37, s36, 31
	s_lshl_b64 s[42:43], s[36:37], 19
	s_add_u32 s42, s23, s42
	s_addc_u32 s43, s52, s43
	s_and_b64 s[50:51], vcc, exec
	s_cselect_b32 s37, s43, s49
	s_cselect_b32 s66, s42, s48
	s_add_u32 s46, s46, 0x40080
	s_addc_u32 s47, s47, 0
	s_add_u32 s67, s48, 0x100
	s_addc_u32 s68, s49, 0
	s_mov_b32 s69, -2
	ds_read_b128 v[144:147], v155
	ds_read_b128 v[148:151], v155 offset:1024
	ds_read_b128 v[158:161], v155 offset:2048
	ds_read_b128 v[162:165], v155 offset:3072
	ds_read_b128 v[166:169], v156
	ds_read_b128 v[170:173], v156 offset:1024
	ds_read_b128 v[174:177], v156 offset:2048
	ds_read_b128 v[178:181], v156 offset:3072
	s_add_u32 s48, s46, 0xfffc0080
	s_addc_u32 s49, s47, -1
	s_cmp_eq_u32 s69, 12
	s_cselect_b32 s51, s39, s49
	s_cselect_b32 s50, s65, s48
	s_cselect_b32 s49, s37, s68
	s_cselect_b32 s48, s66, s67
	s_add_i32 m0, s45, 0xc000
	ds_read_b128 v[182:185], v157
	ds_read_b128 v[186:189], v157 offset:1024
	ds_read_b128 v[190:193], v157 offset:2048
	ds_read_b128 v[194:197], v157 offset:3072
	ds_read_b128 v[198:201], v157 offset:4096
	ds_read_b128 v[202:205], v157 offset:5120
	ds_read_b128 v[206:209], v157 offset:6144
	ds_read_b128 v[214:217], v157 offset:7168
	global_load_lds_dwordx4 v136, s[46:47]
	s_add_i32 m0, s45, 0xe000
	s_nop 0
	global_load_lds_dwordx4 v138, s[46:47]
	s_waitcnt vmcnt(8)
	s_waitcnt lgkmcnt(0)
	s_barrier
	s_waitcnt lgkmcnt(0)
	v_mfma_f32_16x16x32_bf16 v[124:127], v[144:147], v[182:185], 0
	v_mfma_f32_16x16x32_bf16 v[120:123], v[158:161], v[182:185], 0
	v_mfma_f32_16x16x32_bf16 v[116:119], v[144:147], v[190:193], 0
	v_mfma_f32_16x16x32_bf16 v[112:115], v[158:161], v[190:193], 0
	v_mfma_f32_16x16x32_bf16 v[96:99], v[144:147], v[198:201], 0
	v_mfma_f32_16x16x32_bf16 v[88:91], v[158:161], v[198:201], 0
	v_mfma_f32_16x16x32_bf16 v[80:83], v[144:147], v[206:209], 0
	v_mfma_f32_16x16x32_bf16 v[72:75], v[158:161], v[206:209], 0
	v_mfma_f32_16x16x32_bf16 v[124:127], v[148:151], v[186:189], v[124:127]
	v_mfma_f32_16x16x32_bf16 v[120:123], v[162:165], v[186:189], v[120:123]
	v_mfma_f32_16x16x32_bf16 v[116:119], v[148:151], v[194:197], v[116:119]
	v_mfma_f32_16x16x32_bf16 v[112:115], v[162:165], v[194:197], v[112:115]
	v_mfma_f32_16x16x32_bf16 v[96:99], v[148:151], v[202:205], v[96:99]
	v_mfma_f32_16x16x32_bf16 v[88:91], v[162:165], v[202:205], v[88:91]
	v_mfma_f32_16x16x32_bf16 v[80:83], v[148:151], v[214:217], v[80:83]
	v_mfma_f32_16x16x32_bf16 v[72:75], v[162:165], v[214:217], v[72:75]
	v_mfma_f32_16x16x32_bf16 v[108:111], v[166:169], v[182:185], 0
	v_mfma_f32_16x16x32_bf16 v[104:107], v[174:177], v[182:185], 0
	v_mfma_f32_16x16x32_bf16 v[100:103], v[166:169], v[190:193], 0
	v_mfma_f32_16x16x32_bf16 v[92:95], v[174:177], v[190:193], 0
	v_mfma_f32_16x16x32_bf16 v[84:87], v[166:169], v[198:201], 0
	v_mfma_f32_16x16x32_bf16 v[76:79], v[174:177], v[198:201], 0
	v_mfma_f32_16x16x32_bf16 v[68:71], v[166:169], v[206:209], 0
	v_mfma_f32_16x16x32_bf16 v[64:67], v[174:177], v[206:209], 0
	v_mfma_f32_16x16x32_bf16 v[108:111], v[170:173], v[186:189], v[108:111]
	v_mfma_f32_16x16x32_bf16 v[104:107], v[178:181], v[186:189], v[104:107]
	v_mfma_f32_16x16x32_bf16 v[100:103], v[170:173], v[194:197], v[100:103]
	v_mfma_f32_16x16x32_bf16 v[92:95], v[178:181], v[194:197], v[92:95]
	v_mfma_f32_16x16x32_bf16 v[84:87], v[170:173], v[202:205], v[84:87]
	v_mfma_f32_16x16x32_bf16 v[76:79], v[178:181], v[202:205], v[76:79]
	v_mfma_f32_16x16x32_bf16 v[68:71], v[170:173], v[214:217], v[68:71]
	v_mfma_f32_16x16x32_bf16 v[64:67], v[178:181], v[214:217], v[64:67]
	s_barrier
	s_add_i32 s70, s62, s53
	s_mov_b32 m0, s70
	ds_read_b128 v[182:185], v157 offset:16384
	ds_read_b128 v[186:189], v157 offset:17408
	ds_read_b128 v[190:193], v157 offset:18432
	ds_read_b128 v[194:197], v157 offset:19456
	ds_read_b128 v[198:201], v157 offset:20480
	ds_read_b128 v[202:205], v157 offset:21504
	ds_read_b128 v[206:209], v157 offset:22528
	ds_read_b128 v[214:217], v157 offset:23552
	global_load_lds_dwordx4 v130, s[48:49]
	s_add_i32 m0, s70, 0x2000
	s_add_u32 s70, s48, 0x40000
	s_addc_u32 s71, s49, 0
	s_add_i32 s72, s63, s53
	global_load_lds_dwordx4 v134, s[48:49]
	s_mov_b32 m0, s72
	s_nop 0
	global_load_lds_dwordx4 v130, s[70:71]
	s_add_i32 m0, s72, 0x2000
	s_nop 0
	global_load_lds_dwordx4 v134, s[70:71]
	s_mov_b32 m0, s45
	s_nop 0
	global_load_lds_dwordx4 v128, s[50:51]
	s_mov_b32 m0, s54
	s_nop 0
	global_load_lds_dwordx4 v132, s[50:51]
	s_waitcnt vmcnt(8)
	s_waitcnt lgkmcnt(0)
	s_barrier
; #define PG8_STAGE(bufoff, gbase, voff) do { _Pragma("unroll") for (int _i = 0; _i < 2; ++_i) \
;         __builtin_amdgcn_global_load_lds((const unsigned*)((const char*)(gbase) + (voff)[_i]), (PG8_LAS unsigned*)(lds + (bufoff) + ldsw + _i * 8192), 16, 0, 0); } while (0)
; #define PG8_LDA(dst, b, h) do { _Pragma("unroll") for (int m = 0; m < 4; ++m) _Pragma("unroll") for (int k = 0; k < 2; ++k) dst[m][k] = *(const PG8_LAS bf16x8*)(lds + PG8_SA(b, h) + aoff + m * 2048 + k * 1024); } while (0)
; #define PG8_LDB(dst, b, h) do { _Pragma("unroll") for (int n = 0; n < 2; ++n) _Pragma("unroll") for (int k = 0; k < 2; ++k) dst[n][k] = *(const PG8_LAS bf16x8*)(lds + PG8_SB(b, h) + boff + n * 2048 + k * 1024); } while (0)
; #define PG8_MMA(ai, bj, At, Bt) do { __builtin_amdgcn_s_setprio(1); _Pragma("unroll") for (int m = 0; m < 4; ++m) _Pragma("unroll") for (int n = 0; n < 2; ++n) _Pragma("unroll") for (int k = 0; k < 2; ++k) \
;         acc[ai][bj][m][n] = __builtin_amdgcn_mfma_f32_16x16x32_bf16(Bt[n][k], At[m][k], acc[ai][bj][m][n], 0, 0, 0); __builtin_amdgcn_s_setprio(0); } while (0)
; #define PG8_WAIT_V(n) asm volatile("s_waitcnt vmcnt(" #n ")" ::: "memory")
; #define PG8_WAIT_L(n) asm volatile("s_waitcnt lgkmcnt(" #n ")" ::: "memory")
; #define PG8_BAR __builtin_amdgcn_s_barrier()
; #define PG8_SCHED __builtin_amdgcn_sched_barrier(0)
; template <class Epi, class Sched, bool ALIGN_EPI = false, bool SP2 = false>
; __device__ __forceinline__ void gemm_phase(PG8_LAS unsigned char* lds, const Gemm g, const Sched& S, const Epi& E) {
;     ...
;             PG8_WAIT_V(8); PG8_WAIT_L(0); PG8_BAR; PG8_MMA(1, 0, At, B0); PG8_MMA(1, 1, At, B1); PG8_BAR; PG8_SCHED;
;             PG8_LDB(B0, 1, 0); PG8_LDB(B1, 1, 1); PG8_SCHED; PG8_LDA(At, 1, 0); PG8_STAGE(PG8_SA(0, 1), a2 + hstep, voffA);
;             PG8_WAIT_V(8); PG8_WAIT_L(0); PG8_BAR; PG8_MMA(0, 0, At, B0); PG8_MMA(0, 1, At, B1); PG8_BAR; PG8_SCHED;
	s_waitcnt lgkmcnt(0)
	v_mfma_f32_16x16x32_bf16 v[60:63], v[144:147], v[182:185], 0
	v_mfma_f32_16x16x32_bf16 v[56:59], v[158:161], v[182:185], 0
	v_mfma_f32_16x16x32_bf16 v[48:51], v[144:147], v[190:193], 0
	v_mfma_f32_16x16x32_bf16 v[40:43], v[158:161], v[190:193], 0
	v_mfma_f32_16x16x32_bf16 v[32:35], v[144:147], v[198:201], 0
	v_mfma_f32_16x16x32_bf16 v[24:27], v[158:161], v[198:201], 0
	v_mfma_f32_16x16x32_bf16 v[16:19], v[144:147], v[206:209], 0
	v_mfma_f32_16x16x32_bf16 v[8:11], v[158:161], v[206:209], 0
	v_mfma_f32_16x16x32_bf16 v[60:63], v[148:151], v[186:189], v[60:63]
	v_mfma_f32_16x16x32_bf16 v[56:59], v[162:165], v[186:189], v[56:59]
	v_mfma_f32_16x16x32_bf16 v[48:51], v[148:151], v[194:197], v[48:51]
	v_mfma_f32_16x16x32_bf16 v[40:43], v[162:165], v[194:197], v[40:43]
	v_mfma_f32_16x16x32_bf16 v[32:35], v[148:151], v[202:205], v[32:35]
	v_mfma_f32_16x16x32_bf16 v[24:27], v[162:165], v[202:205], v[24:27]
	v_mfma_f32_16x16x32_bf16 v[16:19], v[148:151], v[214:217], v[16:19]
	v_mfma_f32_16x16x32_bf16 v[8:11], v[162:165], v[214:217], v[8:11]
	v_mfma_f32_16x16x32_bf16 v[52:55], v[166:169], v[182:185], 0
	v_mfma_f32_16x16x32_bf16 v[44:47], v[174:177], v[182:185], 0
	v_mfma_f32_16x16x32_bf16 v[36:39], v[166:169], v[190:193], 0
	v_mfma_f32_16x16x32_bf16 v[28:31], v[174:177], v[190:193], 0
	v_mfma_f32_16x16x32_bf16 v[20:23], v[166:169], v[198:201], 0
	v_mfma_f32_16x16x32_bf16 v[12:15], v[174:177], v[198:201], 0
	v_mfma_f32_16x16x32_bf16 v[4:7], v[166:169], v[206:209], 0
	v_mfma_f32_16x16x32_bf16 v[0:3], v[174:177], v[206:209], 0
	v_mfma_f32_16x16x32_bf16 v[52:55], v[170:173], v[186:189], v[52:55]
	v_mfma_f32_16x16x32_bf16 v[44:47], v[178:181], v[186:189], v[44:47]
	v_mfma_f32_16x16x32_bf16 v[36:39], v[170:173], v[194:197], v[36:39]
	v_mfma_f32_16x16x32_bf16 v[28:31], v[178:181], v[194:197], v[28:31]
	v_mfma_f32_16x16x32_bf16 v[20:23], v[170:173], v[202:205], v[20:23]
	v_mfma_f32_16x16x32_bf16 v[12:15], v[178:181], v[202:205], v[12:15]
	v_mfma_f32_16x16x32_bf16 v[4:7], v[170:173], v[214:217], v[4:7]
	v_mfma_f32_16x16x32_bf16 v[0:3], v[178:181], v[214:217], v[0:3]
	s_barrier
	s_add_i32 s70, 0, 0x18000
	s_add_i32 s71, 0, 0x1c000
	v_add_u32_e32 v162, s70, v153
	v_add_u32_e32 v178, s71, v153
	ds_read_b128 v[144:147], v162
	ds_read_b128 v[148:151], v162 offset:1024
	ds_read_b128 v[158:161], v162 offset:2048
	ds_read_b128 v[162:165], v162 offset:3072
	ds_read_b128 v[166:169], v178
	ds_read_b128 v[170:173], v178 offset:1024
	ds_read_b128 v[174:177], v178 offset:2048
	ds_read_b128 v[178:181], v178 offset:3072
	s_add_u32 s80, s50, 0x80
	s_addc_u32 s81, s51, 0
	s_add_u32 s50, s50, 0x40000
	s_addc_u32 s51, s51, 0
	s_mov_b32 m0, s55
	ds_read_b128 v[182:185], v157 offset:32768
	ds_read_b128 v[186:189], v157 offset:33792
	ds_read_b128 v[190:193], v157 offset:34816
	ds_read_b128 v[194:197], v157 offset:35840
	ds_read_b128 v[198:201], v157 offset:36864
	ds_read_b128 v[202:205], v157 offset:37888
	ds_read_b128 v[206:209], v157 offset:38912
	ds_read_b128 v[214:217], v157 offset:39936
	global_load_lds_dwordx4 v128, s[50:51]
	s_mov_b32 m0, s56
	s_nop 0
	global_load_lds_dwordx4 v132, s[50:51]
	s_waitcnt vmcnt(8)
	s_waitcnt lgkmcnt(0)
	s_barrier
	s_waitcnt lgkmcnt(0)
	v_mfma_f32_16x16x32_bf16 v[124:127], v[144:147], v[182:185], v[124:127]
	v_mfma_f32_16x16x32_bf16 v[120:123], v[158:161], v[182:185], v[120:123]
	v_mfma_f32_16x16x32_bf16 v[116:119], v[144:147], v[190:193], v[116:119]
	v_mfma_f32_16x16x32_bf16 v[112:115], v[158:161], v[190:193], v[112:115]
	v_mfma_f32_16x16x32_bf16 v[96:99], v[144:147], v[198:201], v[96:99]
	v_mfma_f32_16x16x32_bf16 v[88:91], v[158:161], v[198:201], v[88:91]
	v_mfma_f32_16x16x32_bf16 v[80:83], v[144:147], v[206:209], v[80:83]
	v_mfma_f32_16x16x32_bf16 v[72:75], v[158:161], v[206:209], v[72:75]
	v_mfma_f32_16x16x32_bf16 v[124:127], v[148:151], v[186:189], v[124:127]
	v_mfma_f32_16x16x32_bf16 v[120:123], v[162:165], v[186:189], v[120:123]
	v_mfma_f32_16x16x32_bf16 v[116:119], v[148:151], v[194:197], v[116:119]
	v_mfma_f32_16x16x32_bf16 v[112:115], v[162:165], v[194:197], v[112:115]
	v_mfma_f32_16x16x32_bf16 v[96:99], v[148:151], v[202:205], v[96:99]
	v_mfma_f32_16x16x32_bf16 v[88:91], v[162:165], v[202:205], v[88:91]
	v_mfma_f32_16x16x32_bf16 v[80:83], v[148:151], v[214:217], v[80:83]
	v_mfma_f32_16x16x32_bf16 v[72:75], v[162:165], v[214:217], v[72:75]
	v_mfma_f32_16x16x32_bf16 v[108:111], v[166:169], v[182:185], v[108:111]
	v_mfma_f32_16x16x32_bf16 v[104:107], v[174:177], v[182:185], v[104:107]
	v_mfma_f32_16x16x32_bf16 v[100:103], v[166:169], v[190:193], v[100:103]
	v_mfma_f32_16x16x32_bf16 v[92:95], v[174:177], v[190:193], v[92:95]
	v_mfma_f32_16x16x32_bf16 v[84:87], v[166:169], v[198:201], v[84:87]
	v_mfma_f32_16x16x32_bf16 v[76:79], v[174:177], v[198:201], v[76:79]
	v_mfma_f32_16x16x32_bf16 v[68:71], v[166:169], v[206:209], v[68:71]
	v_mfma_f32_16x16x32_bf16 v[64:67], v[174:177], v[206:209], v[64:67]
	v_mfma_f32_16x16x32_bf16 v[108:111], v[170:173], v[186:189], v[108:111]
	v_mfma_f32_16x16x32_bf16 v[104:107], v[178:181], v[186:189], v[104:107]
	v_mfma_f32_16x16x32_bf16 v[100:103], v[170:173], v[194:197], v[100:103]
	v_mfma_f32_16x16x32_bf16 v[92:95], v[178:181], v[194:197], v[92:95]
	v_mfma_f32_16x16x32_bf16 v[84:87], v[170:173], v[202:205], v[84:87]
	v_mfma_f32_16x16x32_bf16 v[76:79], v[178:181], v[202:205], v[76:79]
	v_mfma_f32_16x16x32_bf16 v[68:71], v[170:173], v[214:217], v[68:71]
	v_mfma_f32_16x16x32_bf16 v[64:67], v[178:181], v[214:217], v[64:67]
	s_barrier
; #define PG8_STAGE(bufoff, gbase, voff) do { _Pragma("unroll") for (int _i = 0; _i < 2; ++_i) \
;         __builtin_amdgcn_global_load_lds((const unsigned*)((const char*)(gbase) + (voff)[_i]), (PG8_LAS unsigned*)(lds + (bufoff) + ldsw + _i * 8192), 16, 0, 0); } while (0)
; #define PG8_LDA(dst, b, h) do { _Pragma("unroll") for (int m = 0; m < 4; ++m) _Pragma("unroll") for (int k = 0; k < 2; ++k) dst[m][k] = *(const PG8_LAS bf16x8*)(lds + PG8_SA(b, h) + aoff + m * 2048 + k * 1024); } while (0)
; #define PG8_MMA(ai, bj, At, Bt) do { __builtin_amdgcn_s_setprio(1); _Pragma("unroll") for (int m = 0; m < 4; ++m) _Pragma("unroll") for (int n = 0; n < 2; ++n) _Pragma("unroll") for (int k = 0; k < 2; ++k) \
;         acc[ai][bj][m][n] = __builtin_amdgcn_mfma_f32_16x16x32_bf16(Bt[n][k], At[m][k], acc[ai][bj][m][n], 0, 0, 0); __builtin_amdgcn_s_setprio(0); } while (0)
; #define PG8_WAIT_V(n) asm volatile("s_waitcnt vmcnt(" #n ")" ::: "memory")
; #define PG8_WAIT_L(n) asm volatile("s_waitcnt lgkmcnt(" #n ")" ::: "memory")
; #define PG8_BAR __builtin_amdgcn_s_barrier()
; #define PG8_SCHED __builtin_amdgcn_sched_barrier(0)
; template <class Epi, class Sched, bool ALIGN_EPI = false, bool SP2 = false>
; __device__ __forceinline__ void gemm_phase(PG8_LAS unsigned char* lds, const Gemm g, const Sched& S, const Epi& E) {
;     ...
;             PG8_LDA(At, 1, 1); PG8_STAGE(PG8_SB(1, 0), b3, voffB); PG8_STAGE(PG8_SB(1, 1), b3 + hstep, voffB); PG8_STAGE(PG8_SA(1, 0), a3, voffA);
;             PG8_WAIT_V(8); PG8_WAIT_L(0); PG8_BAR; PG8_MMA(1, 0, At, B0); PG8_MMA(1, 1, At, B1); PG8_BAR; PG8_SCHED;
	s_add_i32 s50, s70, s53
	s_add_u32 s82, s48, 0x80
	s_addc_u32 s83, s49, 0
	s_mov_b32 m0, s50
	ds_read_b128 v[182:185], v157 offset:49152
	ds_read_b128 v[186:189], v157 offset:50176
	ds_read_b128 v[190:193], v157 offset:51200
	ds_read_b128 v[194:197], v157 offset:52224
	ds_read_b128 v[198:201], v157 offset:53248
	ds_read_b128 v[202:205], v157 offset:54272
	ds_read_b128 v[206:209], v157 offset:55296
	ds_read_b128 v[214:217], v157 offset:56320
	global_load_lds_dwordx4 v130, s[82:83]
	s_add_i32 m0, s50, 0x2000
	s_add_u32 s48, s48, 0x40080
	s_addc_u32 s49, s49, 0
	s_add_i32 s50, s71, s53
	global_load_lds_dwordx4 v134, s[82:83]
	s_mov_b32 m0, s50
	s_nop 0
	global_load_lds_dwordx4 v130, s[48:49]
	s_add_i32 m0, s50, 0x2000
	s_nop 0
	global_load_lds_dwordx4 v134, s[48:49]
	s_mov_b32 m0, s58
	s_nop 0
	global_load_lds_dwordx4 v128, s[80:81]
	s_mov_b32 m0, s59
	s_nop 0
	global_load_lds_dwordx4 v132, s[80:81]
	s_waitcnt vmcnt(8)
	s_waitcnt lgkmcnt(0)
	s_barrier
	s_waitcnt lgkmcnt(0)
	v_mfma_f32_16x16x32_bf16 v[60:63], v[144:147], v[182:185], v[60:63]
	v_mfma_f32_16x16x32_bf16 v[56:59], v[158:161], v[182:185], v[56:59]
	v_mfma_f32_16x16x32_bf16 v[48:51], v[144:147], v[190:193], v[48:51]
	v_mfma_f32_16x16x32_bf16 v[40:43], v[158:161], v[190:193], v[40:43]
	v_mfma_f32_16x16x32_bf16 v[32:35], v[144:147], v[198:201], v[32:35]
	v_mfma_f32_16x16x32_bf16 v[24:27], v[158:161], v[198:201], v[24:27]
	v_mfma_f32_16x16x32_bf16 v[16:19], v[144:147], v[206:209], v[16:19]
	v_mfma_f32_16x16x32_bf16 v[8:11], v[158:161], v[206:209], v[8:11]
	v_mfma_f32_16x16x32_bf16 v[60:63], v[148:151], v[186:189], v[60:63]
	v_mfma_f32_16x16x32_bf16 v[56:59], v[162:165], v[186:189], v[56:59]
	v_mfma_f32_16x16x32_bf16 v[48:51], v[148:151], v[194:197], v[48:51]
	v_mfma_f32_16x16x32_bf16 v[40:43], v[162:165], v[194:197], v[40:43]
	v_mfma_f32_16x16x32_bf16 v[32:35], v[148:151], v[202:205], v[32:35]
	v_mfma_f32_16x16x32_bf16 v[24:27], v[162:165], v[202:205], v[24:27]
	v_mfma_f32_16x16x32_bf16 v[16:19], v[148:151], v[214:217], v[16:19]
	v_mfma_f32_16x16x32_bf16 v[8:11], v[162:165], v[214:217], v[8:11]
	v_mfma_f32_16x16x32_bf16 v[52:55], v[166:169], v[182:185], v[52:55]
	v_mfma_f32_16x16x32_bf16 v[44:47], v[174:177], v[182:185], v[44:47]
	v_mfma_f32_16x16x32_bf16 v[36:39], v[166:169], v[190:193], v[36:39]
	v_mfma_f32_16x16x32_bf16 v[28:31], v[174:177], v[190:193], v[28:31]
	v_mfma_f32_16x16x32_bf16 v[20:23], v[166:169], v[198:201], v[20:23]
	v_mfma_f32_16x16x32_bf16 v[12:15], v[174:177], v[198:201], v[12:15]
	v_mfma_f32_16x16x32_bf16 v[4:7], v[166:169], v[206:209], v[4:7]
	v_mfma_f32_16x16x32_bf16 v[0:3], v[174:177], v[206:209], v[0:3]
	v_mfma_f32_16x16x32_bf16 v[52:55], v[170:173], v[186:189], v[52:55]
	v_mfma_f32_16x16x32_bf16 v[44:47], v[178:181], v[186:189], v[44:47]
	v_mfma_f32_16x16x32_bf16 v[36:39], v[170:173], v[194:197], v[36:39]
	v_mfma_f32_16x16x32_bf16 v[28:31], v[178:181], v[194:197], v[28:31]
	v_mfma_f32_16x16x32_bf16 v[20:23], v[170:173], v[202:205], v[20:23]
	v_mfma_f32_16x16x32_bf16 v[12:15], v[178:181], v[202:205], v[12:15]
	v_mfma_f32_16x16x32_bf16 v[4:7], v[170:173], v[214:217], v[4:7]
	v_mfma_f32_16x16x32_bf16 v[0:3], v[178:181], v[214:217], v[0:3]
	s_barrier
	s_add_i32 s69, s69, 2
	s_add_u32 s46, s46, 0x100
	s_addc_u32 s47, s47, 0
	s_add_u32 s67, s67, 0x100
	s_addc_u32 s68, s68, 0
	s_cmp_gt_u32 s69, 13

; #define PG8_STAGE(bufoff, gbase, voff) do { _Pragma("unroll") for (int _i = 0; _i < 2; ++_i) \
;         __builtin_amdgcn_global_load_lds((const unsigned*)((const char*)(gbase) + (voff)[_i]), (PG8_LAS unsigned*)(lds + (bufoff) + ldsw + _i * 8192), 16, 0, 0); } while (0)
; #define PG8_LDA(dst, b, h) do { _Pragma("unroll") for (int m = 0; m < 4; ++m) _Pragma("unroll") for (int k = 0; k < 2; ++k) dst[m][k] = *(const PG8_LAS bf16x8*)(lds + PG8_SA(b, h) + aoff + m * 2048 + k * 1024); } while (0)
; #define PG8_LDB(dst, b, h) do { _Pragma("unroll") for (int n = 0; n < 2; ++n) _Pragma("unroll") for (int k = 0; k < 2; ++k) dst[n][k] = *(const PG8_LAS bf16x8*)(lds + PG8_SB(b, h) + boff + n * 2048 + k * 1024); } while (0)
; #define PG8_MMA(ai, bj, At, Bt) do { __builtin_amdgcn_s_setprio(1); _Pragma("unroll") for (int m = 0; m < 4; ++m) _Pragma("unroll") for (int n = 0; n < 2; ++n) _Pragma("unroll") for (int k = 0; k < 2; ++k) \
;         acc[ai][bj][m][n] = __builtin_amdgcn_mfma_f32_16x16x32_bf16(Bt[n][k], At[m][k], acc[ai][bj][m][n], 0, 0, 0); __builtin_amdgcn_s_setprio(0); } while (0)
; #define PG8_BAR __builtin_amdgcn_s_barrier()
; template <class Epi, class Sched, bool ALIGN_EPI = false, bool SP2 = false>
; __device__ __forceinline__ void gemm_phase(PG8_LAS unsigned char* lds, const Gemm g, const Sched& S, const Epi& E) {
;     ...
;         const bool has_next = S.next(ui + 1, nxt);
;         const char* nA = has_next ? (const char*)g.A + (size_t)nxt.pm * tstep : cA; const char* nB = has_next ? (const char*)g.Bt + (size_t)nxt.pn * tstep : cB;
;         for (int t = 0; t < nt; t += 2) {
;             const bool last = (t == nt - 2);
;             const char* a1 = cA + (size_t)(t + 1) * kstep;
;             const char* a2 = last ? nA : cA + (size_t)(t + 2) * kstep; const char* b2 = last ? nB : cB + (size_t)(t + 2) * kstep;
;             const char* a3 = a2 + kstep; const char* b3 = b2 + kstep;
;             if (last && has_next) S.a_ready(nxt);
;             if constexpr (SP2) {
;             PG8_LDB(B0, 0, 0); PG8_LDB(B1, 0, 1); PG8_SCHED; PG8_LDA(At, 0, 0); PG8_STAGE(PG8_SA(1, 1), a1 + hstep, voffA);
;             PG8_WAIT_V(8); PG8_WAIT_L(0); PG8_BAR; PG8_MMA(0, 0, At, B0); PG8_MMA(0, 1, At, B1); PG8_BAR; PG8_SCHED;
;             PG8_LDA(At, 0, 1); PG8_STAGE(PG8_SB(0, 0), b2, voffB); PG8_STAGE(PG8_SB(0, 1), b2 + hstep, voffB); PG8_STAGE(PG8_SA(0, 0), a2, voffA);
.LBB0_754:
	s_ashr_i32 s29, s28, 31
	v_cmp_lt_i64_e32 vcc, s[30:31], v[160:161]
	s_lshl_b64 s[30:31], s[28:29], 19
	s_add_u32 s30, s9, s30
	s_addc_u32 s31, s22, s31
	s_and_b64 s[34:35], vcc, exec
	s_cselect_b32 s29, s31, s39
	s_cselect_b32 s57, s30, s38
	s_ashr_i32 s27, s26, 31
	s_lshl_b64 s[34:35], s[26:27], 19
	s_add_u32 s34, s23, s34
	s_addc_u32 s35, s44, s35
	s_and_b64 s[42:43], vcc, exec
	s_cselect_b32 s27, s35, s41
	s_cselect_b32 s58, s34, s40
	s_add_u32 s38, s38, 0x40080
	s_addc_u32 s39, s39, 0
	s_add_u32 s59, s40, 0x100
	s_addc_u32 s60, s41, 0
	s_mov_b32 s61, -2
	ds_read_b128 v[128:131], v177
	ds_read_b128 v[132:135], v177 offset:1024
	ds_read_b128 v[136:139], v177 offset:2048
	ds_read_b128 v[140:143], v177 offset:3072
	ds_read_b128 v[144:147], v178
	ds_read_b128 v[164:167], v178 offset:1024
	ds_read_b128 v[168:171], v178 offset:2048
	ds_read_b128 v[180:183], v178 offset:3072
	s_add_u32 s40, s38, 0xfffc0080
	s_addc_u32 s41, s39, -1
	s_cmp_eq_u32 s61, 12
	s_cselect_b32 s43, s29, s41
	s_cselect_b32 s42, s57, s40
	s_cselect_b32 s41, s27, s60
	s_cselect_b32 s40, s58, s59
	s_add_i32 m0, s37, 0xc000
	ds_read_b128 v[184:187], v179
	ds_read_b128 v[188:191], v179 offset:1024
	ds_read_b128 v[192:195], v179 offset:2048
	ds_read_b128 v[196:199], v179 offset:3072
	ds_read_b128 v[200:203], v179 offset:4096
	ds_read_b128 v[204:207], v179 offset:5120
	ds_read_b128 v[208:211], v179 offset:6144
	ds_read_b128 v[214:217], v179 offset:7168
	global_load_lds_dwordx4 v156, s[38:39]
	s_add_i32 m0, s37, 0xe000
	s_nop 0
	global_load_lds_dwordx4 v158, s[38:39]
	s_waitcnt vmcnt(8)
	s_waitcnt lgkmcnt(0)
	s_barrier
	s_waitcnt lgkmcnt(0)
	v_mfma_f32_16x16x32_bf16 v[124:127], v[128:131], v[184:187], 0
	v_mfma_f32_16x16x32_bf16 v[120:123], v[136:139], v[184:187], 0
	v_mfma_f32_16x16x32_bf16 v[108:111], v[128:131], v[192:195], 0
	v_mfma_f32_16x16x32_bf16 v[104:107], v[136:139], v[192:195], 0
	v_mfma_f32_16x16x32_bf16 v[92:95], v[128:131], v[200:203], 0
	v_mfma_f32_16x16x32_bf16 v[88:91], v[136:139], v[200:203], 0
	v_mfma_f32_16x16x32_bf16 v[76:79], v[128:131], v[208:211], 0
	v_mfma_f32_16x16x32_bf16 v[72:75], v[136:139], v[208:211], 0
	v_mfma_f32_16x16x32_bf16 v[124:127], v[132:135], v[188:191], v[124:127]
	v_mfma_f32_16x16x32_bf16 v[120:123], v[140:143], v[188:191], v[120:123]
	v_mfma_f32_16x16x32_bf16 v[108:111], v[132:135], v[196:199], v[108:111]
	v_mfma_f32_16x16x32_bf16 v[104:107], v[140:143], v[196:199], v[104:107]
	v_mfma_f32_16x16x32_bf16 v[92:95], v[132:135], v[204:207], v[92:95]
	v_mfma_f32_16x16x32_bf16 v[88:91], v[140:143], v[204:207], v[88:91]
	v_mfma_f32_16x16x32_bf16 v[76:79], v[132:135], v[214:217], v[76:79]
	v_mfma_f32_16x16x32_bf16 v[72:75], v[140:143], v[214:217], v[72:75]
	v_mfma_f32_16x16x32_bf16 v[116:119], v[144:147], v[184:187], 0
	v_mfma_f32_16x16x32_bf16 v[112:115], v[168:171], v[184:187], 0
	v_mfma_f32_16x16x32_bf16 v[100:103], v[144:147], v[192:195], 0
	v_mfma_f32_16x16x32_bf16 v[96:99], v[168:171], v[192:195], 0
	v_mfma_f32_16x16x32_bf16 v[84:87], v[144:147], v[200:203], 0
	v_mfma_f32_16x16x32_bf16 v[80:83], v[168:171], v[200:203], 0
	v_mfma_f32_16x16x32_bf16 v[68:71], v[144:147], v[208:211], 0
	v_mfma_f32_16x16x32_bf16 v[64:67], v[168:171], v[208:211], 0
	v_mfma_f32_16x16x32_bf16 v[116:119], v[164:167], v[188:191], v[116:119]
	v_mfma_f32_16x16x32_bf16 v[112:115], v[180:183], v[188:191], v[112:115]
	v_mfma_f32_16x16x32_bf16 v[100:103], v[164:167], v[196:199], v[100:103]
	v_mfma_f32_16x16x32_bf16 v[96:99], v[180:183], v[196:199], v[96:99]
	v_mfma_f32_16x16x32_bf16 v[84:87], v[164:167], v[204:207], v[84:87]
	v_mfma_f32_16x16x32_bf16 v[80:83], v[180:183], v[204:207], v[80:83]
	v_mfma_f32_16x16x32_bf16 v[68:71], v[164:167], v[214:217], v[68:71]
	v_mfma_f32_16x16x32_bf16 v[64:67], v[180:183], v[214:217], v[64:67]
	s_barrier
	s_add_i32 s62, s54, s45
	s_mov_b32 m0, s62
	ds_read_b128 v[184:187], v179 offset:16384
	ds_read_b128 v[188:191], v179 offset:17408
	ds_read_b128 v[192:195], v179 offset:18432
	ds_read_b128 v[196:199], v179 offset:19456
	ds_read_b128 v[200:203], v179 offset:20480
	ds_read_b128 v[204:207], v179 offset:21504
	ds_read_b128 v[208:211], v179 offset:22528
	ds_read_b128 v[214:217], v179 offset:23552
	global_load_lds_dwordx4 v150, s[40:41]
	s_add_i32 m0, s62, 0x2000
	s_add_u32 s62, s40, 0x40000
	s_addc_u32 s63, s41, 0
	s_add_i32 s64, s55, s45
	global_load_lds_dwordx4 v154, s[40:41]
	s_mov_b32 m0, s64
	s_nop 0
	global_load_lds_dwordx4 v150, s[62:63]
	s_add_i32 m0, s64, 0x2000
	s_nop 0
	global_load_lds_dwordx4 v154, s[62:63]
	s_mov_b32 m0, s37
	s_nop 0
	global_load_lds_dwordx4 v148, s[42:43]
	s_mov_b32 m0, s46
	s_nop 0
	global_load_lds_dwordx4 v152, s[42:43]
	s_waitcnt vmcnt(8)
	s_waitcnt lgkmcnt(0)
	s_barrier
; #define PG8_STAGE(bufoff, gbase, voff) do { _Pragma("unroll") for (int _i = 0; _i < 2; ++_i) \
;         __builtin_amdgcn_global_load_lds((const unsigned*)((const char*)(gbase) + (voff)[_i]), (PG8_LAS unsigned*)(lds + (bufoff) + ldsw + _i * 8192), 16, 0, 0); } while (0)
; #define PG8_LDA(dst, b, h) do { _Pragma("unroll") for (int m = 0; m < 4; ++m) _Pragma("unroll") for (int k = 0; k < 2; ++k) dst[m][k] = *(const PG8_LAS bf16x8*)(lds + PG8_SA(b, h) + aoff + m * 2048 + k * 1024); } while (0)
; #define PG8_LDB(dst, b, h) do { _Pragma("unroll") for (int n = 0; n < 2; ++n) _Pragma("unroll") for (int k = 0; k < 2; ++k) dst[n][k] = *(const PG8_LAS bf16x8*)(lds + PG8_SB(b, h) + boff + n * 2048 + k * 1024); } while (0)
; #define PG8_MMA(ai, bj, At, Bt) do { __builtin_amdgcn_s_setprio(1); _Pragma("unroll") for (int m = 0; m < 4; ++m) _Pragma("unroll") for (int n = 0; n < 2; ++n) _Pragma("unroll") for (int k = 0; k < 2; ++k) \
;         acc[ai][bj][m][n] = __builtin_amdgcn_mfma_f32_16x16x32_bf16(Bt[n][k], At[m][k], acc[ai][bj][m][n], 0, 0, 0); __builtin_amdgcn_s_setprio(0); } while (0)
; #define PG8_WAIT_V(n) asm volatile("s_waitcnt vmcnt(" #n ")" ::: "memory")
; #define PG8_WAIT_L(n) asm volatile("s_waitcnt lgkmcnt(" #n ")" ::: "memory")
; #define PG8_BAR __builtin_amdgcn_s_barrier()
; #define PG8_SCHED __builtin_amdgcn_sched_barrier(0)
; template <class Epi, class Sched, bool ALIGN_EPI = false, bool SP2 = false>
; __device__ __forceinline__ void gemm_phase(PG8_LAS unsigned char* lds, const Gemm g, const Sched& S, const Epi& E) {
;     ...
;             PG8_WAIT_V(8); PG8_WAIT_L(0); PG8_BAR; PG8_MMA(1, 0, At, B0); PG8_MMA(1, 1, At, B1); PG8_BAR; PG8_SCHED;
;             PG8_LDB(B0, 1, 0); PG8_LDB(B1, 1, 1); PG8_SCHED; PG8_LDA(At, 1, 0); PG8_STAGE(PG8_SA(0, 1), a2 + hstep, voffA);
;             PG8_WAIT_V(8); PG8_WAIT_L(0); PG8_BAR; PG8_MMA(0, 0, At, B0); PG8_MMA(0, 1, At, B1); PG8_BAR; PG8_SCHED;
	s_waitcnt lgkmcnt(0)
	v_mfma_f32_16x16x32_bf16 v[60:63], v[128:131], v[184:187], 0
	v_mfma_f32_16x16x32_bf16 v[56:59], v[136:139], v[184:187], 0
	v_mfma_f32_16x16x32_bf16 v[44:47], v[128:131], v[192:195], 0
	v_mfma_f32_16x16x32_bf16 v[40:43], v[136:139], v[192:195], 0
	v_mfma_f32_16x16x32_bf16 v[28:31], v[128:131], v[200:203], 0
	v_mfma_f32_16x16x32_bf16 v[24:27], v[136:139], v[200:203], 0
	v_mfma_f32_16x16x32_bf16 v[12:15], v[128:131], v[208:211], 0
	v_mfma_f32_16x16x32_bf16 v[8:11], v[136:139], v[208:211], 0
	v_mfma_f32_16x16x32_bf16 v[60:63], v[132:135], v[188:191], v[60:63]
	v_mfma_f32_16x16x32_bf16 v[56:59], v[140:143], v[188:191], v[56:59]
	v_mfma_f32_16x16x32_bf16 v[44:47], v[132:135], v[196:199], v[44:47]
	v_mfma_f32_16x16x32_bf16 v[40:43], v[140:143], v[196:199], v[40:43]
	v_mfma_f32_16x16x32_bf16 v[28:31], v[132:135], v[204:207], v[28:31]
	v_mfma_f32_16x16x32_bf16 v[24:27], v[140:143], v[204:207], v[24:27]
	v_mfma_f32_16x16x32_bf16 v[12:15], v[132:135], v[214:217], v[12:15]
	v_mfma_f32_16x16x32_bf16 v[8:11], v[140:143], v[214:217], v[8:11]
	v_mfma_f32_16x16x32_bf16 v[52:55], v[144:147], v[184:187], 0
	v_mfma_f32_16x16x32_bf16 v[48:51], v[168:171], v[184:187], 0
	v_mfma_f32_16x16x32_bf16 v[36:39], v[144:147], v[192:195], 0
	v_mfma_f32_16x16x32_bf16 v[32:35], v[168:171], v[192:195], 0
	v_mfma_f32_16x16x32_bf16 v[20:23], v[144:147], v[200:203], 0
	v_mfma_f32_16x16x32_bf16 v[16:19], v[168:171], v[200:203], 0
	v_mfma_f32_16x16x32_bf16 v[4:7], v[144:147], v[208:211], 0
	v_mfma_f32_16x16x32_bf16 v[0:3], v[168:171], v[208:211], 0
	v_mfma_f32_16x16x32_bf16 v[52:55], v[164:167], v[188:191], v[52:55]
	v_mfma_f32_16x16x32_bf16 v[48:51], v[180:183], v[188:191], v[48:51]
	v_mfma_f32_16x16x32_bf16 v[36:39], v[164:167], v[196:199], v[36:39]
	v_mfma_f32_16x16x32_bf16 v[32:35], v[180:183], v[196:199], v[32:35]
	v_mfma_f32_16x16x32_bf16 v[20:23], v[164:167], v[204:207], v[20:23]
	v_mfma_f32_16x16x32_bf16 v[16:19], v[180:183], v[204:207], v[16:19]
	v_mfma_f32_16x16x32_bf16 v[4:7], v[164:167], v[214:217], v[4:7]
	v_mfma_f32_16x16x32_bf16 v[0:3], v[180:183], v[214:217], v[0:3]
	s_barrier
	s_add_i32 s62, 0, 0x18000
	s_add_i32 s63, 0, 0x1c000
	v_add_u32_e32 v140, s62, v175
	v_add_u32_e32 v180, s63, v175
	ds_read_b128 v[128:131], v140
	ds_read_b128 v[132:135], v140 offset:1024
	ds_read_b128 v[136:139], v140 offset:2048
	ds_read_b128 v[140:143], v140 offset:3072
	ds_read_b128 v[144:147], v180
	ds_read_b128 v[164:167], v180 offset:1024
	ds_read_b128 v[168:171], v180 offset:2048
	ds_read_b128 v[180:183], v180 offset:3072
	s_add_u32 s84, s42, 0x80
	s_addc_u32 s85, s43, 0
	s_add_u32 s42, s42, 0x40000
	s_addc_u32 s43, s43, 0
	s_mov_b32 m0, s47
	ds_read_b128 v[184:187], v179 offset:32768
	ds_read_b128 v[188:191], v179 offset:33792
	ds_read_b128 v[192:195], v179 offset:34816
	ds_read_b128 v[196:199], v179 offset:35840
	ds_read_b128 v[200:203], v179 offset:36864
	ds_read_b128 v[204:207], v179 offset:37888
	ds_read_b128 v[208:211], v179 offset:38912
	ds_read_b128 v[214:217], v179 offset:39936
	global_load_lds_dwordx4 v148, s[42:43]
	s_mov_b32 m0, s48
	s_nop 0
	global_load_lds_dwordx4 v152, s[42:43]
	s_waitcnt vmcnt(8)
	s_waitcnt lgkmcnt(0)
	s_barrier
	s_waitcnt lgkmcnt(0)
	v_mfma_f32_16x16x32_bf16 v[124:127], v[128:131], v[184:187], v[124:127]
	v_mfma_f32_16x16x32_bf16 v[120:123], v[136:139], v[184:187], v[120:123]
	v_mfma_f32_16x16x32_bf16 v[108:111], v[128:131], v[192:195], v[108:111]
	v_mfma_f32_16x16x32_bf16 v[104:107], v[136:139], v[192:195], v[104:107]
	v_mfma_f32_16x16x32_bf16 v[92:95], v[128:131], v[200:203], v[92:95]
	v_mfma_f32_16x16x32_bf16 v[88:91], v[136:139], v[200:203], v[88:91]
	v_mfma_f32_16x16x32_bf16 v[76:79], v[128:131], v[208:211], v[76:79]
	v_mfma_f32_16x16x32_bf16 v[72:75], v[136:139], v[208:211], v[72:75]
	v_mfma_f32_16x16x32_bf16 v[124:127], v[132:135], v[188:191], v[124:127]
	v_mfma_f32_16x16x32_bf16 v[120:123], v[140:143], v[188:191], v[120:123]
	v_mfma_f32_16x16x32_bf16 v[108:111], v[132:135], v[196:199], v[108:111]
	v_mfma_f32_16x16x32_bf16 v[104:107], v[140:143], v[196:199], v[104:107]
	v_mfma_f32_16x16x32_bf16 v[92:95], v[132:135], v[204:207], v[92:95]
	v_mfma_f32_16x16x32_bf16 v[88:91], v[140:143], v[204:207], v[88:91]
	v_mfma_f32_16x16x32_bf16 v[76:79], v[132:135], v[214:217], v[76:79]
	v_mfma_f32_16x16x32_bf16 v[72:75], v[140:143], v[214:217], v[72:75]
	v_mfma_f32_16x16x32_bf16 v[116:119], v[144:147], v[184:187], v[116:119]
	v_mfma_f32_16x16x32_bf16 v[112:115], v[168:171], v[184:187], v[112:115]
	v_mfma_f32_16x16x32_bf16 v[100:103], v[144:147], v[192:195], v[100:103]
	v_mfma_f32_16x16x32_bf16 v[96:99], v[168:171], v[192:195], v[96:99]
	v_mfma_f32_16x16x32_bf16 v[84:87], v[144:147], v[200:203], v[84:87]
	v_mfma_f32_16x16x32_bf16 v[80:83], v[168:171], v[200:203], v[80:83]
	v_mfma_f32_16x16x32_bf16 v[68:71], v[144:147], v[208:211], v[68:71]
	v_mfma_f32_16x16x32_bf16 v[64:67], v[168:171], v[208:211], v[64:67]
	v_mfma_f32_16x16x32_bf16 v[116:119], v[164:167], v[188:191], v[116:119]
	v_mfma_f32_16x16x32_bf16 v[112:115], v[180:183], v[188:191], v[112:115]
	v_mfma_f32_16x16x32_bf16 v[100:103], v[164:167], v[196:199], v[100:103]
	v_mfma_f32_16x16x32_bf16 v[96:99], v[180:183], v[196:199], v[96:99]
	v_mfma_f32_16x16x32_bf16 v[84:87], v[164:167], v[204:207], v[84:87]
	v_mfma_f32_16x16x32_bf16 v[80:83], v[180:183], v[204:207], v[80:83]
	v_mfma_f32_16x16x32_bf16 v[68:71], v[164:167], v[214:217], v[68:71]
	v_mfma_f32_16x16x32_bf16 v[64:67], v[180:183], v[214:217], v[64:67]
	s_barrier
; #define PG8_STAGE(bufoff, gbase, voff) do { _Pragma("unroll") for (int _i = 0; _i < 2; ++_i) \
;         __builtin_amdgcn_global_load_lds((const unsigned*)((const char*)(gbase) + (voff)[_i]), (PG8_LAS unsigned*)(lds + (bufoff) + ldsw + _i * 8192), 16, 0, 0); } while (0)
; #define PG8_LDA(dst, b, h) do { _Pragma("unroll") for (int m = 0; m < 4; ++m) _Pragma("unroll") for (int k = 0; k < 2; ++k) dst[m][k] = *(const PG8_LAS bf16x8*)(lds + PG8_SA(b, h) + aoff + m * 2048 + k * 1024); } while (0)
; #define PG8_MMA(ai, bj, At, Bt) do { __builtin_amdgcn_s_setprio(1); _Pragma("unroll") for (int m = 0; m < 4; ++m) _Pragma("unroll") for (int n = 0; n < 2; ++n) _Pragma("unroll") for (int k = 0; k < 2; ++k) \
;         acc[ai][bj][m][n] = __builtin_amdgcn_mfma_f32_16x16x32_bf16(Bt[n][k], At[m][k], acc[ai][bj][m][n], 0, 0, 0); __builtin_amdgcn_s_setprio(0); } while (0)
; #define PG8_WAIT_V(n) asm volatile("s_waitcnt vmcnt(" #n ")" ::: "memory")
; #define PG8_WAIT_L(n) asm volatile("s_waitcnt lgkmcnt(" #n ")" ::: "memory")
; #define PG8_BAR __builtin_amdgcn_s_barrier()
; #define PG8_SCHED __builtin_amdgcn_sched_barrier(0)
; template <class Epi, class Sched, bool ALIGN_EPI = false, bool SP2 = false>
; __device__ __forceinline__ void gemm_phase(PG8_LAS unsigned char* lds, const Gemm g, const Sched& S, const Epi& E) {
;     ...
;             PG8_LDA(At, 1, 1); PG8_STAGE(PG8_SB(1, 0), b3, voffB); PG8_STAGE(PG8_SB(1, 1), b3 + hstep, voffB); PG8_STAGE(PG8_SA(1, 0), a3, voffA);
;             PG8_WAIT_V(8); PG8_WAIT_L(0); PG8_BAR; PG8_MMA(1, 0, At, B0); PG8_MMA(1, 1, At, B1); PG8_BAR; PG8_SCHED;
	s_add_i32 s42, s62, s45
	s_add_u32 s86, s40, 0x80
	s_addc_u32 s87, s41, 0
	s_mov_b32 m0, s42
	ds_read_b128 v[184:187], v179 offset:49152
	ds_read_b128 v[188:191], v179 offset:50176
	ds_read_b128 v[192:195], v179 offset:51200
	ds_read_b128 v[196:199], v179 offset:52224
	ds_read_b128 v[200:203], v179 offset:53248
	ds_read_b128 v[204:207], v179 offset:54272
	ds_read_b128 v[208:211], v179 offset:55296
	ds_read_b128 v[214:217], v179 offset:56320
	global_load_lds_dwordx4 v150, s[86:87]
	s_add_i32 m0, s42, 0x2000
	s_add_u32 s40, s40, 0x40080
	s_addc_u32 s41, s41, 0
	s_add_i32 s42, s63, s45
	global_load_lds_dwordx4 v154, s[86:87]
	s_mov_b32 m0, s42
	s_nop 0
	global_load_lds_dwordx4 v150, s[40:41]
	s_add_i32 m0, s42, 0x2000
	s_nop 0
	global_load_lds_dwordx4 v154, s[40:41]
	s_mov_b32 m0, s50
	s_nop 0
	global_load_lds_dwordx4 v148, s[84:85]
	s_mov_b32 m0, s51
	s_nop 0
	global_load_lds_dwordx4 v152, s[84:85]
	s_waitcnt vmcnt(8)
	s_waitcnt lgkmcnt(0)
	s_barrier
	s_waitcnt lgkmcnt(0)
	v_mfma_f32_16x16x32_bf16 v[60:63], v[128:131], v[184:187], v[60:63]
	v_mfma_f32_16x16x32_bf16 v[56:59], v[136:139], v[184:187], v[56:59]
	v_mfma_f32_16x16x32_bf16 v[44:47], v[128:131], v[192:195], v[44:47]
	v_mfma_f32_16x16x32_bf16 v[40:43], v[136:139], v[192:195], v[40:43]
	v_mfma_f32_16x16x32_bf16 v[28:31], v[128:131], v[200:203], v[28:31]
	v_mfma_f32_16x16x32_bf16 v[24:27], v[136:139], v[200:203], v[24:27]
	v_mfma_f32_16x16x32_bf16 v[12:15], v[128:131], v[208:211], v[12:15]
	v_mfma_f32_16x16x32_bf16 v[8:11], v[136:139], v[208:211], v[8:11]
	v_mfma_f32_16x16x32_bf16 v[60:63], v[132:135], v[188:191], v[60:63]
	v_mfma_f32_16x16x32_bf16 v[56:59], v[140:143], v[188:191], v[56:59]
	v_mfma_f32_16x16x32_bf16 v[44:47], v[132:135], v[196:199], v[44:47]
	v_mfma_f32_16x16x32_bf16 v[40:43], v[140:143], v[196:199], v[40:43]
	v_mfma_f32_16x16x32_bf16 v[28:31], v[132:135], v[204:207], v[28:31]
	v_mfma_f32_16x16x32_bf16 v[24:27], v[140:143], v[204:207], v[24:27]
	v_mfma_f32_16x16x32_bf16 v[12:15], v[132:135], v[214:217], v[12:15]
	v_mfma_f32_16x16x32_bf16 v[8:11], v[140:143], v[214:217], v[8:11]
	v_mfma_f32_16x16x32_bf16 v[52:55], v[144:147], v[184:187], v[52:55]
	v_mfma_f32_16x16x32_bf16 v[48:51], v[168:171], v[184:187], v[48:51]
	v_mfma_f32_16x16x32_bf16 v[36:39], v[144:147], v[192:195], v[36:39]
	v_mfma_f32_16x16x32_bf16 v[32:35], v[168:171], v[192:195], v[32:35]
	v_mfma_f32_16x16x32_bf16 v[20:23], v[144:147], v[200:203], v[20:23]
	v_mfma_f32_16x16x32_bf16 v[16:19], v[168:171], v[200:203], v[16:19]
	v_mfma_f32_16x16x32_bf16 v[4:7], v[144:147], v[208:211], v[4:7]
	v_mfma_f32_16x16x32_bf16 v[0:3], v[168:171], v[208:211], v[0:3]
	v_mfma_f32_16x16x32_bf16 v[52:55], v[164:167], v[188:191], v[52:55]
	v_mfma_f32_16x16x32_bf16 v[48:51], v[180:183], v[188:191], v[48:51]
	v_mfma_f32_16x16x32_bf16 v[36:39], v[164:167], v[196:199], v[36:39]
	v_mfma_f32_16x16x32_bf16 v[32:35], v[180:183], v[196:199], v[32:35]
	v_mfma_f32_16x16x32_bf16 v[20:23], v[164:167], v[204:207], v[20:23]
	v_mfma_f32_16x16x32_bf16 v[16:19], v[180:183], v[204:207], v[16:19]
	v_mfma_f32_16x16x32_bf16 v[4:7], v[164:167], v[214:217], v[4:7]
	v_mfma_f32_16x16x32_bf16 v[0:3], v[180:183], v[214:217], v[0:3]
	s_barrier
	s_add_i32 s61, s61, 2
	s_add_u32 s38, s38, 0x100
	s_addc_u32 s39, s39, 0
	s_add_u32 s59, s59, 0x100
	s_addc_u32 s60, s60, 0
	s_cmp_gt_u32 s61, 13

; #define PG8_STAGE(bufoff, gbase, voff) do { _Pragma("unroll") for (int _i = 0; _i < 2; ++_i) \
;         __builtin_amdgcn_global_load_lds((const unsigned*)((const char*)(gbase) + (voff)[_i]), (PG8_LAS unsigned*)(lds + (bufoff) + ldsw + _i * 8192), 16, 0, 0); } while (0)
; #define PG8_LDA(dst, b, h) do { _Pragma("unroll") for (int m = 0; m < 4; ++m) _Pragma("unroll") for (int k = 0; k < 2; ++k) dst[m][k] = *(const PG8_LAS bf16x8*)(lds + PG8_SA(b, h) + aoff + m * 2048 + k * 1024); } while (0)
; #define PG8_LDB(dst, b, h) do { _Pragma("unroll") for (int n = 0; n < 2; ++n) _Pragma("unroll") for (int k = 0; k < 2; ++k) dst[n][k] = *(const PG8_LAS bf16x8*)(lds + PG8_SB(b, h) + boff + n * 2048 + k * 1024); } while (0)
; #define PG8_MMA(ai, bj, At, Bt) do { __builtin_amdgcn_s_setprio(1); _Pragma("unroll") for (int m = 0; m < 4; ++m) _Pragma("unroll") for (int n = 0; n < 2; ++n) _Pragma("unroll") for (int k = 0; k < 2; ++k) \
;         acc[ai][bj][m][n] = __builtin_amdgcn_mfma_f32_16x16x32_bf16(Bt[n][k], At[m][k], acc[ai][bj][m][n], 0, 0, 0); __builtin_amdgcn_s_setprio(0); } while (0)
; #define PG8_BAR __builtin_amdgcn_s_barrier()
; template <class Epi, class Sched, bool ALIGN_EPI = false, bool SP2 = false>
; __device__ __forceinline__ void gemm_phase(PG8_LAS unsigned char* lds, const Gemm g, const Sched& S, const Epi& E) {
;     ...
;         const bool has_next = S.next(ui + 1, nxt);
;         const char* nA = has_next ? (const char*)g.A + (size_t)nxt.pm * tstep : cA; const char* nB = has_next ? (const char*)g.Bt + (size_t)nxt.pn * tstep : cB;
;         for (int t = 0; t < nt; t += 2) {
;             const bool last = (t == nt - 2);
;             const char* a1 = cA + (size_t)(t + 1) * kstep;
;             const char* a2 = last ? nA : cA + (size_t)(t + 2) * kstep; const char* b2 = last ? nB : cB + (size_t)(t + 2) * kstep;
;             const char* a3 = a2 + kstep; const char* b3 = b2 + kstep;
;             if (last && has_next) S.a_ready(nxt);
;             if constexpr (SP2) {
;             PG8_LDB(B0, 0, 0); PG8_LDB(B1, 0, 1); PG8_SCHED; PG8_LDA(At, 0, 0); PG8_STAGE(PG8_SA(1, 1), a1 + hstep, voffA);
;             PG8_WAIT_V(8); PG8_WAIT_L(0); PG8_BAR; PG8_MMA(0, 0, At, B0); PG8_MMA(0, 1, At, B1); PG8_BAR; PG8_SCHED;
;             PG8_LDA(At, 0, 1); PG8_STAGE(PG8_SB(0, 0), b2, voffB); PG8_STAGE(PG8_SB(0, 1), b2 + hstep, voffB); PG8_STAGE(PG8_SA(0, 0), a2, voffA);
.LBB0_826:
	s_ashr_i32 s39, s38, 31
	v_cmp_lt_i64_e32 vcc, s[40:41], v[156:157]
	s_lshl_b64 s[40:41], s[38:39], 20
	s_add_u32 s40, s9, s40
	s_addc_u32 s41, s22, s41
	s_and_b64 s[42:43], vcc, exec
	s_cselect_b32 s39, s41, s47
	s_cselect_b32 s67, s40, s46
	s_ashr_i32 s37, s36, 31
	s_lshl_b64 s[42:43], s[36:37], 20
	s_add_u32 s42, s23, s42
	s_addc_u32 s43, s52, s43
	s_and_b64 s[50:51], vcc, exec
	s_cselect_b32 s37, s43, s49
	s_cselect_b32 s68, s42, s48
	s_add_u32 s46, s46, 0x80080
	s_addc_u32 s47, s47, 0
	s_add_u32 s69, s48, 0x100
	s_addc_u32 s70, s49, 0
	s_mov_b32 s71, -2
	ds_read_b128 v[128:131], v169
	ds_read_b128 v[132:135], v169 offset:1024
	ds_read_b128 v[136:139], v169 offset:2048
	ds_read_b128 v[140:143], v169 offset:3072
	ds_read_b128 v[160:163], v170
	ds_read_b128 v[172:175], v170 offset:1024
	ds_read_b128 v[176:179], v170 offset:2048
	ds_read_b128 v[180:183], v170 offset:3072
	s_add_u32 s48, s46, 0xfff80080
	s_addc_u32 s49, s47, -1
	s_cmp_eq_u32 s71, 28
	s_cselect_b32 s51, s39, s49
	s_cselect_b32 s50, s67, s48
	s_cselect_b32 s49, s37, s70
	s_cselect_b32 s48, s68, s69
	s_add_i32 m0, s45, 0xc000
	ds_read_b128 v[184:187], v171
	ds_read_b128 v[188:191], v171 offset:1024
	ds_read_b128 v[192:195], v171 offset:2048
	ds_read_b128 v[196:199], v171 offset:3072
	ds_read_b128 v[200:203], v171 offset:4096
	ds_read_b128 v[204:207], v171 offset:5120
	ds_read_b128 v[208:211], v171 offset:6144
	ds_read_b128 v[214:217], v171 offset:7168
	global_load_lds_dwordx4 v152, s[46:47]
	s_add_i32 m0, s45, 0xe000
	s_nop 0
	global_load_lds_dwordx4 v154, s[46:47]
	s_waitcnt vmcnt(8)
	s_waitcnt lgkmcnt(0)
	s_barrier
	s_waitcnt lgkmcnt(0)
	v_mfma_f32_16x16x32_bf16 v[124:127], v[128:131], v[184:187], 0
	v_mfma_f32_16x16x32_bf16 v[120:123], v[136:139], v[184:187], 0
	v_mfma_f32_16x16x32_bf16 v[116:119], v[128:131], v[192:195], 0
	v_mfma_f32_16x16x32_bf16 v[112:115], v[136:139], v[192:195], 0
	v_mfma_f32_16x16x32_bf16 v[108:111], v[128:131], v[200:203], 0
	v_mfma_f32_16x16x32_bf16 v[96:99], v[136:139], v[200:203], 0
	v_mfma_f32_16x16x32_bf16 v[80:83], v[128:131], v[208:211], 0
	v_mfma_f32_16x16x32_bf16 v[72:75], v[136:139], v[208:211], 0
	v_mfma_f32_16x16x32_bf16 v[124:127], v[132:135], v[188:191], v[124:127]
	v_mfma_f32_16x16x32_bf16 v[120:123], v[140:143], v[188:191], v[120:123]
	v_mfma_f32_16x16x32_bf16 v[116:119], v[132:135], v[196:199], v[116:119]
	v_mfma_f32_16x16x32_bf16 v[112:115], v[140:143], v[196:199], v[112:115]
	v_mfma_f32_16x16x32_bf16 v[108:111], v[132:135], v[204:207], v[108:111]
	v_mfma_f32_16x16x32_bf16 v[96:99], v[140:143], v[204:207], v[96:99]
	v_mfma_f32_16x16x32_bf16 v[80:83], v[132:135], v[214:217], v[80:83]
	v_mfma_f32_16x16x32_bf16 v[72:75], v[140:143], v[214:217], v[72:75]
	v_mfma_f32_16x16x32_bf16 v[104:107], v[160:163], v[184:187], 0
	v_mfma_f32_16x16x32_bf16 v[100:103], v[176:179], v[184:187], 0
	v_mfma_f32_16x16x32_bf16 v[92:95], v[160:163], v[192:195], 0
	v_mfma_f32_16x16x32_bf16 v[88:91], v[176:179], v[192:195], 0
	v_mfma_f32_16x16x32_bf16 v[84:87], v[160:163], v[200:203], 0
	v_mfma_f32_16x16x32_bf16 v[76:79], v[176:179], v[200:203], 0
	v_mfma_f32_16x16x32_bf16 v[68:71], v[160:163], v[208:211], 0
	v_mfma_f32_16x16x32_bf16 v[64:67], v[176:179], v[208:211], 0
	v_mfma_f32_16x16x32_bf16 v[104:107], v[172:175], v[188:191], v[104:107]
	v_mfma_f32_16x16x32_bf16 v[100:103], v[180:183], v[188:191], v[100:103]
	v_mfma_f32_16x16x32_bf16 v[92:95], v[172:175], v[196:199], v[92:95]
	v_mfma_f32_16x16x32_bf16 v[88:91], v[180:183], v[196:199], v[88:91]
	v_mfma_f32_16x16x32_bf16 v[84:87], v[172:175], v[204:207], v[84:87]
	v_mfma_f32_16x16x32_bf16 v[76:79], v[180:183], v[204:207], v[76:79]
	v_mfma_f32_16x16x32_bf16 v[68:71], v[172:175], v[214:217], v[68:71]
	v_mfma_f32_16x16x32_bf16 v[64:67], v[180:183], v[214:217], v[64:67]
	s_barrier
	s_add_i32 s72, s64, s53
	s_mov_b32 m0, s72
	ds_read_b128 v[184:187], v171 offset:16384
	ds_read_b128 v[188:191], v171 offset:17408
	ds_read_b128 v[192:195], v171 offset:18432
	ds_read_b128 v[196:199], v171 offset:19456
	ds_read_b128 v[200:203], v171 offset:20480
	ds_read_b128 v[204:207], v171 offset:21504
	ds_read_b128 v[208:211], v171 offset:22528
	ds_read_b128 v[214:217], v171 offset:23552
	global_load_lds_dwordx4 v146, s[48:49]
	s_add_i32 m0, s72, 0x2000
	s_add_u32 s72, s48, 0x80000
	s_addc_u32 s73, s49, 0
	s_add_i32 s74, s65, s53
	global_load_lds_dwordx4 v150, s[48:49]
	s_mov_b32 m0, s74
	s_nop 0
	global_load_lds_dwordx4 v146, s[72:73]
	s_add_i32 m0, s74, 0x2000
	s_nop 0
	global_load_lds_dwordx4 v150, s[72:73]
	s_mov_b32 m0, s45
	s_nop 0
	global_load_lds_dwordx4 v144, s[50:51]
	s_mov_b32 m0, s54
	s_nop 0
	global_load_lds_dwordx4 v148, s[50:51]
	s_waitcnt vmcnt(8)
	s_waitcnt lgkmcnt(0)
	s_barrier
; #define PG8_STAGE(bufoff, gbase, voff) do { _Pragma("unroll") for (int _i = 0; _i < 2; ++_i) \
;         __builtin_amdgcn_global_load_lds((const unsigned*)((const char*)(gbase) + (voff)[_i]), (PG8_LAS unsigned*)(lds + (bufoff) + ldsw + _i * 8192), 16, 0, 0); } while (0)
; #define PG8_LDA(dst, b, h) do { _Pragma("unroll") for (int m = 0; m < 4; ++m) _Pragma("unroll") for (int k = 0; k < 2; ++k) dst[m][k] = *(const PG8_LAS bf16x8*)(lds + PG8_SA(b, h) + aoff + m * 2048 + k * 1024); } while (0)
; #define PG8_LDB(dst, b, h) do { _Pragma("unroll") for (int n = 0; n < 2; ++n) _Pragma("unroll") for (int k = 0; k < 2; ++k) dst[n][k] = *(const PG8_LAS bf16x8*)(lds + PG8_SB(b, h) + boff + n * 2048 + k * 1024); } while (0)
; #define PG8_MMA(ai, bj, At, Bt) do { __builtin_amdgcn_s_setprio(1); _Pragma("unroll") for (int m = 0; m < 4; ++m) _Pragma("unroll") for (int n = 0; n < 2; ++n) _Pragma("unroll") for (int k = 0; k < 2; ++k) \
;         acc[ai][bj][m][n] = __builtin_amdgcn_mfma_f32_16x16x32_bf16(Bt[n][k], At[m][k], acc[ai][bj][m][n], 0, 0, 0); __builtin_amdgcn_s_setprio(0); } while (0)
; #define PG8_WAIT_V(n) asm volatile("s_waitcnt vmcnt(" #n ")" ::: "memory")
; #define PG8_WAIT_L(n) asm volatile("s_waitcnt lgkmcnt(" #n ")" ::: "memory")
; #define PG8_BAR __builtin_amdgcn_s_barrier()
; #define PG8_SCHED __builtin_amdgcn_sched_barrier(0)
; template <class Epi, class Sched, bool ALIGN_EPI = false, bool SP2 = false>
; __device__ __forceinline__ void gemm_phase(PG8_LAS unsigned char* lds, const Gemm g, const Sched& S, const Epi& E) {
;     ...
;             PG8_WAIT_V(8); PG8_WAIT_L(0); PG8_BAR; PG8_MMA(1, 0, At, B0); PG8_MMA(1, 1, At, B1); PG8_BAR; PG8_SCHED;
;             PG8_LDB(B0, 1, 0); PG8_LDB(B1, 1, 1); PG8_SCHED; PG8_LDA(At, 1, 0); PG8_STAGE(PG8_SA(0, 1), a2 + hstep, voffA);
;             PG8_WAIT_V(8); PG8_WAIT_L(0); PG8_BAR; PG8_MMA(0, 0, At, B0); PG8_MMA(0, 1, At, B1); PG8_BAR; PG8_SCHED;
	s_waitcnt lgkmcnt(0)
	v_mfma_f32_16x16x32_bf16 v[60:63], v[128:131], v[184:187], 0
	v_mfma_f32_16x16x32_bf16 v[56:59], v[136:139], v[184:187], 0
	v_mfma_f32_16x16x32_bf16 v[52:55], v[128:131], v[192:195], 0
	v_mfma_f32_16x16x32_bf16 v[48:51], v[136:139], v[192:195], 0
	v_mfma_f32_16x16x32_bf16 v[44:47], v[128:131], v[200:203], 0
	v_mfma_f32_16x16x32_bf16 v[32:35], v[136:139], v[200:203], 0
	v_mfma_f32_16x16x32_bf16 v[20:23], v[128:131], v[208:211], 0
	v_mfma_f32_16x16x32_bf16 v[8:11], v[136:139], v[208:211], 0
	v_mfma_f32_16x16x32_bf16 v[60:63], v[132:135], v[188:191], v[60:63]
	v_mfma_f32_16x16x32_bf16 v[56:59], v[140:143], v[188:191], v[56:59]
	v_mfma_f32_16x16x32_bf16 v[52:55], v[132:135], v[196:199], v[52:55]
	v_mfma_f32_16x16x32_bf16 v[48:51], v[140:143], v[196:199], v[48:51]
	v_mfma_f32_16x16x32_bf16 v[44:47], v[132:135], v[204:207], v[44:47]
	v_mfma_f32_16x16x32_bf16 v[32:35], v[140:143], v[204:207], v[32:35]
	v_mfma_f32_16x16x32_bf16 v[20:23], v[132:135], v[214:217], v[20:23]
	v_mfma_f32_16x16x32_bf16 v[8:11], v[140:143], v[214:217], v[8:11]
	v_mfma_f32_16x16x32_bf16 v[40:43], v[160:163], v[184:187], 0
	v_mfma_f32_16x16x32_bf16 v[36:39], v[176:179], v[184:187], 0
	v_mfma_f32_16x16x32_bf16 v[28:31], v[160:163], v[192:195], 0
	v_mfma_f32_16x16x32_bf16 v[24:27], v[176:179], v[192:195], 0
	v_mfma_f32_16x16x32_bf16 v[16:19], v[160:163], v[200:203], 0
	v_mfma_f32_16x16x32_bf16 v[12:15], v[176:179], v[200:203], 0
	v_mfma_f32_16x16x32_bf16 v[4:7], v[160:163], v[208:211], 0
	v_mfma_f32_16x16x32_bf16 v[0:3], v[176:179], v[208:211], 0
	v_mfma_f32_16x16x32_bf16 v[40:43], v[172:175], v[188:191], v[40:43]
	v_mfma_f32_16x16x32_bf16 v[36:39], v[180:183], v[188:191], v[36:39]
	v_mfma_f32_16x16x32_bf16 v[28:31], v[172:175], v[196:199], v[28:31]
	v_mfma_f32_16x16x32_bf16 v[24:27], v[180:183], v[196:199], v[24:27]
	v_mfma_f32_16x16x32_bf16 v[16:19], v[172:175], v[204:207], v[16:19]
	v_mfma_f32_16x16x32_bf16 v[12:15], v[180:183], v[204:207], v[12:15]
	v_mfma_f32_16x16x32_bf16 v[4:7], v[172:175], v[214:217], v[4:7]
	v_mfma_f32_16x16x32_bf16 v[0:3], v[180:183], v[214:217], v[0:3]
	s_barrier
	s_add_i32 s72, 0, 0x18000
	s_add_i32 s73, 0, 0x1c000
	v_add_u32_e32 v140, s72, v167
	v_add_u32_e32 v180, s73, v167
	ds_read_b128 v[128:131], v140
	ds_read_b128 v[132:135], v140 offset:1024
	ds_read_b128 v[136:139], v140 offset:2048
	ds_read_b128 v[140:143], v140 offset:3072
	ds_read_b128 v[160:163], v180
	ds_read_b128 v[172:175], v180 offset:1024
	ds_read_b128 v[176:179], v180 offset:2048
	ds_read_b128 v[180:183], v180 offset:3072
	s_add_u32 s84, s50, 0x80
	s_addc_u32 s85, s51, 0
	s_add_u32 s50, s50, 0x80000
	s_addc_u32 s51, s51, 0
	s_mov_b32 m0, s55
	ds_read_b128 v[184:187], v171 offset:32768
	ds_read_b128 v[188:191], v171 offset:33792
	ds_read_b128 v[192:195], v171 offset:34816
	ds_read_b128 v[196:199], v171 offset:35840
	ds_read_b128 v[200:203], v171 offset:36864
	ds_read_b128 v[204:207], v171 offset:37888
	ds_read_b128 v[208:211], v171 offset:38912
	ds_read_b128 v[214:217], v171 offset:39936
	global_load_lds_dwordx4 v144, s[50:51]
	s_mov_b32 m0, s56
	s_nop 0
	global_load_lds_dwordx4 v148, s[50:51]
	s_waitcnt vmcnt(8)
	s_waitcnt lgkmcnt(0)
	s_barrier
	s_waitcnt lgkmcnt(0)
	v_mfma_f32_16x16x32_bf16 v[124:127], v[128:131], v[184:187], v[124:127]
	v_mfma_f32_16x16x32_bf16 v[120:123], v[136:139], v[184:187], v[120:123]
	v_mfma_f32_16x16x32_bf16 v[116:119], v[128:131], v[192:195], v[116:119]
	v_mfma_f32_16x16x32_bf16 v[112:115], v[136:139], v[192:195], v[112:115]
	v_mfma_f32_16x16x32_bf16 v[108:111], v[128:131], v[200:203], v[108:111]
	v_mfma_f32_16x16x32_bf16 v[96:99], v[136:139], v[200:203], v[96:99]
	v_mfma_f32_16x16x32_bf16 v[80:83], v[128:131], v[208:211], v[80:83]
	v_mfma_f32_16x16x32_bf16 v[72:75], v[136:139], v[208:211], v[72:75]
	v_mfma_f32_16x16x32_bf16 v[124:127], v[132:135], v[188:191], v[124:127]
	v_mfma_f32_16x16x32_bf16 v[120:123], v[140:143], v[188:191], v[120:123]
	v_mfma_f32_16x16x32_bf16 v[116:119], v[132:135], v[196:199], v[116:119]
	v_mfma_f32_16x16x32_bf16 v[112:115], v[140:143], v[196:199], v[112:115]
	v_mfma_f32_16x16x32_bf16 v[108:111], v[132:135], v[204:207], v[108:111]
	v_mfma_f32_16x16x32_bf16 v[96:99], v[140:143], v[204:207], v[96:99]
	v_mfma_f32_16x16x32_bf16 v[80:83], v[132:135], v[214:217], v[80:83]
	v_mfma_f32_16x16x32_bf16 v[72:75], v[140:143], v[214:217], v[72:75]
	v_mfma_f32_16x16x32_bf16 v[104:107], v[160:163], v[184:187], v[104:107]
	v_mfma_f32_16x16x32_bf16 v[100:103], v[176:179], v[184:187], v[100:103]
	v_mfma_f32_16x16x32_bf16 v[92:95], v[160:163], v[192:195], v[92:95]
	v_mfma_f32_16x16x32_bf16 v[88:91], v[176:179], v[192:195], v[88:91]
	v_mfma_f32_16x16x32_bf16 v[84:87], v[160:163], v[200:203], v[84:87]
	v_mfma_f32_16x16x32_bf16 v[76:79], v[176:179], v[200:203], v[76:79]
	v_mfma_f32_16x16x32_bf16 v[68:71], v[160:163], v[208:211], v[68:71]
	v_mfma_f32_16x16x32_bf16 v[64:67], v[176:179], v[208:211], v[64:67]
	v_mfma_f32_16x16x32_bf16 v[104:107], v[172:175], v[188:191], v[104:107]
	v_mfma_f32_16x16x32_bf16 v[100:103], v[180:183], v[188:191], v[100:103]
	v_mfma_f32_16x16x32_bf16 v[92:95], v[172:175], v[196:199], v[92:95]
	v_mfma_f32_16x16x32_bf16 v[88:91], v[180:183], v[196:199], v[88:91]
	v_mfma_f32_16x16x32_bf16 v[84:87], v[172:175], v[204:207], v[84:87]
	v_mfma_f32_16x16x32_bf16 v[76:79], v[180:183], v[204:207], v[76:79]
	v_mfma_f32_16x16x32_bf16 v[68:71], v[172:175], v[214:217], v[68:71]
	v_mfma_f32_16x16x32_bf16 v[64:67], v[180:183], v[214:217], v[64:67]
	s_barrier
; #define PG8_STAGE(bufoff, gbase, voff) do { _Pragma("unroll") for (int _i = 0; _i < 2; ++_i) \
;         __builtin_amdgcn_global_load_lds((const unsigned*)((const char*)(gbase) + (voff)[_i]), (PG8_LAS unsigned*)(lds + (bufoff) + ldsw + _i * 8192), 16, 0, 0); } while (0)
; #define PG8_LDA(dst, b, h) do { _Pragma("unroll") for (int m = 0; m < 4; ++m) _Pragma("unroll") for (int k = 0; k < 2; ++k) dst[m][k] = *(const PG8_LAS bf16x8*)(lds + PG8_SA(b, h) + aoff + m * 2048 + k * 1024); } while (0)
; #define PG8_MMA(ai, bj, At, Bt) do { __builtin_amdgcn_s_setprio(1); _Pragma("unroll") for (int m = 0; m < 4; ++m) _Pragma("unroll") for (int n = 0; n < 2; ++n) _Pragma("unroll") for (int k = 0; k < 2; ++k) \
;         acc[ai][bj][m][n] = __builtin_amdgcn_mfma_f32_16x16x32_bf16(Bt[n][k], At[m][k], acc[ai][bj][m][n], 0, 0, 0); __builtin_amdgcn_s_setprio(0); } while (0)
; #define PG8_WAIT_V(n) asm volatile("s_waitcnt vmcnt(" #n ")" ::: "memory")
; #define PG8_WAIT_L(n) asm volatile("s_waitcnt lgkmcnt(" #n ")" ::: "memory")
; #define PG8_BAR __builtin_amdgcn_s_barrier()
; #define PG8_SCHED __builtin_amdgcn_sched_barrier(0)
; template <class Epi, class Sched, bool ALIGN_EPI = false, bool SP2 = false>
; __device__ __forceinline__ void gemm_phase(PG8_LAS unsigned char* lds, const Gemm g, const Sched& S, const Epi& E) {
;     ...
;             PG8_LDA(At, 1, 1); PG8_STAGE(PG8_SB(1, 0), b3, voffB); PG8_STAGE(PG8_SB(1, 1), b3 + hstep, voffB); PG8_STAGE(PG8_SA(1, 0), a3, voffA);
;             PG8_WAIT_V(8); PG8_WAIT_L(0); PG8_BAR; PG8_MMA(1, 0, At, B0); PG8_MMA(1, 1, At, B1); PG8_BAR; PG8_SCHED;
	s_add_i32 s50, s72, s53
	s_add_u32 s86, s48, 0x80
	s_addc_u32 s87, s49, 0
	s_mov_b32 m0, s50
	ds_read_b128 v[184:187], v171 offset:49152
	ds_read_b128 v[188:191], v171 offset:50176
	ds_read_b128 v[192:195], v171 offset:51200
	ds_read_b128 v[196:199], v171 offset:52224
	ds_read_b128 v[200:203], v171 offset:53248
	ds_read_b128 v[204:207], v171 offset:54272
	ds_read_b128 v[208:211], v171 offset:55296
	ds_read_b128 v[214:217], v171 offset:56320
	global_load_lds_dwordx4 v146, s[86:87]
	s_add_i32 m0, s50, 0x2000
	s_add_u32 s48, s48, 0x80080
	s_addc_u32 s49, s49, 0
	s_add_i32 s50, s73, s53
	global_load_lds_dwordx4 v150, s[86:87]
	s_mov_b32 m0, s50
	s_nop 0
	global_load_lds_dwordx4 v146, s[48:49]
	s_add_i32 m0, s50, 0x2000
	s_nop 0
	global_load_lds_dwordx4 v150, s[48:49]
	s_mov_b32 m0, s60
	s_nop 0
	global_load_lds_dwordx4 v144, s[84:85]
	s_mov_b32 m0, s61
	s_nop 0
	global_load_lds_dwordx4 v148, s[84:85]
	s_waitcnt vmcnt(8)
	s_waitcnt lgkmcnt(0)
	s_barrier
	s_waitcnt lgkmcnt(0)
	v_mfma_f32_16x16x32_bf16 v[60:63], v[128:131], v[184:187], v[60:63]
	v_mfma_f32_16x16x32_bf16 v[56:59], v[136:139], v[184:187], v[56:59]
	v_mfma_f32_16x16x32_bf16 v[52:55], v[128:131], v[192:195], v[52:55]
	v_mfma_f32_16x16x32_bf16 v[48:51], v[136:139], v[192:195], v[48:51]
	v_mfma_f32_16x16x32_bf16 v[44:47], v[128:131], v[200:203], v[44:47]
	v_mfma_f32_16x16x32_bf16 v[32:35], v[136:139], v[200:203], v[32:35]
	v_mfma_f32_16x16x32_bf16 v[20:23], v[128:131], v[208:211], v[20:23]
	v_mfma_f32_16x16x32_bf16 v[8:11], v[136:139], v[208:211], v[8:11]
	v_mfma_f32_16x16x32_bf16 v[60:63], v[132:135], v[188:191], v[60:63]
	v_mfma_f32_16x16x32_bf16 v[56:59], v[140:143], v[188:191], v[56:59]
	v_mfma_f32_16x16x32_bf16 v[52:55], v[132:135], v[196:199], v[52:55]
	v_mfma_f32_16x16x32_bf16 v[48:51], v[140:143], v[196:199], v[48:51]
	v_mfma_f32_16x16x32_bf16 v[44:47], v[132:135], v[204:207], v[44:47]
	v_mfma_f32_16x16x32_bf16 v[32:35], v[140:143], v[204:207], v[32:35]
	v_mfma_f32_16x16x32_bf16 v[20:23], v[132:135], v[214:217], v[20:23]
	v_mfma_f32_16x16x32_bf16 v[8:11], v[140:143], v[214:217], v[8:11]
	v_mfma_f32_16x16x32_bf16 v[40:43], v[160:163], v[184:187], v[40:43]
	v_mfma_f32_16x16x32_bf16 v[36:39], v[176:179], v[184:187], v[36:39]
	v_mfma_f32_16x16x32_bf16 v[28:31], v[160:163], v[192:195], v[28:31]
	v_mfma_f32_16x16x32_bf16 v[24:27], v[176:179], v[192:195], v[24:27]
	v_mfma_f32_16x16x32_bf16 v[16:19], v[160:163], v[200:203], v[16:19]
	v_mfma_f32_16x16x32_bf16 v[12:15], v[176:179], v[200:203], v[12:15]
	v_mfma_f32_16x16x32_bf16 v[4:7], v[160:163], v[208:211], v[4:7]
	v_mfma_f32_16x16x32_bf16 v[0:3], v[176:179], v[208:211], v[0:3]
	v_mfma_f32_16x16x32_bf16 v[40:43], v[172:175], v[188:191], v[40:43]
	v_mfma_f32_16x16x32_bf16 v[36:39], v[180:183], v[188:191], v[36:39]
	v_mfma_f32_16x16x32_bf16 v[28:31], v[172:175], v[196:199], v[28:31]
	v_mfma_f32_16x16x32_bf16 v[24:27], v[180:183], v[196:199], v[24:27]
	v_mfma_f32_16x16x32_bf16 v[16:19], v[172:175], v[204:207], v[16:19]
	v_mfma_f32_16x16x32_bf16 v[12:15], v[180:183], v[204:207], v[12:15]
	v_mfma_f32_16x16x32_bf16 v[4:7], v[172:175], v[214:217], v[4:7]
	v_mfma_f32_16x16x32_bf16 v[0:3], v[180:183], v[214:217], v[0:3]
	s_barrier
	s_add_i32 s71, s71, 2
	s_add_u32 s46, s46, 0x100
	s_addc_u32 s47, s47, 0
	s_add_u32 s69, s69, 0x100
	s_addc_u32 s70, s70, 0
	s_cmp_gt_u32 s71, 29

; #define PG8_STAGE(bufoff, gbase, voff) do { _Pragma("unroll") for (int _i = 0; _i < 2; ++_i) \
;         __builtin_amdgcn_global_load_lds((const unsigned*)((const char*)(gbase) + (voff)[_i]), (PG8_LAS unsigned*)(lds + (bufoff) + ldsw + _i * 8192), 16, 0, 0); } while (0)
; #define PG8_LDA(dst, b, h) do { _Pragma("unroll") for (int m = 0; m < 4; ++m) _Pragma("unroll") for (int k = 0; k < 2; ++k) dst[m][k] = *(const PG8_LAS bf16x8*)(lds + PG8_SA(b, h) + aoff + m * 2048 + k * 1024); } while (0)
; #define PG8_LDB(dst, b, h) do { _Pragma("unroll") for (int n = 0; n < 2; ++n) _Pragma("unroll") for (int k = 0; k < 2; ++k) dst[n][k] = *(const PG8_LAS bf16x8*)(lds + PG8_SB(b, h) + boff + n * 2048 + k * 1024); } while (0)
; #define PG8_MMA(ai, bj, At, Bt) do { __builtin_amdgcn_s_setprio(1); _Pragma("unroll") for (int m = 0; m < 4; ++m) _Pragma("unroll") for (int n = 0; n < 2; ++n) _Pragma("unroll") for (int k = 0; k < 2; ++k) \
;         acc[ai][bj][m][n] = __builtin_amdgcn_mfma_f32_16x16x32_bf16(Bt[n][k], At[m][k], acc[ai][bj][m][n], 0, 0, 0); __builtin_amdgcn_s_setprio(0); } while (0)
; #define PG8_BAR __builtin_amdgcn_s_barrier()
; template <class Epi, class Sched, bool ALIGN_EPI = false, bool SP2 = false>
; __device__ __forceinline__ void gemm_phase(PG8_LAS unsigned char* lds, const Gemm g, const Sched& S, const Epi& E) {
;     ...
;         const bool has_next = S.next(ui + 1, nxt);
;         const char* nA = has_next ? (const char*)g.A + (size_t)nxt.pm * tstep : cA; const char* nB = has_next ? (const char*)g.Bt + (size_t)nxt.pn * tstep : cB;
;         for (int t = 0; t < nt; t += 2) {
;             const bool last = (t == nt - 2);
;             const char* a1 = cA + (size_t)(t + 1) * kstep;
;             const char* a2 = last ? nA : cA + (size_t)(t + 2) * kstep; const char* b2 = last ? nB : cB + (size_t)(t + 2) * kstep;
;             const char* a3 = a2 + kstep; const char* b3 = b2 + kstep;
;             if (last && has_next) S.a_ready(nxt);
;             if constexpr (SP2) {
;             PG8_LDB(B0, 0, 0); PG8_LDB(B1, 0, 1); PG8_SCHED; PG8_LDA(At, 0, 0); PG8_STAGE(PG8_SA(1, 1), a1 + hstep, voffA);
;             PG8_WAIT_V(8); PG8_WAIT_L(0); PG8_BAR; PG8_MMA(0, 0, At, B0); PG8_MMA(0, 1, At, B1); PG8_BAR; PG8_SCHED;
;             PG8_LDA(At, 0, 1); PG8_STAGE(PG8_SB(0, 0), b2, voffB); PG8_STAGE(PG8_SB(0, 1), b2 + hstep, voffB); PG8_STAGE(PG8_SA(0, 0), a2, voffA);
.LBB0_944:
	s_ashr_i32 s23, s22, 31
	v_cmp_lt_i64_e32 vcc, s[24:25], v[140:141]
	s_lshl_b64 s[24:25], s[22:23], 20
	s_add_u32 s24, s38, s24
	s_addc_u32 s25, s39, s25
	s_and_b64 s[26:27], vcc, exec
	s_cselect_b32 s23, s25, s31
	s_cselect_b32 s57, s24, s30
	s_ashr_i32 s15, s14, 31
	s_lshl_b64 s[26:27], s[14:15], 20
	s_add_u32 s26, s40, s26
	s_addc_u32 s27, s41, s27
	s_and_b64 s[36:37], vcc, exec
	s_cselect_b32 s15, s27, s35
	s_cselect_b32 s58, s26, s34
	s_add_u32 s30, s30, 0x80080
	s_addc_u32 s31, s31, 0
	s_add_u32 s59, s34, 0x100
	s_addc_u32 s60, s35, 0
	s_mov_b32 s61, -2
	ds_read_b128 v[152:155], v149
	ds_read_b128 v[156:159], v149 offset:1024
	ds_read_b128 v[160:163], v149 offset:2048
	ds_read_b128 v[164:167], v149 offset:3072
	ds_read_b128 v[168:171], v150
	ds_read_b128 v[172:175], v150 offset:1024
	ds_read_b128 v[176:179], v150 offset:2048
	ds_read_b128 v[180:183], v150 offset:3072
	s_add_u32 s34, s30, 0xfff80080
	s_addc_u32 s35, s31, -1
	s_cmp_eq_u32 s61, 28
	s_cselect_b32 s37, s23, s35
	s_cselect_b32 s36, s57, s34
	s_cselect_b32 s35, s15, s60
	s_cselect_b32 s34, s58, s59
	s_add_i32 m0, s29, 0xc000
	ds_read_b128 v[184:187], v151
	ds_read_b128 v[188:191], v151 offset:1024
	ds_read_b128 v[192:195], v151 offset:2048
	ds_read_b128 v[196:199], v151 offset:3072
	ds_read_b128 v[200:203], v151 offset:4096
	ds_read_b128 v[204:207], v151 offset:5120
	ds_read_b128 v[208:211], v151 offset:6144
	ds_read_b128 v[212:215], v151 offset:7168
	global_load_lds_dwordx4 v136, s[30:31]
	s_add_i32 m0, s29, 0xe000
	s_nop 0
	global_load_lds_dwordx4 v138, s[30:31]
	s_waitcnt vmcnt(8)
	s_waitcnt lgkmcnt(0)
	s_barrier
	s_waitcnt lgkmcnt(0)
	v_mfma_f32_16x16x32_bf16 v[124:127], v[152:155], v[184:187], 0
	v_mfma_f32_16x16x32_bf16 v[120:123], v[160:163], v[184:187], 0
	v_mfma_f32_16x16x32_bf16 v[108:111], v[152:155], v[192:195], 0
	v_mfma_f32_16x16x32_bf16 v[104:107], v[160:163], v[192:195], 0
	v_mfma_f32_16x16x32_bf16 v[92:95], v[152:155], v[200:203], 0
	v_mfma_f32_16x16x32_bf16 v[88:91], v[160:163], v[200:203], 0
	v_mfma_f32_16x16x32_bf16 v[76:79], v[152:155], v[208:211], 0
	v_mfma_f32_16x16x32_bf16 v[72:75], v[160:163], v[208:211], 0
	v_mfma_f32_16x16x32_bf16 v[124:127], v[156:159], v[188:191], v[124:127]
	v_mfma_f32_16x16x32_bf16 v[120:123], v[164:167], v[188:191], v[120:123]
	v_mfma_f32_16x16x32_bf16 v[108:111], v[156:159], v[196:199], v[108:111]
	v_mfma_f32_16x16x32_bf16 v[104:107], v[164:167], v[196:199], v[104:107]
	v_mfma_f32_16x16x32_bf16 v[92:95], v[156:159], v[204:207], v[92:95]
	v_mfma_f32_16x16x32_bf16 v[88:91], v[164:167], v[204:207], v[88:91]
	v_mfma_f32_16x16x32_bf16 v[76:79], v[156:159], v[212:215], v[76:79]
	v_mfma_f32_16x16x32_bf16 v[72:75], v[164:167], v[212:215], v[72:75]
	v_mfma_f32_16x16x32_bf16 v[116:119], v[168:171], v[184:187], 0
	v_mfma_f32_16x16x32_bf16 v[112:115], v[176:179], v[184:187], 0
	v_mfma_f32_16x16x32_bf16 v[100:103], v[168:171], v[192:195], 0
	v_mfma_f32_16x16x32_bf16 v[96:99], v[176:179], v[192:195], 0
	v_mfma_f32_16x16x32_bf16 v[84:87], v[168:171], v[200:203], 0
	v_mfma_f32_16x16x32_bf16 v[80:83], v[176:179], v[200:203], 0
	v_mfma_f32_16x16x32_bf16 v[68:71], v[168:171], v[208:211], 0
	v_mfma_f32_16x16x32_bf16 v[64:67], v[176:179], v[208:211], 0
	v_mfma_f32_16x16x32_bf16 v[116:119], v[172:175], v[188:191], v[116:119]
	v_mfma_f32_16x16x32_bf16 v[112:115], v[180:183], v[188:191], v[112:115]
	v_mfma_f32_16x16x32_bf16 v[100:103], v[172:175], v[196:199], v[100:103]
	v_mfma_f32_16x16x32_bf16 v[96:99], v[180:183], v[196:199], v[96:99]
	v_mfma_f32_16x16x32_bf16 v[84:87], v[172:175], v[204:207], v[84:87]
	v_mfma_f32_16x16x32_bf16 v[80:83], v[180:183], v[204:207], v[80:83]
	v_mfma_f32_16x16x32_bf16 v[68:71], v[172:175], v[212:215], v[68:71]
	v_mfma_f32_16x16x32_bf16 v[64:67], v[180:183], v[212:215], v[64:67]
	s_barrier
	s_add_i32 s62, s53, s42
	s_mov_b32 m0, s62
	ds_read_b128 v[184:187], v151 offset:16384
	ds_read_b128 v[188:191], v151 offset:17408
	ds_read_b128 v[192:195], v151 offset:18432
	ds_read_b128 v[196:199], v151 offset:19456
	ds_read_b128 v[200:203], v151 offset:20480
	ds_read_b128 v[204:207], v151 offset:21504
	ds_read_b128 v[208:211], v151 offset:22528
	ds_read_b128 v[212:215], v151 offset:23552
	global_load_lds_dwordx4 v132, s[34:35]
	s_add_i32 m0, s62, 0x2000
	s_add_u32 s62, s34, 0x80000
	s_addc_u32 s63, s35, 0
	s_add_i32 s64, s54, s42
	global_load_lds_dwordx4 v128, s[34:35]
	s_mov_b32 m0, s64
	s_nop 0
	global_load_lds_dwordx4 v132, s[62:63]
	s_add_i32 m0, s64, 0x2000
	s_nop 0
	global_load_lds_dwordx4 v128, s[62:63]
	s_mov_b32 m0, s29
	s_nop 0
	global_load_lds_dwordx4 v134, s[36:37]
	s_mov_b32 m0, s45
	s_nop 0
	global_load_lds_dwordx4 v130, s[36:37]
	s_waitcnt vmcnt(8)
	s_waitcnt lgkmcnt(0)
	s_barrier
; #define PG8_STAGE(bufoff, gbase, voff) do { _Pragma("unroll") for (int _i = 0; _i < 2; ++_i) \
;         __builtin_amdgcn_global_load_lds((const unsigned*)((const char*)(gbase) + (voff)[_i]), (PG8_LAS unsigned*)(lds + (bufoff) + ldsw + _i * 8192), 16, 0, 0); } while (0)
; #define PG8_LDA(dst, b, h) do { _Pragma("unroll") for (int m = 0; m < 4; ++m) _Pragma("unroll") for (int k = 0; k < 2; ++k) dst[m][k] = *(const PG8_LAS bf16x8*)(lds + PG8_SA(b, h) + aoff + m * 2048 + k * 1024); } while (0)
; #define PG8_LDB(dst, b, h) do { _Pragma("unroll") for (int n = 0; n < 2; ++n) _Pragma("unroll") for (int k = 0; k < 2; ++k) dst[n][k] = *(const PG8_LAS bf16x8*)(lds + PG8_SB(b, h) + boff + n * 2048 + k * 1024); } while (0)
; #define PG8_MMA(ai, bj, At, Bt) do { __builtin_amdgcn_s_setprio(1); _Pragma("unroll") for (int m = 0; m < 4; ++m) _Pragma("unroll") for (int n = 0; n < 2; ++n) _Pragma("unroll") for (int k = 0; k < 2; ++k) \
;         acc[ai][bj][m][n] = __builtin_amdgcn_mfma_f32_16x16x32_bf16(Bt[n][k], At[m][k], acc[ai][bj][m][n], 0, 0, 0); __builtin_amdgcn_s_setprio(0); } while (0)
; #define PG8_WAIT_V(n) asm volatile("s_waitcnt vmcnt(" #n ")" ::: "memory")
; #define PG8_WAIT_L(n) asm volatile("s_waitcnt lgkmcnt(" #n ")" ::: "memory")
; #define PG8_BAR __builtin_amdgcn_s_barrier()
; #define PG8_SCHED __builtin_amdgcn_sched_barrier(0)
; template <class Epi, class Sched, bool ALIGN_EPI = false, bool SP2 = false>
; __device__ __forceinline__ void gemm_phase(PG8_LAS unsigned char* lds, const Gemm g, const Sched& S, const Epi& E) {
;     ...
;             PG8_WAIT_V(8); PG8_WAIT_L(0); PG8_BAR; PG8_MMA(1, 0, At, B0); PG8_MMA(1, 1, At, B1); PG8_BAR; PG8_SCHED;
;             PG8_LDB(B0, 1, 0); PG8_LDB(B1, 1, 1); PG8_SCHED; PG8_LDA(At, 1, 0); PG8_STAGE(PG8_SA(0, 1), a2 + hstep, voffA);
;             PG8_WAIT_V(8); PG8_WAIT_L(0); PG8_BAR; PG8_MMA(0, 0, At, B0); PG8_MMA(0, 1, At, B1); PG8_BAR; PG8_SCHED;
	s_waitcnt lgkmcnt(0)
	v_mfma_f32_16x16x32_bf16 v[60:63], v[152:155], v[184:187], 0
	v_mfma_f32_16x16x32_bf16 v[56:59], v[160:163], v[184:187], 0
	v_mfma_f32_16x16x32_bf16 v[44:47], v[152:155], v[192:195], 0
	v_mfma_f32_16x16x32_bf16 v[40:43], v[160:163], v[192:195], 0
	v_mfma_f32_16x16x32_bf16 v[28:31], v[152:155], v[200:203], 0
	v_mfma_f32_16x16x32_bf16 v[24:27], v[160:163], v[200:203], 0
	v_mfma_f32_16x16x32_bf16 v[12:15], v[152:155], v[208:211], 0
	v_mfma_f32_16x16x32_bf16 v[8:11], v[160:163], v[208:211], 0
	v_mfma_f32_16x16x32_bf16 v[60:63], v[156:159], v[188:191], v[60:63]
	v_mfma_f32_16x16x32_bf16 v[56:59], v[164:167], v[188:191], v[56:59]
	v_mfma_f32_16x16x32_bf16 v[44:47], v[156:159], v[196:199], v[44:47]
	v_mfma_f32_16x16x32_bf16 v[40:43], v[164:167], v[196:199], v[40:43]
	v_mfma_f32_16x16x32_bf16 v[28:31], v[156:159], v[204:207], v[28:31]
	v_mfma_f32_16x16x32_bf16 v[24:27], v[164:167], v[204:207], v[24:27]
	v_mfma_f32_16x16x32_bf16 v[12:15], v[156:159], v[212:215], v[12:15]
	v_mfma_f32_16x16x32_bf16 v[8:11], v[164:167], v[212:215], v[8:11]
	v_mfma_f32_16x16x32_bf16 v[52:55], v[168:171], v[184:187], 0
	v_mfma_f32_16x16x32_bf16 v[48:51], v[176:179], v[184:187], 0
	v_mfma_f32_16x16x32_bf16 v[36:39], v[168:171], v[192:195], 0
	v_mfma_f32_16x16x32_bf16 v[32:35], v[176:179], v[192:195], 0
	v_mfma_f32_16x16x32_bf16 v[20:23], v[168:171], v[200:203], 0
	v_mfma_f32_16x16x32_bf16 v[16:19], v[176:179], v[200:203], 0
	v_mfma_f32_16x16x32_bf16 v[4:7], v[168:171], v[208:211], 0
	v_mfma_f32_16x16x32_bf16 v[0:3], v[176:179], v[208:211], 0
	v_mfma_f32_16x16x32_bf16 v[52:55], v[172:175], v[188:191], v[52:55]
	v_mfma_f32_16x16x32_bf16 v[48:51], v[180:183], v[188:191], v[48:51]
	v_mfma_f32_16x16x32_bf16 v[36:39], v[172:175], v[196:199], v[36:39]
	v_mfma_f32_16x16x32_bf16 v[32:35], v[180:183], v[196:199], v[32:35]
	v_mfma_f32_16x16x32_bf16 v[20:23], v[172:175], v[204:207], v[20:23]
	v_mfma_f32_16x16x32_bf16 v[16:19], v[180:183], v[204:207], v[16:19]
	v_mfma_f32_16x16x32_bf16 v[4:7], v[172:175], v[212:215], v[4:7]
	v_mfma_f32_16x16x32_bf16 v[0:3], v[180:183], v[212:215], v[0:3]
	s_barrier
	s_add_i32 s62, 0, 0x18000
	s_add_i32 s63, 0, 0x1c000
	v_add_u32_e32 v164, s62, v147
	v_add_u32_e32 v180, s63, v147
	ds_read_b128 v[152:155], v164
	ds_read_b128 v[156:159], v164 offset:1024
	ds_read_b128 v[160:163], v164 offset:2048
	ds_read_b128 v[164:167], v164 offset:3072
	ds_read_b128 v[168:171], v180
	ds_read_b128 v[172:175], v180 offset:1024
	ds_read_b128 v[176:179], v180 offset:2048
	ds_read_b128 v[180:183], v180 offset:3072
	s_add_u32 s84, s36, 0x80
	s_addc_u32 s85, s37, 0
	s_add_u32 s36, s36, 0x80000
	s_addc_u32 s37, s37, 0
	s_mov_b32 m0, s46
	ds_read_b128 v[184:187], v151 offset:32768
	ds_read_b128 v[188:191], v151 offset:33792
	ds_read_b128 v[192:195], v151 offset:34816
	ds_read_b128 v[196:199], v151 offset:35840
	ds_read_b128 v[200:203], v151 offset:36864
	ds_read_b128 v[204:207], v151 offset:37888
	ds_read_b128 v[208:211], v151 offset:38912
	ds_read_b128 v[212:215], v151 offset:39936
	global_load_lds_dwordx4 v134, s[36:37]
	s_mov_b32 m0, s47
	s_nop 0
	global_load_lds_dwordx4 v130, s[36:37]
	s_waitcnt vmcnt(8)
	s_waitcnt lgkmcnt(0)
	s_barrier
	s_waitcnt lgkmcnt(0)
	v_mfma_f32_16x16x32_bf16 v[124:127], v[152:155], v[184:187], v[124:127]
	v_mfma_f32_16x16x32_bf16 v[120:123], v[160:163], v[184:187], v[120:123]
	v_mfma_f32_16x16x32_bf16 v[108:111], v[152:155], v[192:195], v[108:111]
	v_mfma_f32_16x16x32_bf16 v[104:107], v[160:163], v[192:195], v[104:107]
	v_mfma_f32_16x16x32_bf16 v[92:95], v[152:155], v[200:203], v[92:95]
	v_mfma_f32_16x16x32_bf16 v[88:91], v[160:163], v[200:203], v[88:91]
	v_mfma_f32_16x16x32_bf16 v[76:79], v[152:155], v[208:211], v[76:79]
	v_mfma_f32_16x16x32_bf16 v[72:75], v[160:163], v[208:211], v[72:75]
	v_mfma_f32_16x16x32_bf16 v[124:127], v[156:159], v[188:191], v[124:127]
	v_mfma_f32_16x16x32_bf16 v[120:123], v[164:167], v[188:191], v[120:123]
	v_mfma_f32_16x16x32_bf16 v[108:111], v[156:159], v[196:199], v[108:111]
	v_mfma_f32_16x16x32_bf16 v[104:107], v[164:167], v[196:199], v[104:107]
	v_mfma_f32_16x16x32_bf16 v[92:95], v[156:159], v[204:207], v[92:95]
	v_mfma_f32_16x16x32_bf16 v[88:91], v[164:167], v[204:207], v[88:91]
	v_mfma_f32_16x16x32_bf16 v[76:79], v[156:159], v[212:215], v[76:79]
	v_mfma_f32_16x16x32_bf16 v[72:75], v[164:167], v[212:215], v[72:75]
	v_mfma_f32_16x16x32_bf16 v[116:119], v[168:171], v[184:187], v[116:119]
	v_mfma_f32_16x16x32_bf16 v[112:115], v[176:179], v[184:187], v[112:115]
	v_mfma_f32_16x16x32_bf16 v[100:103], v[168:171], v[192:195], v[100:103]
	v_mfma_f32_16x16x32_bf16 v[96:99], v[176:179], v[192:195], v[96:99]
	v_mfma_f32_16x16x32_bf16 v[84:87], v[168:171], v[200:203], v[84:87]
	v_mfma_f32_16x16x32_bf16 v[80:83], v[176:179], v[200:203], v[80:83]
	v_mfma_f32_16x16x32_bf16 v[68:71], v[168:171], v[208:211], v[68:71]
	v_mfma_f32_16x16x32_bf16 v[64:67], v[176:179], v[208:211], v[64:67]
	v_mfma_f32_16x16x32_bf16 v[116:119], v[172:175], v[188:191], v[116:119]
	v_mfma_f32_16x16x32_bf16 v[112:115], v[180:183], v[188:191], v[112:115]
	v_mfma_f32_16x16x32_bf16 v[100:103], v[172:175], v[196:199], v[100:103]
	v_mfma_f32_16x16x32_bf16 v[96:99], v[180:183], v[196:199], v[96:99]
	v_mfma_f32_16x16x32_bf16 v[84:87], v[172:175], v[204:207], v[84:87]
	v_mfma_f32_16x16x32_bf16 v[80:83], v[180:183], v[204:207], v[80:83]
	v_mfma_f32_16x16x32_bf16 v[68:71], v[172:175], v[212:215], v[68:71]
	v_mfma_f32_16x16x32_bf16 v[64:67], v[180:183], v[212:215], v[64:67]
	s_barrier
; #define PG8_STAGE(bufoff, gbase, voff) do { _Pragma("unroll") for (int _i = 0; _i < 2; ++_i) \
;         __builtin_amdgcn_global_load_lds((const unsigned*)((const char*)(gbase) + (voff)[_i]), (PG8_LAS unsigned*)(lds + (bufoff) + ldsw + _i * 8192), 16, 0, 0); } while (0)
; #define PG8_LDA(dst, b, h) do { _Pragma("unroll") for (int m = 0; m < 4; ++m) _Pragma("unroll") for (int k = 0; k < 2; ++k) dst[m][k] = *(const PG8_LAS bf16x8*)(lds + PG8_SA(b, h) + aoff + m * 2048 + k * 1024); } while (0)
; #define PG8_MMA(ai, bj, At, Bt) do { __builtin_amdgcn_s_setprio(1); _Pragma("unroll") for (int m = 0; m < 4; ++m) _Pragma("unroll") for (int n = 0; n < 2; ++n) _Pragma("unroll") for (int k = 0; k < 2; ++k) \
;         acc[ai][bj][m][n] = __builtin_amdgcn_mfma_f32_16x16x32_bf16(Bt[n][k], At[m][k], acc[ai][bj][m][n], 0, 0, 0); __builtin_amdgcn_s_setprio(0); } while (0)
; #define PG8_WAIT_V(n) asm volatile("s_waitcnt vmcnt(" #n ")" ::: "memory")
; #define PG8_WAIT_L(n) asm volatile("s_waitcnt lgkmcnt(" #n ")" ::: "memory")
; #define PG8_BAR __builtin_amdgcn_s_barrier()
; #define PG8_SCHED __builtin_amdgcn_sched_barrier(0)
; template <class Epi, class Sched, bool ALIGN_EPI = false, bool SP2 = false>
; __device__ __forceinline__ void gemm_phase(PG8_LAS unsigned char* lds, const Gemm g, const Sched& S, const Epi& E) {
;     ...
;             PG8_LDA(At, 1, 1); PG8_STAGE(PG8_SB(1, 0), b3, voffB); PG8_STAGE(PG8_SB(1, 1), b3 + hstep, voffB); PG8_STAGE(PG8_SA(1, 0), a3, voffA);
;             PG8_WAIT_V(8); PG8_WAIT_L(0); PG8_BAR; PG8_MMA(1, 0, At, B0); PG8_MMA(1, 1, At, B1); PG8_BAR; PG8_SCHED;
	s_add_i32 s36, s62, s42
	s_add_u32 s86, s34, 0x80
	s_addc_u32 s87, s35, 0
	s_mov_b32 m0, s36
	ds_read_b128 v[184:187], v151 offset:49152
	ds_read_b128 v[188:191], v151 offset:50176
	ds_read_b128 v[192:195], v151 offset:51200
	ds_read_b128 v[196:199], v151 offset:52224
	ds_read_b128 v[200:203], v151 offset:53248
	ds_read_b128 v[204:207], v151 offset:54272
	ds_read_b128 v[208:211], v151 offset:55296
	ds_read_b128 v[212:215], v151 offset:56320
	global_load_lds_dwordx4 v132, s[86:87]
	s_add_i32 m0, s36, 0x2000
	s_add_u32 s34, s34, 0x80080
	s_addc_u32 s35, s35, 0
	s_add_i32 s36, s63, s42
	global_load_lds_dwordx4 v128, s[86:87]
	s_mov_b32 m0, s36
	s_nop 0
	global_load_lds_dwordx4 v132, s[34:35]
	s_add_i32 m0, s36, 0x2000
	s_nop 0
	global_load_lds_dwordx4 v128, s[34:35]
	s_mov_b32 m0, s49
	s_nop 0
	global_load_lds_dwordx4 v134, s[84:85]
	s_mov_b32 m0, s50
	s_nop 0
	global_load_lds_dwordx4 v130, s[84:85]
	s_waitcnt vmcnt(8)
	s_waitcnt lgkmcnt(0)
	s_barrier
	s_waitcnt lgkmcnt(0)
	v_mfma_f32_16x16x32_bf16 v[60:63], v[152:155], v[184:187], v[60:63]
	v_mfma_f32_16x16x32_bf16 v[56:59], v[160:163], v[184:187], v[56:59]
	v_mfma_f32_16x16x32_bf16 v[44:47], v[152:155], v[192:195], v[44:47]
	v_mfma_f32_16x16x32_bf16 v[40:43], v[160:163], v[192:195], v[40:43]
	v_mfma_f32_16x16x32_bf16 v[28:31], v[152:155], v[200:203], v[28:31]
	v_mfma_f32_16x16x32_bf16 v[24:27], v[160:163], v[200:203], v[24:27]
	v_mfma_f32_16x16x32_bf16 v[12:15], v[152:155], v[208:211], v[12:15]
	v_mfma_f32_16x16x32_bf16 v[8:11], v[160:163], v[208:211], v[8:11]
	v_mfma_f32_16x16x32_bf16 v[60:63], v[156:159], v[188:191], v[60:63]
	v_mfma_f32_16x16x32_bf16 v[56:59], v[164:167], v[188:191], v[56:59]
	v_mfma_f32_16x16x32_bf16 v[44:47], v[156:159], v[196:199], v[44:47]
	v_mfma_f32_16x16x32_bf16 v[40:43], v[164:167], v[196:199], v[40:43]
	v_mfma_f32_16x16x32_bf16 v[28:31], v[156:159], v[204:207], v[28:31]
	v_mfma_f32_16x16x32_bf16 v[24:27], v[164:167], v[204:207], v[24:27]
	v_mfma_f32_16x16x32_bf16 v[12:15], v[156:159], v[212:215], v[12:15]
	v_mfma_f32_16x16x32_bf16 v[8:11], v[164:167], v[212:215], v[8:11]
	v_mfma_f32_16x16x32_bf16 v[52:55], v[168:171], v[184:187], v[52:55]
	v_mfma_f32_16x16x32_bf16 v[48:51], v[176:179], v[184:187], v[48:51]
	v_mfma_f32_16x16x32_bf16 v[36:39], v[168:171], v[192:195], v[36:39]
	v_mfma_f32_16x16x32_bf16 v[32:35], v[176:179], v[192:195], v[32:35]
	v_mfma_f32_16x16x32_bf16 v[20:23], v[168:171], v[200:203], v[20:23]
	v_mfma_f32_16x16x32_bf16 v[16:19], v[176:179], v[200:203], v[16:19]
	v_mfma_f32_16x16x32_bf16 v[4:7], v[168:171], v[208:211], v[4:7]
	v_mfma_f32_16x16x32_bf16 v[0:3], v[176:179], v[208:211], v[0:3]
	v_mfma_f32_16x16x32_bf16 v[52:55], v[172:175], v[188:191], v[52:55]
	v_mfma_f32_16x16x32_bf16 v[48:51], v[180:183], v[188:191], v[48:51]
	v_mfma_f32_16x16x32_bf16 v[36:39], v[172:175], v[196:199], v[36:39]
	v_mfma_f32_16x16x32_bf16 v[32:35], v[180:183], v[196:199], v[32:35]
	v_mfma_f32_16x16x32_bf16 v[20:23], v[172:175], v[204:207], v[20:23]
	v_mfma_f32_16x16x32_bf16 v[16:19], v[180:183], v[204:207], v[16:19]
	v_mfma_f32_16x16x32_bf16 v[4:7], v[172:175], v[212:215], v[4:7]
	v_mfma_f32_16x16x32_bf16 v[0:3], v[180:183], v[212:215], v[0:3]
	s_barrier
	s_add_i32 s61, s61, 2
	s_add_u32 s30, s30, 0x100
	s_addc_u32 s31, s31, 0
	s_add_u32 s59, s59, 0x100
	s_addc_u32 s60, s60, 0
	s_cmp_gt_u32 s61, 29

; #define PG8_STAGE(bufoff, gbase, voff) do { _Pragma("unroll") for (int _i = 0; _i < 2; ++_i) \
;         __builtin_amdgcn_global_load_lds((const unsigned*)((const char*)(gbase) + (voff)[_i]), (PG8_LAS unsigned*)(lds + (bufoff) + ldsw + _i * 8192), 16, 0, 0); } while (0)
; #define PG8_LDA(dst, b, h) do { _Pragma("unroll") for (int m = 0; m < 4; ++m) _Pragma("unroll") for (int k = 0; k < 2; ++k) dst[m][k] = *(const PG8_LAS bf16x8*)(lds + PG8_SA(b, h) + aoff + m * 2048 + k * 1024); } while (0)
; #define PG8_LDB(dst, b, h) do { _Pragma("unroll") for (int n = 0; n < 2; ++n) _Pragma("unroll") for (int k = 0; k < 2; ++k) dst[n][k] = *(const PG8_LAS bf16x8*)(lds + PG8_SB(b, h) + boff + n * 2048 + k * 1024); } while (0)
; #define PG8_MMA(ai, bj, At, Bt) do { __builtin_amdgcn_s_setprio(1); _Pragma("unroll") for (int m = 0; m < 4; ++m) _Pragma("unroll") for (int n = 0; n < 2; ++n) _Pragma("unroll") for (int k = 0; k < 2; ++k) \
;         acc[ai][bj][m][n] = __builtin_amdgcn_mfma_f32_16x16x32_bf16(Bt[n][k], At[m][k], acc[ai][bj][m][n], 0, 0, 0); __builtin_amdgcn_s_setprio(0); } while (0)
; #define PG8_WAIT_V(n) asm volatile("s_waitcnt vmcnt(" #n ")" ::: "memory")
; #define PG8_BAR __builtin_amdgcn_s_barrier()
; template <class Epi, class Sched, bool ALIGN_EPI = false, bool SP2 = false>
; __device__ __forceinline__ void gemm_phase(PG8_LAS unsigned char* lds, const Gemm g, const Sched& S, const Epi& E) {
;     ...
;         for (int t = 0; t < nt; t += 2) {
;             const bool last = (t == nt - 2);
;             const char* a1 = cA + (size_t)(t + 1) * kstep;
;             const char* a2 = last ? nA : cA + (size_t)(t + 2) * kstep; const char* b2 = last ? nB : cB + (size_t)(t + 2) * kstep;
;             const char* a3 = a2 + kstep; const char* b3 = b2 + kstep;
;             if (last && has_next) S.a_ready(nxt);
;             if constexpr (SP2) {
;             PG8_LDB(B0, 0, 0); PG8_LDB(B1, 0, 1); PG8_SCHED; PG8_LDA(At, 0, 0); PG8_STAGE(PG8_SA(1, 1), a1 + hstep, voffA);
;             PG8_WAIT_V(8); PG8_WAIT_L(0); PG8_BAR; PG8_MMA(0, 0, At, B0); PG8_MMA(0, 1, At, B1); PG8_BAR; PG8_SCHED;
;             PG8_LDA(At, 0, 1); PG8_STAGE(PG8_SB(0, 0), b2, voffB); PG8_STAGE(PG8_SB(0, 1), b2 + hstep, voffB); PG8_STAGE(PG8_SA(0, 0), a2, voffA);
;             PG8_WAIT_V(8); PG8_WAIT_L(0); PG8_BAR; PG8_MMA(1, 0, At, B0); PG8_MMA(1, 1, At, B1); PG8_BAR; PG8_SCHED;
.LBB0_1020:
	s_add_u32 s54, s26, 0x100
	s_addc_u32 s55, s27, 0
	s_mov_b32 s56, -2
	ds_read_b128 v[144:147], v169
	ds_read_b128 v[148:151], v169 offset:1024
	ds_read_b128 v[152:155], v169 offset:2048
	ds_read_b128 v[156:159], v169 offset:3072
	ds_read_b128 v[160:163], v170
	ds_read_b128 v[172:175], v170 offset:1024
	ds_read_b128 v[176:179], v170 offset:2048
	ds_read_b128 v[180:183], v170 offset:3072
	s_add_u32 s26, s24, 0x100
	s_addc_u32 s27, s25, 0
	s_cmpk_eq_i32 s56, 0x54
	s_cselect_b32 s31, s5, s27
	s_cselect_b32 s30, s4, s26
	s_cselect_b32 s29, s7, s55
	s_cselect_b32 s28, s6, s54
	s_add_i32 m0, s38, 0xc000
	ds_read_b128 v[184:187], v171
	ds_read_b128 v[188:191], v171 offset:1024
	ds_read_b128 v[192:195], v171 offset:2048
	ds_read_b128 v[196:199], v171 offset:3072
	ds_read_b128 v[200:203], v171 offset:4096
	ds_read_b128 v[204:207], v171 offset:5120
	ds_read_b128 v[208:211], v171 offset:6144
	ds_read_b128 v[212:215], v171 offset:7168
	global_load_lds_dwordx4 v136, s[24:25]
	s_add_i32 m0, s38, 0xe000
	s_nop 0
	global_load_lds_dwordx4 v138, s[24:25]
	s_waitcnt vmcnt(8)
	s_waitcnt lgkmcnt(0)
	s_barrier
	s_waitcnt lgkmcnt(0)
	v_mfma_f32_16x16x32_bf16 v[124:127], v[144:147], v[184:187], 0
	v_mfma_f32_16x16x32_bf16 v[120:123], v[152:155], v[184:187], 0
	v_mfma_f32_16x16x32_bf16 v[116:119], v[144:147], v[192:195], 0
	v_mfma_f32_16x16x32_bf16 v[112:115], v[152:155], v[192:195], 0
	v_mfma_f32_16x16x32_bf16 v[108:111], v[144:147], v[200:203], 0
	v_mfma_f32_16x16x32_bf16 v[96:99], v[152:155], v[200:203], 0
	v_mfma_f32_16x16x32_bf16 v[84:87], v[144:147], v[208:211], 0
	v_mfma_f32_16x16x32_bf16 v[76:79], v[152:155], v[208:211], 0
	v_mfma_f32_16x16x32_bf16 v[124:127], v[148:151], v[188:191], v[124:127]
	v_mfma_f32_16x16x32_bf16 v[120:123], v[156:159], v[188:191], v[120:123]
	v_mfma_f32_16x16x32_bf16 v[116:119], v[148:151], v[196:199], v[116:119]
	v_mfma_f32_16x16x32_bf16 v[112:115], v[156:159], v[196:199], v[112:115]
	v_mfma_f32_16x16x32_bf16 v[108:111], v[148:151], v[204:207], v[108:111]
	v_mfma_f32_16x16x32_bf16 v[96:99], v[156:159], v[204:207], v[96:99]
	v_mfma_f32_16x16x32_bf16 v[84:87], v[148:151], v[212:215], v[84:87]
	v_mfma_f32_16x16x32_bf16 v[76:79], v[156:159], v[212:215], v[76:79]
	v_mfma_f32_16x16x32_bf16 v[104:107], v[160:163], v[184:187], 0
	v_mfma_f32_16x16x32_bf16 v[100:103], v[176:179], v[184:187], 0
	v_mfma_f32_16x16x32_bf16 v[92:95], v[160:163], v[192:195], 0
	v_mfma_f32_16x16x32_bf16 v[88:91], v[176:179], v[192:195], 0
	v_mfma_f32_16x16x32_bf16 v[80:83], v[160:163], v[200:203], 0
	v_mfma_f32_16x16x32_bf16 v[72:75], v[176:179], v[200:203], 0
	v_mfma_f32_16x16x32_bf16 v[68:71], v[160:163], v[208:211], 0
	v_mfma_f32_16x16x32_bf16 v[64:67], v[176:179], v[208:211], 0
	v_mfma_f32_16x16x32_bf16 v[104:107], v[172:175], v[188:191], v[104:107]
	v_mfma_f32_16x16x32_bf16 v[100:103], v[180:183], v[188:191], v[100:103]
	v_mfma_f32_16x16x32_bf16 v[92:95], v[172:175], v[196:199], v[92:95]
	v_mfma_f32_16x16x32_bf16 v[88:91], v[180:183], v[196:199], v[88:91]
	v_mfma_f32_16x16x32_bf16 v[80:83], v[172:175], v[204:207], v[80:83]
	v_mfma_f32_16x16x32_bf16 v[72:75], v[180:183], v[204:207], v[72:75]
	v_mfma_f32_16x16x32_bf16 v[68:71], v[172:175], v[212:215], v[68:71]
	v_mfma_f32_16x16x32_bf16 v[64:67], v[180:183], v[212:215], v[64:67]
	s_barrier
	s_add_i32 s24, s48, s37
	s_mov_b32 m0, s24
	ds_read_b128 v[184:187], v171 offset:16384
	ds_read_b128 v[188:191], v171 offset:17408
	ds_read_b128 v[192:195], v171 offset:18432
	ds_read_b128 v[196:199], v171 offset:19456
	ds_read_b128 v[200:203], v171 offset:20480
	ds_read_b128 v[204:207], v171 offset:21504
	ds_read_b128 v[208:211], v171 offset:22528
	ds_read_b128 v[212:215], v171 offset:23552
	global_load_lds_dwordx4 v130, s[28:29]
	s_add_i32 m0, s24, 0x2000
	s_add_u32 s24, s28, 0x160000
	s_addc_u32 s25, s29, 0
	s_add_i32 s57, s49, s37
	global_load_lds_dwordx4 v134, s[28:29]
	s_mov_b32 m0, s57
	s_nop 0
	global_load_lds_dwordx4 v130, s[24:25]
	s_add_i32 m0, s57, 0x2000
	s_nop 0
	global_load_lds_dwordx4 v134, s[24:25]
	s_mov_b32 m0, s38
	s_nop 0
	global_load_lds_dwordx4 v128, s[30:31]
	s_mov_b32 m0, s39
	s_nop 0
	global_load_lds_dwordx4 v132, s[30:31]
	s_waitcnt vmcnt(8)
	s_waitcnt lgkmcnt(0)
	s_barrier
	s_waitcnt lgkmcnt(0)
	v_mfma_f32_16x16x32_bf16 v[60:63], v[144:147], v[184:187], 0
	v_mfma_f32_16x16x32_bf16 v[56:59], v[152:155], v[184:187], 0
	v_mfma_f32_16x16x32_bf16 v[52:55], v[144:147], v[192:195], 0
	v_mfma_f32_16x16x32_bf16 v[48:51], v[152:155], v[192:195], 0
	v_mfma_f32_16x16x32_bf16 v[44:47], v[144:147], v[200:203], 0
	v_mfma_f32_16x16x32_bf16 v[32:35], v[152:155], v[200:203], 0
	v_mfma_f32_16x16x32_bf16 v[20:23], v[144:147], v[208:211], 0
	v_mfma_f32_16x16x32_bf16 v[12:15], v[152:155], v[208:211], 0
	v_mfma_f32_16x16x32_bf16 v[60:63], v[148:151], v[188:191], v[60:63]
	v_mfma_f32_16x16x32_bf16 v[56:59], v[156:159], v[188:191], v[56:59]
	v_mfma_f32_16x16x32_bf16 v[52:55], v[148:151], v[196:199], v[52:55]
	v_mfma_f32_16x16x32_bf16 v[48:51], v[156:159], v[196:199], v[48:51]
	v_mfma_f32_16x16x32_bf16 v[44:47], v[148:151], v[204:207], v[44:47]
	v_mfma_f32_16x16x32_bf16 v[32:35], v[156:159], v[204:207], v[32:35]
	v_mfma_f32_16x16x32_bf16 v[20:23], v[148:151], v[212:215], v[20:23]
	v_mfma_f32_16x16x32_bf16 v[12:15], v[156:159], v[212:215], v[12:15]
	v_mfma_f32_16x16x32_bf16 v[40:43], v[160:163], v[184:187], 0
	v_mfma_f32_16x16x32_bf16 v[36:39], v[176:179], v[184:187], 0
	v_mfma_f32_16x16x32_bf16 v[28:31], v[160:163], v[192:195], 0
	v_mfma_f32_16x16x32_bf16 v[24:27], v[176:179], v[192:195], 0
	v_mfma_f32_16x16x32_bf16 v[16:19], v[160:163], v[200:203], 0
	v_mfma_f32_16x16x32_bf16 v[8:11], v[176:179], v[200:203], 0
	v_mfma_f32_16x16x32_bf16 v[4:7], v[160:163], v[208:211], 0
	v_mfma_f32_16x16x32_bf16 v[0:3], v[176:179], v[208:211], 0
	v_mfma_f32_16x16x32_bf16 v[40:43], v[172:175], v[188:191], v[40:43]
	v_mfma_f32_16x16x32_bf16 v[36:39], v[180:183], v[188:191], v[36:39]
	v_mfma_f32_16x16x32_bf16 v[28:31], v[172:175], v[196:199], v[28:31]
	v_mfma_f32_16x16x32_bf16 v[24:27], v[180:183], v[196:199], v[24:27]
	v_mfma_f32_16x16x32_bf16 v[16:19], v[172:175], v[204:207], v[16:19]
	v_mfma_f32_16x16x32_bf16 v[8:11], v[180:183], v[204:207], v[8:11]
	v_mfma_f32_16x16x32_bf16 v[4:7], v[172:175], v[212:215], v[4:7]
	v_mfma_f32_16x16x32_bf16 v[0:3], v[180:183], v[212:215], v[0:3]
	s_barrier
; #define PG8_STAGE(bufoff, gbase, voff) do { _Pragma("unroll") for (int _i = 0; _i < 2; ++_i) \
;         __builtin_amdgcn_global_load_lds((const unsigned*)((const char*)(gbase) + (voff)[_i]), (PG8_LAS unsigned*)(lds + (bufoff) + ldsw + _i * 8192), 16, 0, 0); } while (0)
; #define PG8_LDA(dst, b, h) do { _Pragma("unroll") for (int m = 0; m < 4; ++m) _Pragma("unroll") for (int k = 0; k < 2; ++k) dst[m][k] = *(const PG8_LAS bf16x8*)(lds + PG8_SA(b, h) + aoff + m * 2048 + k * 1024); } while (0)
; #define PG8_LDB(dst, b, h) do { _Pragma("unroll") for (int n = 0; n < 2; ++n) _Pragma("unroll") for (int k = 0; k < 2; ++k) dst[n][k] = *(const PG8_LAS bf16x8*)(lds + PG8_SB(b, h) + boff + n * 2048 + k * 1024); } while (0)
; #define PG8_MMA(ai, bj, At, Bt) do { __builtin_amdgcn_s_setprio(1); _Pragma("unroll") for (int m = 0; m < 4; ++m) _Pragma("unroll") for (int n = 0; n < 2; ++n) _Pragma("unroll") for (int k = 0; k < 2; ++k) \
;         acc[ai][bj][m][n] = __builtin_amdgcn_mfma_f32_16x16x32_bf16(Bt[n][k], At[m][k], acc[ai][bj][m][n], 0, 0, 0); __builtin_amdgcn_s_setprio(0); } while (0)
; #define PG8_WAIT_V(n) asm volatile("s_waitcnt vmcnt(" #n ")" ::: "memory")
; #define PG8_WAIT_L(n) asm volatile("s_waitcnt lgkmcnt(" #n ")" ::: "memory")
; #define PG8_BAR __builtin_amdgcn_s_barrier()
; #define PG8_SCHED __builtin_amdgcn_sched_barrier(0)
; template <class Epi, class Sched, bool ALIGN_EPI = false, bool SP2 = false>
; __device__ __forceinline__ void gemm_phase(PG8_LAS unsigned char* lds, const Gemm g, const Sched& S, const Epi& E) {
;     ...
;             PG8_LDB(B0, 1, 0); PG8_LDB(B1, 1, 1); PG8_SCHED; PG8_LDA(At, 1, 0); PG8_STAGE(PG8_SA(0, 1), a2 + hstep, voffA);
;             PG8_WAIT_V(8); PG8_WAIT_L(0); PG8_BAR; PG8_MMA(0, 0, At, B0); PG8_MMA(0, 1, At, B1); PG8_BAR; PG8_SCHED;
;             PG8_LDA(At, 1, 1); PG8_STAGE(PG8_SB(1, 0), b3, voffB); PG8_STAGE(PG8_SB(1, 1), b3 + hstep, voffB); PG8_STAGE(PG8_SA(1, 0), a3, voffA);
;             PG8_WAIT_V(8); PG8_WAIT_L(0); PG8_BAR; PG8_MMA(1, 0, At, B0); PG8_MMA(1, 1, At, B1); PG8_BAR; PG8_SCHED;
	s_add_i32 s57, 0, 0x18000
	s_add_i32 s58, 0, 0x1c000
	v_add_u32_e32 v156, s57, v167
	v_add_u32_e32 v180, s58, v167
	ds_read_b128 v[144:147], v156
	ds_read_b128 v[148:151], v156 offset:1024
	ds_read_b128 v[152:155], v156 offset:2048
	ds_read_b128 v[156:159], v156 offset:3072
	ds_read_b128 v[160:163], v180
	ds_read_b128 v[172:175], v180 offset:1024
	ds_read_b128 v[176:179], v180 offset:2048
	ds_read_b128 v[180:183], v180 offset:3072
	s_add_u32 s24, s30, 0x160000
	s_addc_u32 s25, s31, 0
	s_mov_b32 m0, s40
	ds_read_b128 v[184:187], v171 offset:32768
	ds_read_b128 v[188:191], v171 offset:33792
	ds_read_b128 v[192:195], v171 offset:34816
	ds_read_b128 v[196:199], v171 offset:35840
	ds_read_b128 v[200:203], v171 offset:36864
	ds_read_b128 v[204:207], v171 offset:37888
	ds_read_b128 v[208:211], v171 offset:38912
	ds_read_b128 v[212:215], v171 offset:39936
	global_load_lds_dwordx4 v128, s[24:25]
	s_mov_b32 m0, s41
	s_nop 0
	global_load_lds_dwordx4 v132, s[24:25]
	s_waitcnt vmcnt(8)
	s_waitcnt lgkmcnt(0)
	s_barrier
	s_waitcnt lgkmcnt(0)
	v_mfma_f32_16x16x32_bf16 v[124:127], v[144:147], v[184:187], v[124:127]
	v_mfma_f32_16x16x32_bf16 v[120:123], v[152:155], v[184:187], v[120:123]
	v_mfma_f32_16x16x32_bf16 v[116:119], v[144:147], v[192:195], v[116:119]
	v_mfma_f32_16x16x32_bf16 v[112:115], v[152:155], v[192:195], v[112:115]
	v_mfma_f32_16x16x32_bf16 v[108:111], v[144:147], v[200:203], v[108:111]
	v_mfma_f32_16x16x32_bf16 v[96:99], v[152:155], v[200:203], v[96:99]
	v_mfma_f32_16x16x32_bf16 v[84:87], v[144:147], v[208:211], v[84:87]
	v_mfma_f32_16x16x32_bf16 v[76:79], v[152:155], v[208:211], v[76:79]
	v_mfma_f32_16x16x32_bf16 v[124:127], v[148:151], v[188:191], v[124:127]
	v_mfma_f32_16x16x32_bf16 v[120:123], v[156:159], v[188:191], v[120:123]
	v_mfma_f32_16x16x32_bf16 v[116:119], v[148:151], v[196:199], v[116:119]
	v_mfma_f32_16x16x32_bf16 v[112:115], v[156:159], v[196:199], v[112:115]
	v_mfma_f32_16x16x32_bf16 v[108:111], v[148:151], v[204:207], v[108:111]
	v_mfma_f32_16x16x32_bf16 v[96:99], v[156:159], v[204:207], v[96:99]
	v_mfma_f32_16x16x32_bf16 v[84:87], v[148:151], v[212:215], v[84:87]
	v_mfma_f32_16x16x32_bf16 v[76:79], v[156:159], v[212:215], v[76:79]
	v_mfma_f32_16x16x32_bf16 v[104:107], v[160:163], v[184:187], v[104:107]
	v_mfma_f32_16x16x32_bf16 v[100:103], v[176:179], v[184:187], v[100:103]
	v_mfma_f32_16x16x32_bf16 v[92:95], v[160:163], v[192:195], v[92:95]
	v_mfma_f32_16x16x32_bf16 v[88:91], v[176:179], v[192:195], v[88:91]
	v_mfma_f32_16x16x32_bf16 v[80:83], v[160:163], v[200:203], v[80:83]
	v_mfma_f32_16x16x32_bf16 v[72:75], v[176:179], v[200:203], v[72:75]
	v_mfma_f32_16x16x32_bf16 v[68:71], v[160:163], v[208:211], v[68:71]
	v_mfma_f32_16x16x32_bf16 v[64:67], v[176:179], v[208:211], v[64:67]
	v_mfma_f32_16x16x32_bf16 v[104:107], v[172:175], v[188:191], v[104:107]
	v_mfma_f32_16x16x32_bf16 v[100:103], v[180:183], v[188:191], v[100:103]
	v_mfma_f32_16x16x32_bf16 v[92:95], v[172:175], v[196:199], v[92:95]
	v_mfma_f32_16x16x32_bf16 v[88:91], v[180:183], v[196:199], v[88:91]
	v_mfma_f32_16x16x32_bf16 v[80:83], v[172:175], v[204:207], v[80:83]
	v_mfma_f32_16x16x32_bf16 v[72:75], v[180:183], v[204:207], v[72:75]
	v_mfma_f32_16x16x32_bf16 v[68:71], v[172:175], v[212:215], v[68:71]
	v_mfma_f32_16x16x32_bf16 v[64:67], v[180:183], v[212:215], v[64:67]
	s_barrier
	s_add_i32 s24, s57, s37
	s_add_u32 s86, s28, 0x80
	s_addc_u32 s87, s29, 0
	s_mov_b32 m0, s24
	ds_read_b128 v[184:187], v171 offset:49152
	ds_read_b128 v[188:191], v171 offset:50176
	ds_read_b128 v[192:195], v171 offset:51200
	ds_read_b128 v[196:199], v171 offset:52224
	ds_read_b128 v[200:203], v171 offset:53248
	ds_read_b128 v[204:207], v171 offset:54272
	ds_read_b128 v[208:211], v171 offset:55296
	ds_read_b128 v[212:215], v171 offset:56320
	global_load_lds_dwordx4 v130, s[86:87]
	s_add_i32 m0, s24, 0x2000
	s_add_u32 s24, s28, 0x160080
	s_addc_u32 s25, s29, 0
	s_add_i32 s28, s58, s37
	global_load_lds_dwordx4 v134, s[86:87]
	s_mov_b32 m0, s28
	s_nop 0
	global_load_lds_dwordx4 v130, s[24:25]
	s_add_i32 m0, s28, 0x2000
	s_nop 0
	global_load_lds_dwordx4 v134, s[24:25]
	s_add_u32 s84, s30, 0x80
	s_addc_u32 s85, s31, 0
	s_mov_b32 m0, s45
	s_nop 0
	global_load_lds_dwordx4 v128, s[84:85]
	s_mov_b32 m0, s46
	s_nop 0
	global_load_lds_dwordx4 v132, s[84:85]
	s_waitcnt vmcnt(8)
	s_waitcnt lgkmcnt(0)
	s_barrier
	s_waitcnt lgkmcnt(0)
	v_mfma_f32_16x16x32_bf16 v[60:63], v[144:147], v[184:187], v[60:63]
	v_mfma_f32_16x16x32_bf16 v[56:59], v[152:155], v[184:187], v[56:59]
	v_mfma_f32_16x16x32_bf16 v[52:55], v[144:147], v[192:195], v[52:55]
	v_mfma_f32_16x16x32_bf16 v[48:51], v[152:155], v[192:195], v[48:51]
	v_mfma_f32_16x16x32_bf16 v[44:47], v[144:147], v[200:203], v[44:47]
	v_mfma_f32_16x16x32_bf16 v[32:35], v[152:155], v[200:203], v[32:35]
	v_mfma_f32_16x16x32_bf16 v[20:23], v[144:147], v[208:211], v[20:23]
	v_mfma_f32_16x16x32_bf16 v[12:15], v[152:155], v[208:211], v[12:15]
	v_mfma_f32_16x16x32_bf16 v[60:63], v[148:151], v[188:191], v[60:63]
	v_mfma_f32_16x16x32_bf16 v[56:59], v[156:159], v[188:191], v[56:59]
	v_mfma_f32_16x16x32_bf16 v[52:55], v[148:151], v[196:199], v[52:55]
	v_mfma_f32_16x16x32_bf16 v[48:51], v[156:159], v[196:199], v[48:51]
	v_mfma_f32_16x16x32_bf16 v[44:47], v[148:151], v[204:207], v[44:47]
	v_mfma_f32_16x16x32_bf16 v[32:35], v[156:159], v[204:207], v[32:35]
	v_mfma_f32_16x16x32_bf16 v[20:23], v[148:151], v[212:215], v[20:23]
	v_mfma_f32_16x16x32_bf16 v[12:15], v[156:159], v[212:215], v[12:15]
	v_mfma_f32_16x16x32_bf16 v[40:43], v[160:163], v[184:187], v[40:43]
	v_mfma_f32_16x16x32_bf16 v[36:39], v[176:179], v[184:187], v[36:39]
	v_mfma_f32_16x16x32_bf16 v[28:31], v[160:163], v[192:195], v[28:31]
	v_mfma_f32_16x16x32_bf16 v[24:27], v[176:179], v[192:195], v[24:27]
	v_mfma_f32_16x16x32_bf16 v[16:19], v[160:163], v[200:203], v[16:19]
	v_mfma_f32_16x16x32_bf16 v[8:11], v[176:179], v[200:203], v[8:11]
	v_mfma_f32_16x16x32_bf16 v[4:7], v[160:163], v[208:211], v[4:7]
	v_mfma_f32_16x16x32_bf16 v[0:3], v[176:179], v[208:211], v[0:3]
	v_mfma_f32_16x16x32_bf16 v[40:43], v[172:175], v[188:191], v[40:43]
	v_mfma_f32_16x16x32_bf16 v[36:39], v[180:183], v[188:191], v[36:39]
	v_mfma_f32_16x16x32_bf16 v[28:31], v[172:175], v[196:199], v[28:31]
	v_mfma_f32_16x16x32_bf16 v[24:27], v[180:183], v[196:199], v[24:27]
	v_mfma_f32_16x16x32_bf16 v[16:19], v[172:175], v[204:207], v[16:19]
	v_mfma_f32_16x16x32_bf16 v[8:11], v[180:183], v[204:207], v[8:11]
	v_mfma_f32_16x16x32_bf16 v[4:7], v[172:175], v[212:215], v[4:7]
	v_mfma_f32_16x16x32_bf16 v[0:3], v[180:183], v[212:215], v[0:3]
	s_barrier
	s_add_i32 s56, s56, 2
	s_add_u32 s54, s54, 0x100
	s_addc_u32 s55, s55, 0
	s_cmpk_gt_u32 s56, 0x55
	s_mov_b64 s[24:25], s[26:27]
